# K-loops: dropped the per-MFMA-block s_setprio 1/0 toggles (20 GEMM loops)
# baseline (speedup 1.0000x reference)
; #define PG8_STAGE(bufoff, gbase, voff) do { _Pragma("unroll") for (int _i = 0; _i < 2; ++_i) \
;         __builtin_amdgcn_global_load_lds((const unsigned*)((const char*)(gbase) + (voff)[_i]), (PG8_LAS unsigned*)(lds + (bufoff) + ldsw + _i * 8192), 16, 0, 0); } while (0)
; #define PG8_LDA(dst, b, h) do { _Pragma("unroll") for (int m = 0; m < 4; ++m) _Pragma("unroll") for (int k = 0; k < 2; ++k) dst[m][k] = *(const PG8_LAS bf16x8*)(lds + PG8_SA(b, h) + aoff + m * 2048 + k * 1024); } while (0)
; #define PG8_LDB(dst, b, h) do { _Pragma("unroll") for (int n = 0; n < 2; ++n) _Pragma("unroll") for (int k = 0; k < 2; ++k) dst[n][k] = *(const PG8_LAS bf16x8*)(lds + PG8_SB(b, h) + boff + n * 2048 + k * 1024); } while (0)
; #define PG8_MMA(ai, bj, At, Bt) do { __builtin_amdgcn_s_setprio(1); _Pragma("unroll") for (int m = 0; m < 4; ++m) _Pragma("unroll") for (int n = 0; n < 2; ++n) _Pragma("unroll") for (int k = 0; k < 2; ++k) \
;         acc[ai][bj][m][n] = __builtin_amdgcn_mfma_f32_16x16x32_bf16(Bt[n][k], At[m][k], acc[ai][bj][m][n], 0, 0, 0); __builtin_amdgcn_s_setprio(0); } while (0)
; #define PG8_WAIT_V(n) asm volatile("s_waitcnt vmcnt(" #n ")" ::: "memory")
; #define PG8_WAIT_L(n) asm volatile("s_waitcnt lgkmcnt(" #n ")" ::: "memory")
; #define PG8_BAR __builtin_amdgcn_s_barrier()
; #define PG8_SCHED __builtin_amdgcn_sched_barrier(0)
; template <class Epi, class Sched, bool ALIGN_EPI = false, bool SP2 = false>
; __device__ __forceinline__ void gemm_phase(PG8_LAS unsigned char* lds, const Gemm g, const Sched S, const Epi E, const int tid) {
;     ...
;             PG8_LDB(B0, 0, 0); PG8_LDB(B1, 0, 1); PG8_SCHED; PG8_LDA(At, 0, 0); PG8_STAGE(PG8_SA(1, 1), a1 + hstepA, voffA);
;             PG8_WAIT_V(8); PG8_WAIT_L(0); PG8_BAR; PG8_MMA(0, 0, At, B0); PG8_MMA(0, 1, At, B1); PG8_BAR; PG8_SCHED;
;             PG8_LDA(At, 0, 1); PG8_STAGE(PG8_SB(0, 0), b2, voffB); PG8_STAGE(PG8_SB(0, 1), b2 + hstepB, voffB); PG8_STAGE(PG8_SA(0, 0), a2, voffA);
;             PG8_WAIT_V(8); PG8_WAIT_L(0); PG8_BAR; PG8_MMA(1, 0, At, B0); PG8_MMA(1, 1, At, B1); PG8_BAR; PG8_SCHED;
.LBB0_157:
	ds_read_b128 v[146:149], v169
	ds_read_b128 v[150:153], v169 offset:1024
	ds_read_b128 v[172:175], v169 offset:2048
	ds_read_b128 v[176:179], v169 offset:3072
	ds_read_b128 v[180:183], v170
	ds_read_b128 v[188:191], v170 offset:1024
	ds_read_b128 v[192:195], v170 offset:2048
	ds_read_b128 v[196:199], v170 offset:3072
	s_add_u32 s34, s30, 0xfffc0080
	s_addc_u32 s35, s31, -1
	s_cmp_eq_u32 s65, 12
	s_cselect_b32 s37, s23, s35
	s_cselect_b32 s36, s61, s34
	s_cselect_b32 s35, s15, s64
	s_cselect_b32 s34, s62, s63
	s_add_i32 m0, s29, 0xc000
	ds_read_b128 v[200:203], v171
	ds_read_b128 v[204:207], v171 offset:1024
	ds_read_b128 v[208:211], v171 offset:2048
	ds_read_b128 v[212:215], v171 offset:3072
	ds_read_b128 v[216:219], v171 offset:4096
	ds_read_b128 v[220:223], v171 offset:5120
	ds_read_b128 v[224:227], v171 offset:6144
	ds_read_b128 v[228:231], v171 offset:7168
	global_load_lds_dwordx4 v138, s[30:31]
	s_add_i32 m0, s29, 0xe000
	s_nop 0
	global_load_lds_dwordx4 v140, s[30:31]
	s_waitcnt vmcnt(8)
	s_waitcnt lgkmcnt(0)
	s_barrier
	s_waitcnt lgkmcnt(0)
	v_mfma_f32_16x16x32_bf16 v[124:127], v[146:149], v[200:203], v[124:127]
	v_mfma_f32_16x16x32_bf16 v[120:123], v[172:175], v[200:203], v[120:123]
	v_mfma_f32_16x16x32_bf16 v[108:111], v[146:149], v[208:211], v[108:111]
	v_mfma_f32_16x16x32_bf16 v[104:107], v[172:175], v[208:211], v[104:107]
	v_mfma_f32_16x16x32_bf16 v[92:95], v[146:149], v[216:219], v[92:95]
	v_mfma_f32_16x16x32_bf16 v[88:91], v[172:175], v[216:219], v[88:91]
	v_mfma_f32_16x16x32_bf16 v[76:79], v[146:149], v[224:227], v[76:79]
	v_mfma_f32_16x16x32_bf16 v[72:75], v[172:175], v[224:227], v[72:75]
	v_mfma_f32_16x16x32_bf16 v[124:127], v[150:153], v[204:207], v[124:127]
	v_mfma_f32_16x16x32_bf16 v[120:123], v[176:179], v[204:207], v[120:123]
	v_mfma_f32_16x16x32_bf16 v[108:111], v[150:153], v[212:215], v[108:111]
	v_mfma_f32_16x16x32_bf16 v[104:107], v[176:179], v[212:215], v[104:107]
	v_mfma_f32_16x16x32_bf16 v[92:95], v[150:153], v[220:223], v[92:95]
	v_mfma_f32_16x16x32_bf16 v[88:91], v[176:179], v[220:223], v[88:91]
	v_mfma_f32_16x16x32_bf16 v[76:79], v[150:153], v[228:231], v[76:79]
	v_mfma_f32_16x16x32_bf16 v[72:75], v[176:179], v[228:231], v[72:75]
	v_mfma_f32_16x16x32_bf16 v[116:119], v[180:183], v[200:203], v[116:119]
	v_mfma_f32_16x16x32_bf16 v[112:115], v[192:195], v[200:203], v[112:115]
	v_mfma_f32_16x16x32_bf16 v[100:103], v[180:183], v[208:211], v[100:103]
	v_mfma_f32_16x16x32_bf16 v[96:99], v[192:195], v[208:211], v[96:99]
	v_mfma_f32_16x16x32_bf16 v[84:87], v[180:183], v[216:219], v[84:87]
	v_mfma_f32_16x16x32_bf16 v[80:83], v[192:195], v[216:219], v[80:83]
	v_mfma_f32_16x16x32_bf16 v[68:71], v[180:183], v[224:227], v[68:71]
	v_mfma_f32_16x16x32_bf16 v[64:67], v[192:195], v[224:227], v[64:67]
	v_mfma_f32_16x16x32_bf16 v[116:119], v[188:191], v[204:207], v[116:119]
	v_mfma_f32_16x16x32_bf16 v[112:115], v[196:199], v[204:207], v[112:115]
	v_mfma_f32_16x16x32_bf16 v[100:103], v[188:191], v[212:215], v[100:103]
	v_mfma_f32_16x16x32_bf16 v[96:99], v[196:199], v[212:215], v[96:99]
	v_mfma_f32_16x16x32_bf16 v[84:87], v[188:191], v[220:223], v[84:87]
	v_mfma_f32_16x16x32_bf16 v[80:83], v[196:199], v[220:223], v[80:83]
	v_mfma_f32_16x16x32_bf16 v[68:71], v[188:191], v[228:231], v[68:71]
	v_mfma_f32_16x16x32_bf16 v[64:67], v[196:199], v[228:231], v[64:67]
	s_barrier
	s_add_u32 s98, s34, 0x80
	s_addc_u32 s99, s35, 0
	s_add_u32 s100, s36, 0x80
	s_addc_u32 s101, s37, 0
	s_add_i32 s66, s52, s13
	s_mov_b32 m0, s66
	ds_read_b128 v[200:203], v171 offset:16384
	ds_read_b128 v[204:207], v171 offset:17408
	ds_read_b128 v[208:211], v171 offset:18432
	ds_read_b128 v[212:215], v171 offset:19456
	ds_read_b128 v[216:219], v171 offset:20480
	ds_read_b128 v[220:223], v171 offset:21504
	ds_read_b128 v[224:227], v171 offset:22528
	ds_read_b128 v[228:231], v171 offset:23552
	global_load_lds_dwordx4 v130, s[34:35]
	s_add_i32 m0, s66, 0x2000
	s_add_u32 s66, s34, 0x40000
	s_addc_u32 s67, s35, 0
	s_add_i32 s69, s53, s13
	global_load_lds_dwordx4 v134, s[34:35]
	s_mov_b32 m0, s69
	s_nop 0
	global_load_lds_dwordx4 v130, s[66:67]
	s_add_i32 m0, s69, 0x2000
	s_nop 0
	global_load_lds_dwordx4 v134, s[66:67]
	s_mov_b32 m0, s29
	s_nop 0
	global_load_lds_dwordx4 v128, s[36:37]
	s_mov_b32 m0, s47
	s_nop 0
	global_load_lds_dwordx4 v132, s[36:37]
	s_waitcnt vmcnt(8)
	s_waitcnt lgkmcnt(0)
	s_barrier
	s_waitcnt lgkmcnt(0)
	v_mfma_f32_16x16x32_bf16 v[60:63], v[146:149], v[200:203], v[60:63]
	v_mfma_f32_16x16x32_bf16 v[56:59], v[172:175], v[200:203], v[56:59]
	v_mfma_f32_16x16x32_bf16 v[44:47], v[146:149], v[208:211], v[44:47]
	v_mfma_f32_16x16x32_bf16 v[40:43], v[172:175], v[208:211], v[40:43]
	v_mfma_f32_16x16x32_bf16 v[28:31], v[146:149], v[216:219], v[28:31]
	v_mfma_f32_16x16x32_bf16 v[24:27], v[172:175], v[216:219], v[24:27]
	v_mfma_f32_16x16x32_bf16 v[12:15], v[146:149], v[224:227], v[12:15]
	v_mfma_f32_16x16x32_bf16 v[8:11], v[172:175], v[224:227], v[8:11]
	v_mfma_f32_16x16x32_bf16 v[60:63], v[150:153], v[204:207], v[60:63]
	v_mfma_f32_16x16x32_bf16 v[56:59], v[176:179], v[204:207], v[56:59]
	v_mfma_f32_16x16x32_bf16 v[44:47], v[150:153], v[212:215], v[44:47]
	v_mfma_f32_16x16x32_bf16 v[40:43], v[176:179], v[212:215], v[40:43]
	v_mfma_f32_16x16x32_bf16 v[28:31], v[150:153], v[220:223], v[28:31]
	v_mfma_f32_16x16x32_bf16 v[24:27], v[176:179], v[220:223], v[24:27]
	v_mfma_f32_16x16x32_bf16 v[12:15], v[150:153], v[228:231], v[12:15]
	v_mfma_f32_16x16x32_bf16 v[8:11], v[176:179], v[228:231], v[8:11]
	v_mfma_f32_16x16x32_bf16 v[52:55], v[180:183], v[200:203], v[52:55]
	v_mfma_f32_16x16x32_bf16 v[48:51], v[192:195], v[200:203], v[48:51]
	v_mfma_f32_16x16x32_bf16 v[36:39], v[180:183], v[208:211], v[36:39]
	v_mfma_f32_16x16x32_bf16 v[32:35], v[192:195], v[208:211], v[32:35]
	v_mfma_f32_16x16x32_bf16 v[20:23], v[180:183], v[216:219], v[20:23]
	v_mfma_f32_16x16x32_bf16 v[16:19], v[192:195], v[216:219], v[16:19]
	v_mfma_f32_16x16x32_bf16 v[4:7], v[180:183], v[224:227], v[4:7]
	v_mfma_f32_16x16x32_bf16 v[0:3], v[192:195], v[224:227], v[0:3]
	v_mfma_f32_16x16x32_bf16 v[52:55], v[188:191], v[204:207], v[52:55]
	v_mfma_f32_16x16x32_bf16 v[48:51], v[196:199], v[204:207], v[48:51]
	v_mfma_f32_16x16x32_bf16 v[36:39], v[188:191], v[212:215], v[36:39]
	v_mfma_f32_16x16x32_bf16 v[32:35], v[196:199], v[212:215], v[32:35]
	v_mfma_f32_16x16x32_bf16 v[20:23], v[188:191], v[220:223], v[20:23]
	v_mfma_f32_16x16x32_bf16 v[16:19], v[196:199], v[220:223], v[16:19]
	v_mfma_f32_16x16x32_bf16 v[4:7], v[188:191], v[228:231], v[4:7]
	v_mfma_f32_16x16x32_bf16 v[0:3], v[196:199], v[228:231], v[0:3]
	s_barrier
; #define PG8_STAGE(bufoff, gbase, voff) do { _Pragma("unroll") for (int _i = 0; _i < 2; ++_i) \
;         __builtin_amdgcn_global_load_lds((const unsigned*)((const char*)(gbase) + (voff)[_i]), (PG8_LAS unsigned*)(lds + (bufoff) + ldsw + _i * 8192), 16, 0, 0); } while (0)
; #define PG8_LDA(dst, b, h) do { _Pragma("unroll") for (int m = 0; m < 4; ++m) _Pragma("unroll") for (int k = 0; k < 2; ++k) dst[m][k] = *(const PG8_LAS bf16x8*)(lds + PG8_SA(b, h) + aoff + m * 2048 + k * 1024); } while (0)
; #define PG8_LDB(dst, b, h) do { _Pragma("unroll") for (int n = 0; n < 2; ++n) _Pragma("unroll") for (int k = 0; k < 2; ++k) dst[n][k] = *(const PG8_LAS bf16x8*)(lds + PG8_SB(b, h) + boff + n * 2048 + k * 1024); } while (0)
; #define PG8_MMA(ai, bj, At, Bt) do { __builtin_amdgcn_s_setprio(1); _Pragma("unroll") for (int m = 0; m < 4; ++m) _Pragma("unroll") for (int n = 0; n < 2; ++n) _Pragma("unroll") for (int k = 0; k < 2; ++k) \
;         acc[ai][bj][m][n] = __builtin_amdgcn_mfma_f32_16x16x32_bf16(Bt[n][k], At[m][k], acc[ai][bj][m][n], 0, 0, 0); __builtin_amdgcn_s_setprio(0); } while (0)
; #define PG8_WAIT_V(n) asm volatile("s_waitcnt vmcnt(" #n ")" ::: "memory")
; #define PG8_WAIT_L(n) asm volatile("s_waitcnt lgkmcnt(" #n ")" ::: "memory")
; #define PG8_BAR __builtin_amdgcn_s_barrier()
; template <class Epi, class Sched, bool ALIGN_EPI = false, bool SP2 = false>
; __device__ __forceinline__ void gemm_phase(PG8_LAS unsigned char* lds, const Gemm g, const Sched S, const Epi E, const int tid) {
;     ...
;         for (int t = 0; t < nt; t += 2) {
;             const bool last = (t == nt - 2);
;             const char* a1 = cA + (size_t)(t + 1) * kstep;
;             const char* a2 = last ? nA : cA + (size_t)(t + 2) * kstep; const char* b2 = last ? nB : cB + (size_t)(t + 2) * kstep;
;             const char* a3 = a2 + kstep; const char* b3 = b2 + kstep;
;     ...
;             PG8_LDB(B0, 1, 0); PG8_LDB(B1, 1, 1); PG8_SCHED; PG8_LDA(At, 1, 0); PG8_STAGE(PG8_SA(0, 1), a2 + hstepA, voffA);
;             PG8_WAIT_V(8); PG8_WAIT_L(0); PG8_BAR; PG8_MMA(0, 0, At, B0); PG8_MMA(0, 1, At, B1); PG8_BAR; PG8_SCHED;
;             PG8_LDA(At, 1, 1); PG8_STAGE(PG8_SB(1, 0), b3, voffB); PG8_STAGE(PG8_SB(1, 1), b3 + hstepB, voffB); PG8_STAGE(PG8_SA(1, 0), a3, voffA);
;             PG8_WAIT_V(8); PG8_WAIT_L(0); PG8_BAR; PG8_MMA(1, 0, At, B0); PG8_MMA(1, 1, At, B1); PG8_BAR; PG8_SCHED;
	s_add_i32 s66, 0, 0x18000
	s_add_i32 s67, 0, 0x1c000
	v_add_u32_e32 v176, s66, v166
	v_add_u32_e32 v187, s67, v166
	ds_read_b128 v[146:149], v176
	ds_read_b128 v[150:153], v176 offset:1024
	ds_read_b128 v[172:175], v176 offset:2048
	ds_read_b128 v[176:179], v176 offset:3072
	ds_read_b128 v[180:183], v187
	ds_read_b128 v[188:191], v187 offset:1024
	ds_read_b128 v[192:195], v187 offset:2048
	ds_read_b128 v[196:199], v187 offset:3072
	s_add_u32 s36, s36, 0x40000
	s_addc_u32 s37, s37, 0
	s_mov_b32 m0, s48
	ds_read_b128 v[200:203], v171 offset:32768
	ds_read_b128 v[204:207], v171 offset:33792
	ds_read_b128 v[208:211], v171 offset:34816
	ds_read_b128 v[212:215], v171 offset:35840
	ds_read_b128 v[216:219], v171 offset:36864
	ds_read_b128 v[220:223], v171 offset:37888
	ds_read_b128 v[224:227], v171 offset:38912
	ds_read_b128 v[228:231], v171 offset:39936
	global_load_lds_dwordx4 v128, s[36:37]
	s_mov_b32 m0, s49
	s_nop 0
	global_load_lds_dwordx4 v132, s[36:37]
	s_waitcnt vmcnt(8)
	s_waitcnt lgkmcnt(0)
	s_barrier
	s_waitcnt lgkmcnt(0)
	v_mfma_f32_16x16x32_bf16 v[124:127], v[146:149], v[200:203], v[124:127]
	v_mfma_f32_16x16x32_bf16 v[120:123], v[172:175], v[200:203], v[120:123]
	v_mfma_f32_16x16x32_bf16 v[108:111], v[146:149], v[208:211], v[108:111]
	v_mfma_f32_16x16x32_bf16 v[104:107], v[172:175], v[208:211], v[104:107]
	v_mfma_f32_16x16x32_bf16 v[92:95], v[146:149], v[216:219], v[92:95]
	v_mfma_f32_16x16x32_bf16 v[88:91], v[172:175], v[216:219], v[88:91]
	v_mfma_f32_16x16x32_bf16 v[76:79], v[146:149], v[224:227], v[76:79]
	v_mfma_f32_16x16x32_bf16 v[72:75], v[172:175], v[224:227], v[72:75]
	v_mfma_f32_16x16x32_bf16 v[124:127], v[150:153], v[204:207], v[124:127]
	v_mfma_f32_16x16x32_bf16 v[120:123], v[176:179], v[204:207], v[120:123]
	v_mfma_f32_16x16x32_bf16 v[108:111], v[150:153], v[212:215], v[108:111]
	v_mfma_f32_16x16x32_bf16 v[104:107], v[176:179], v[212:215], v[104:107]
	v_mfma_f32_16x16x32_bf16 v[92:95], v[150:153], v[220:223], v[92:95]
	v_mfma_f32_16x16x32_bf16 v[88:91], v[176:179], v[220:223], v[88:91]
	v_mfma_f32_16x16x32_bf16 v[76:79], v[150:153], v[228:231], v[76:79]
	v_mfma_f32_16x16x32_bf16 v[72:75], v[176:179], v[228:231], v[72:75]
	v_mfma_f32_16x16x32_bf16 v[116:119], v[180:183], v[200:203], v[116:119]
	v_mfma_f32_16x16x32_bf16 v[112:115], v[192:195], v[200:203], v[112:115]
	v_mfma_f32_16x16x32_bf16 v[100:103], v[180:183], v[208:211], v[100:103]
	v_mfma_f32_16x16x32_bf16 v[96:99], v[192:195], v[208:211], v[96:99]
	v_mfma_f32_16x16x32_bf16 v[84:87], v[180:183], v[216:219], v[84:87]
	v_mfma_f32_16x16x32_bf16 v[80:83], v[192:195], v[216:219], v[80:83]
	v_mfma_f32_16x16x32_bf16 v[68:71], v[180:183], v[224:227], v[68:71]
	v_mfma_f32_16x16x32_bf16 v[64:67], v[192:195], v[224:227], v[64:67]
	v_mfma_f32_16x16x32_bf16 v[116:119], v[188:191], v[204:207], v[116:119]
	v_mfma_f32_16x16x32_bf16 v[112:115], v[196:199], v[204:207], v[112:115]
	v_mfma_f32_16x16x32_bf16 v[100:103], v[188:191], v[212:215], v[100:103]
	v_mfma_f32_16x16x32_bf16 v[96:99], v[196:199], v[212:215], v[96:99]
	v_mfma_f32_16x16x32_bf16 v[84:87], v[188:191], v[220:223], v[84:87]
	v_mfma_f32_16x16x32_bf16 v[80:83], v[196:199], v[220:223], v[80:83]
	v_mfma_f32_16x16x32_bf16 v[68:71], v[188:191], v[228:231], v[68:71]
	v_mfma_f32_16x16x32_bf16 v[64:67], v[196:199], v[228:231], v[64:67]
	s_barrier
	s_add_i32 s36, s66, s13
	s_mov_b32 m0, s36
	ds_read_b128 v[200:203], v171 offset:49152
	ds_read_b128 v[204:207], v171 offset:50176
	ds_read_b128 v[208:211], v171 offset:51200
	ds_read_b128 v[212:215], v171 offset:52224
	ds_read_b128 v[216:219], v171 offset:53248
	ds_read_b128 v[220:223], v171 offset:54272
	ds_read_b128 v[224:227], v171 offset:55296
	ds_read_b128 v[228:231], v171 offset:56320
	global_load_lds_dwordx4 v130, s[98:99]
	s_add_i32 m0, s36, 0x2000
	s_add_u32 s34, s34, 0x40080
	s_addc_u32 s35, s35, 0
	s_add_i32 s36, s67, s13
	global_load_lds_dwordx4 v134, s[98:99]
	s_mov_b32 m0, s36
	s_nop 0
	global_load_lds_dwordx4 v130, s[34:35]
	s_add_i32 m0, s36, 0x2000
	s_nop 0
	global_load_lds_dwordx4 v134, s[34:35]
	s_mov_b32 m0, s50
	s_nop 0
	global_load_lds_dwordx4 v128, s[100:101]
	s_mov_b32 m0, s51
	s_nop 0
	global_load_lds_dwordx4 v132, s[100:101]
	s_waitcnt vmcnt(8)
	s_waitcnt lgkmcnt(0)
	s_barrier
	s_waitcnt lgkmcnt(0)
	v_mfma_f32_16x16x32_bf16 v[60:63], v[146:149], v[200:203], v[60:63]
	v_mfma_f32_16x16x32_bf16 v[56:59], v[172:175], v[200:203], v[56:59]
	v_mfma_f32_16x16x32_bf16 v[44:47], v[146:149], v[208:211], v[44:47]
	v_mfma_f32_16x16x32_bf16 v[40:43], v[172:175], v[208:211], v[40:43]
	v_mfma_f32_16x16x32_bf16 v[28:31], v[146:149], v[216:219], v[28:31]
	v_mfma_f32_16x16x32_bf16 v[24:27], v[172:175], v[216:219], v[24:27]
	v_mfma_f32_16x16x32_bf16 v[12:15], v[146:149], v[224:227], v[12:15]
	v_mfma_f32_16x16x32_bf16 v[8:11], v[172:175], v[224:227], v[8:11]
	v_mfma_f32_16x16x32_bf16 v[60:63], v[150:153], v[204:207], v[60:63]
	v_mfma_f32_16x16x32_bf16 v[56:59], v[176:179], v[204:207], v[56:59]
	v_mfma_f32_16x16x32_bf16 v[44:47], v[150:153], v[212:215], v[44:47]
	v_mfma_f32_16x16x32_bf16 v[40:43], v[176:179], v[212:215], v[40:43]
	v_mfma_f32_16x16x32_bf16 v[28:31], v[150:153], v[220:223], v[28:31]
	v_mfma_f32_16x16x32_bf16 v[24:27], v[176:179], v[220:223], v[24:27]
	v_mfma_f32_16x16x32_bf16 v[12:15], v[150:153], v[228:231], v[12:15]
	v_mfma_f32_16x16x32_bf16 v[8:11], v[176:179], v[228:231], v[8:11]
	v_mfma_f32_16x16x32_bf16 v[52:55], v[180:183], v[200:203], v[52:55]
	v_mfma_f32_16x16x32_bf16 v[48:51], v[192:195], v[200:203], v[48:51]
	v_mfma_f32_16x16x32_bf16 v[36:39], v[180:183], v[208:211], v[36:39]
	v_mfma_f32_16x16x32_bf16 v[32:35], v[192:195], v[208:211], v[32:35]
	v_mfma_f32_16x16x32_bf16 v[20:23], v[180:183], v[216:219], v[20:23]
	v_mfma_f32_16x16x32_bf16 v[16:19], v[192:195], v[216:219], v[16:19]
	v_mfma_f32_16x16x32_bf16 v[4:7], v[180:183], v[224:227], v[4:7]
	v_mfma_f32_16x16x32_bf16 v[0:3], v[192:195], v[224:227], v[0:3]
	v_mfma_f32_16x16x32_bf16 v[52:55], v[188:191], v[204:207], v[52:55]
	v_mfma_f32_16x16x32_bf16 v[48:51], v[196:199], v[204:207], v[48:51]
	v_mfma_f32_16x16x32_bf16 v[36:39], v[188:191], v[212:215], v[36:39]
	v_mfma_f32_16x16x32_bf16 v[32:35], v[196:199], v[212:215], v[32:35]
	v_mfma_f32_16x16x32_bf16 v[20:23], v[188:191], v[220:223], v[20:23]
	v_mfma_f32_16x16x32_bf16 v[16:19], v[196:199], v[220:223], v[16:19]
	v_mfma_f32_16x16x32_bf16 v[4:7], v[188:191], v[228:231], v[4:7]
	v_mfma_f32_16x16x32_bf16 v[0:3], v[196:199], v[228:231], v[0:3]
	s_barrier
	s_add_i32 s65, s65, 2
	s_add_u32 s30, s30, 0x100
	s_addc_u32 s31, s31, 0
	s_add_u32 s63, s63, 0x100
	s_addc_u32 s64, s64, 0
	s_cmp_gt_u32 s65, 13
	s_cbranch_scc0 .LBB0_157
	s_and_b64 vcc, exec, s[10:11]
	s_cbranch_vccz .LBB0_160
	s_barrier

; #define PG8_STAGE(bufoff, gbase, voff) do { _Pragma("unroll") for (int _i = 0; _i < 2; ++_i) \
;         __builtin_amdgcn_global_load_lds((const unsigned*)((const char*)(gbase) + (voff)[_i]), (PG8_LAS unsigned*)(lds + (bufoff) + ldsw + _i * 8192), 16, 0, 0); } while (0)
; #define PG8_LDA(dst, b, h) do { _Pragma("unroll") for (int m = 0; m < 4; ++m) _Pragma("unroll") for (int k = 0; k < 2; ++k) dst[m][k] = *(const PG8_LAS bf16x8*)(lds + PG8_SA(b, h) + aoff + m * 2048 + k * 1024); } while (0)
; #define PG8_LDB(dst, b, h) do { _Pragma("unroll") for (int n = 0; n < 2; ++n) _Pragma("unroll") for (int k = 0; k < 2; ++k) dst[n][k] = *(const PG8_LAS bf16x8*)(lds + PG8_SB(b, h) + boff + n * 2048 + k * 1024); } while (0)
; #define PG8_MMA(ai, bj, At, Bt) do { __builtin_amdgcn_s_setprio(1); _Pragma("unroll") for (int m = 0; m < 4; ++m) _Pragma("unroll") for (int n = 0; n < 2; ++n) _Pragma("unroll") for (int k = 0; k < 2; ++k) \
;         acc[ai][bj][m][n] = __builtin_amdgcn_mfma_f32_16x16x32_bf16(Bt[n][k], At[m][k], acc[ai][bj][m][n], 0, 0, 0); __builtin_amdgcn_s_setprio(0); } while (0)
; #define PG8_WAIT_V(n) asm volatile("s_waitcnt vmcnt(" #n ")" ::: "memory")
; #define PG8_WAIT_L(n) asm volatile("s_waitcnt lgkmcnt(" #n ")" ::: "memory")
; #define PG8_BAR __builtin_amdgcn_s_barrier()
; #define PG8_SCHED __builtin_amdgcn_sched_barrier(0)
; template <class Epi, class Sched, bool ALIGN_EPI = false, bool SP2 = false>
; __device__ __forceinline__ void gemm_phase(PG8_LAS unsigned char* lds, const Gemm g, const Sched S, const Epi E, const int tid) {
;     ...
;             PG8_LDB(B0, 0, 0); PG8_LDB(B1, 0, 1); PG8_SCHED; PG8_LDA(At, 0, 0); PG8_STAGE(PG8_SA(1, 1), a1 + hstepA, voffA);
;             PG8_WAIT_V(8); PG8_WAIT_L(0); PG8_BAR; PG8_MMA(0, 0, At, B0); PG8_MMA(0, 1, At, B1); PG8_BAR; PG8_SCHED;
;             PG8_LDA(At, 0, 1); PG8_STAGE(PG8_SB(0, 0), b2, voffB); PG8_STAGE(PG8_SB(0, 1), b2 + hstepB, voffB); PG8_STAGE(PG8_SA(0, 0), a2, voffA);
;             PG8_WAIT_V(8); PG8_WAIT_L(0); PG8_BAR; PG8_MMA(1, 0, At, B0); PG8_MMA(1, 1, At, B1); PG8_BAR; PG8_SCHED;
.LBB0_204:
	ds_read_b128 v[150:153], v147
	ds_read_b128 v[166:169], v147 offset:1024
	ds_read_b128 v[170:173], v147 offset:2048
	ds_read_b128 v[174:177], v147 offset:3072
	ds_read_b128 v[178:181], v148
	ds_read_b128 v[182:185], v148 offset:1024
	ds_read_b128 v[188:191], v148 offset:2048
	ds_read_b128 v[192:195], v148 offset:3072
	s_add_u32 s52, s50, 0xfffc0080
	s_addc_u32 s53, s51, -1
	s_cmp_eq_u32 s80, 12
	s_cselect_b32 s55, s37, s53
	s_cselect_b32 s54, s76, s52
	s_cselect_b32 s53, s35, s79
	s_cselect_b32 s52, s77, s78
	s_add_i32 m0, s49, 0xc000
	ds_read_b128 v[196:199], v149
	ds_read_b128 v[200:203], v149 offset:1024
	ds_read_b128 v[204:207], v149 offset:2048
	ds_read_b128 v[208:211], v149 offset:3072
	ds_read_b128 v[212:215], v149 offset:4096
	ds_read_b128 v[216:219], v149 offset:5120
	ds_read_b128 v[220:223], v149 offset:6144
	ds_read_b128 v[224:227], v149 offset:7168
	global_load_lds_dwordx4 v138, s[50:51]
	s_add_i32 m0, s49, 0xe000
	s_nop 0
	global_load_lds_dwordx4 v140, s[50:51]
	s_waitcnt vmcnt(8)
	s_waitcnt lgkmcnt(0)
	s_barrier
	s_waitcnt lgkmcnt(0)
	v_mfma_f32_16x16x32_bf16 v[124:127], v[150:153], v[196:199], v[124:127]
	v_mfma_f32_16x16x32_bf16 v[120:123], v[170:173], v[196:199], v[120:123]
	v_mfma_f32_16x16x32_bf16 v[112:115], v[150:153], v[204:207], v[112:115]
	v_mfma_f32_16x16x32_bf16 v[104:107], v[170:173], v[204:207], v[104:107]
	v_mfma_f32_16x16x32_bf16 v[96:99], v[150:153], v[212:215], v[96:99]
	v_mfma_f32_16x16x32_bf16 v[88:91], v[170:173], v[212:215], v[88:91]
	v_mfma_f32_16x16x32_bf16 v[80:83], v[150:153], v[220:223], v[80:83]
	v_mfma_f32_16x16x32_bf16 v[72:75], v[170:173], v[220:223], v[72:75]
	v_mfma_f32_16x16x32_bf16 v[124:127], v[166:169], v[200:203], v[124:127]
	v_mfma_f32_16x16x32_bf16 v[120:123], v[174:177], v[200:203], v[120:123]
	v_mfma_f32_16x16x32_bf16 v[112:115], v[166:169], v[208:211], v[112:115]
	v_mfma_f32_16x16x32_bf16 v[104:107], v[174:177], v[208:211], v[104:107]
	v_mfma_f32_16x16x32_bf16 v[96:99], v[166:169], v[216:219], v[96:99]
	v_mfma_f32_16x16x32_bf16 v[88:91], v[174:177], v[216:219], v[88:91]
	v_mfma_f32_16x16x32_bf16 v[80:83], v[166:169], v[224:227], v[80:83]
	v_mfma_f32_16x16x32_bf16 v[72:75], v[174:177], v[224:227], v[72:75]
	v_mfma_f32_16x16x32_bf16 v[116:119], v[178:181], v[196:199], v[116:119]
	v_mfma_f32_16x16x32_bf16 v[108:111], v[188:191], v[196:199], v[108:111]
	v_mfma_f32_16x16x32_bf16 v[100:103], v[178:181], v[204:207], v[100:103]
	v_mfma_f32_16x16x32_bf16 v[92:95], v[188:191], v[204:207], v[92:95]
	v_mfma_f32_16x16x32_bf16 v[84:87], v[178:181], v[212:215], v[84:87]
	v_mfma_f32_16x16x32_bf16 v[76:79], v[188:191], v[212:215], v[76:79]
	v_mfma_f32_16x16x32_bf16 v[68:71], v[178:181], v[220:223], v[68:71]
	v_mfma_f32_16x16x32_bf16 v[64:67], v[188:191], v[220:223], v[64:67]
	v_mfma_f32_16x16x32_bf16 v[116:119], v[182:185], v[200:203], v[116:119]
	v_mfma_f32_16x16x32_bf16 v[108:111], v[192:195], v[200:203], v[108:111]
	v_mfma_f32_16x16x32_bf16 v[100:103], v[182:185], v[208:211], v[100:103]
	v_mfma_f32_16x16x32_bf16 v[92:95], v[192:195], v[208:211], v[92:95]
	v_mfma_f32_16x16x32_bf16 v[84:87], v[182:185], v[216:219], v[84:87]
	v_mfma_f32_16x16x32_bf16 v[76:79], v[192:195], v[216:219], v[76:79]
	v_mfma_f32_16x16x32_bf16 v[68:71], v[182:185], v[224:227], v[68:71]
	v_mfma_f32_16x16x32_bf16 v[64:67], v[192:195], v[224:227], v[64:67]
	s_barrier
	s_add_u32 s98, s52, 0x80
	s_addc_u32 s99, s53, 0
	s_add_u32 s100, s54, 0x80
	s_addc_u32 s101, s55, 0
	s_add_i32 s81, s73, s65
	s_mov_b32 m0, s81
	ds_read_b128 v[196:199], v149 offset:16384
	ds_read_b128 v[200:203], v149 offset:17408
	ds_read_b128 v[204:207], v149 offset:18432
	ds_read_b128 v[208:211], v149 offset:19456
	ds_read_b128 v[212:215], v149 offset:20480
	ds_read_b128 v[216:219], v149 offset:21504
	ds_read_b128 v[220:223], v149 offset:22528
	ds_read_b128 v[224:227], v149 offset:23552
	global_load_lds_dwordx4 v130, s[52:53]
	s_add_i32 m0, s81, 0x2000
	s_add_u32 s82, s52, 0x40000
	s_addc_u32 s83, s53, 0
	s_add_i32 s81, s74, s65
	global_load_lds_dwordx4 v134, s[52:53]
	s_mov_b32 m0, s81
	s_nop 0
	global_load_lds_dwordx4 v130, s[82:83]
	s_add_i32 m0, s81, 0x2000
	s_nop 0
	global_load_lds_dwordx4 v134, s[82:83]
	s_mov_b32 m0, s49
	s_nop 0
	global_load_lds_dwordx4 v128, s[54:55]
	s_mov_b32 m0, s66
	s_nop 0
	global_load_lds_dwordx4 v132, s[54:55]
	s_waitcnt vmcnt(8)
	s_waitcnt lgkmcnt(0)
	s_barrier
	s_waitcnt lgkmcnt(0)
	v_mfma_f32_16x16x32_bf16 v[60:63], v[150:153], v[196:199], v[60:63]
	v_mfma_f32_16x16x32_bf16 v[56:59], v[170:173], v[196:199], v[56:59]
	v_mfma_f32_16x16x32_bf16 v[52:55], v[150:153], v[204:207], v[52:55]
	v_mfma_f32_16x16x32_bf16 v[44:47], v[170:173], v[204:207], v[44:47]
	v_mfma_f32_16x16x32_bf16 v[36:39], v[150:153], v[212:215], v[36:39]
	v_mfma_f32_16x16x32_bf16 v[28:31], v[170:173], v[212:215], v[28:31]
	v_mfma_f32_16x16x32_bf16 v[20:23], v[150:153], v[220:223], v[20:23]
	v_mfma_f32_16x16x32_bf16 v[12:15], v[170:173], v[220:223], v[12:15]
	v_mfma_f32_16x16x32_bf16 v[60:63], v[166:169], v[200:203], v[60:63]
	v_mfma_f32_16x16x32_bf16 v[56:59], v[174:177], v[200:203], v[56:59]
	v_mfma_f32_16x16x32_bf16 v[52:55], v[166:169], v[208:211], v[52:55]
	v_mfma_f32_16x16x32_bf16 v[44:47], v[174:177], v[208:211], v[44:47]
	v_mfma_f32_16x16x32_bf16 v[36:39], v[166:169], v[216:219], v[36:39]
	v_mfma_f32_16x16x32_bf16 v[28:31], v[174:177], v[216:219], v[28:31]
	v_mfma_f32_16x16x32_bf16 v[20:23], v[166:169], v[224:227], v[20:23]
	v_mfma_f32_16x16x32_bf16 v[12:15], v[174:177], v[224:227], v[12:15]
	v_mfma_f32_16x16x32_bf16 v[48:51], v[178:181], v[196:199], v[48:51]
	v_mfma_f32_16x16x32_bf16 v[40:43], v[188:191], v[196:199], v[40:43]
	v_mfma_f32_16x16x32_bf16 v[32:35], v[178:181], v[204:207], v[32:35]
	v_mfma_f32_16x16x32_bf16 v[24:27], v[188:191], v[204:207], v[24:27]
	v_mfma_f32_16x16x32_bf16 v[16:19], v[178:181], v[212:215], v[16:19]
	v_mfma_f32_16x16x32_bf16 v[8:11], v[188:191], v[212:215], v[8:11]
	v_mfma_f32_16x16x32_bf16 v[4:7], v[178:181], v[220:223], v[4:7]
	v_mfma_f32_16x16x32_bf16 v[0:3], v[188:191], v[220:223], v[0:3]
	v_mfma_f32_16x16x32_bf16 v[48:51], v[182:185], v[200:203], v[48:51]
	v_mfma_f32_16x16x32_bf16 v[40:43], v[192:195], v[200:203], v[40:43]
	v_mfma_f32_16x16x32_bf16 v[32:35], v[182:185], v[208:211], v[32:35]
	v_mfma_f32_16x16x32_bf16 v[24:27], v[192:195], v[208:211], v[24:27]
	v_mfma_f32_16x16x32_bf16 v[16:19], v[182:185], v[216:219], v[16:19]
	v_mfma_f32_16x16x32_bf16 v[8:11], v[192:195], v[216:219], v[8:11]
	v_mfma_f32_16x16x32_bf16 v[4:7], v[182:185], v[224:227], v[4:7]
	v_mfma_f32_16x16x32_bf16 v[0:3], v[192:195], v[224:227], v[0:3]
	s_barrier
; #define PG8_STAGE(bufoff, gbase, voff) do { _Pragma("unroll") for (int _i = 0; _i < 2; ++_i) \
;         __builtin_amdgcn_global_load_lds((const unsigned*)((const char*)(gbase) + (voff)[_i]), (PG8_LAS unsigned*)(lds + (bufoff) + ldsw + _i * 8192), 16, 0, 0); } while (0)
; #define PG8_LDA(dst, b, h) do { _Pragma("unroll") for (int m = 0; m < 4; ++m) _Pragma("unroll") for (int k = 0; k < 2; ++k) dst[m][k] = *(const PG8_LAS bf16x8*)(lds + PG8_SA(b, h) + aoff + m * 2048 + k * 1024); } while (0)
; #define PG8_LDB(dst, b, h) do { _Pragma("unroll") for (int n = 0; n < 2; ++n) _Pragma("unroll") for (int k = 0; k < 2; ++k) dst[n][k] = *(const PG8_LAS bf16x8*)(lds + PG8_SB(b, h) + boff + n * 2048 + k * 1024); } while (0)
; #define PG8_MMA(ai, bj, At, Bt) do { __builtin_amdgcn_s_setprio(1); _Pragma("unroll") for (int m = 0; m < 4; ++m) _Pragma("unroll") for (int n = 0; n < 2; ++n) _Pragma("unroll") for (int k = 0; k < 2; ++k) \
;         acc[ai][bj][m][n] = __builtin_amdgcn_mfma_f32_16x16x32_bf16(Bt[n][k], At[m][k], acc[ai][bj][m][n], 0, 0, 0); __builtin_amdgcn_s_setprio(0); } while (0)
; #define PG8_WAIT_V(n) asm volatile("s_waitcnt vmcnt(" #n ")" ::: "memory")
; #define PG8_WAIT_L(n) asm volatile("s_waitcnt lgkmcnt(" #n ")" ::: "memory")
; #define PG8_BAR __builtin_amdgcn_s_barrier()
; template <class Epi, class Sched, bool ALIGN_EPI = false, bool SP2 = false>
; __device__ __forceinline__ void gemm_phase(PG8_LAS unsigned char* lds, const Gemm g, const Sched S, const Epi E, const int tid) {
;     ...
;         for (int t = 0; t < nt; t += 2) {
;             const bool last = (t == nt - 2);
;             const char* a1 = cA + (size_t)(t + 1) * kstep;
;             const char* a2 = last ? nA : cA + (size_t)(t + 2) * kstep; const char* b2 = last ? nB : cB + (size_t)(t + 2) * kstep;
;             const char* a3 = a2 + kstep; const char* b3 = b2 + kstep;
;     ...
;             PG8_LDB(B0, 1, 0); PG8_LDB(B1, 1, 1); PG8_SCHED; PG8_LDA(At, 1, 0); PG8_STAGE(PG8_SA(0, 1), a2 + hstepA, voffA);
;             PG8_WAIT_V(8); PG8_WAIT_L(0); PG8_BAR; PG8_MMA(0, 0, At, B0); PG8_MMA(0, 1, At, B1); PG8_BAR; PG8_SCHED;
;             PG8_LDA(At, 1, 1); PG8_STAGE(PG8_SB(1, 0), b3, voffB); PG8_STAGE(PG8_SB(1, 1), b3 + hstepB, voffB); PG8_STAGE(PG8_SA(1, 0), a3, voffA);
;             PG8_WAIT_V(8); PG8_WAIT_L(0); PG8_BAR; PG8_MMA(1, 0, At, B0); PG8_MMA(1, 1, At, B1); PG8_BAR; PG8_SCHED;
	s_add_i32 s81, 0, 0x18000
	v_add_u32_e32 v165, s81, v145
	s_add_i32 s82, 0, 0x1c000
	ds_read_b128 v[150:153], v165
	ds_read_b128 v[166:169], v165 offset:1024
	ds_read_b128 v[170:173], v165 offset:2048
	ds_read_b128 v[174:177], v165 offset:3072
	v_add_u32_e32 v165, s82, v145
	ds_read_b128 v[178:181], v165
	ds_read_b128 v[182:185], v165 offset:1024
	ds_read_b128 v[188:191], v165 offset:2048
	ds_read_b128 v[192:195], v165 offset:3072
	s_add_u32 s54, s54, 0x40000
	s_addc_u32 s55, s55, 0
	s_mov_b32 m0, s67
	ds_read_b128 v[196:199], v149 offset:32768
	ds_read_b128 v[200:203], v149 offset:33792
	ds_read_b128 v[204:207], v149 offset:34816
	ds_read_b128 v[208:211], v149 offset:35840
	ds_read_b128 v[212:215], v149 offset:36864
	ds_read_b128 v[216:219], v149 offset:37888
	ds_read_b128 v[220:223], v149 offset:38912
	ds_read_b128 v[224:227], v149 offset:39936
	global_load_lds_dwordx4 v128, s[54:55]
	s_mov_b32 m0, s69
	s_nop 0
	global_load_lds_dwordx4 v132, s[54:55]
	s_waitcnt vmcnt(8)
	s_waitcnt lgkmcnt(0)
	s_barrier
	s_waitcnt lgkmcnt(0)
	v_mfma_f32_16x16x32_bf16 v[124:127], v[150:153], v[196:199], v[124:127]
	v_mfma_f32_16x16x32_bf16 v[120:123], v[170:173], v[196:199], v[120:123]
	v_mfma_f32_16x16x32_bf16 v[112:115], v[150:153], v[204:207], v[112:115]
	v_mfma_f32_16x16x32_bf16 v[104:107], v[170:173], v[204:207], v[104:107]
	v_mfma_f32_16x16x32_bf16 v[96:99], v[150:153], v[212:215], v[96:99]
	v_mfma_f32_16x16x32_bf16 v[88:91], v[170:173], v[212:215], v[88:91]
	v_mfma_f32_16x16x32_bf16 v[80:83], v[150:153], v[220:223], v[80:83]
	v_mfma_f32_16x16x32_bf16 v[72:75], v[170:173], v[220:223], v[72:75]
	v_mfma_f32_16x16x32_bf16 v[124:127], v[166:169], v[200:203], v[124:127]
	v_mfma_f32_16x16x32_bf16 v[120:123], v[174:177], v[200:203], v[120:123]
	v_mfma_f32_16x16x32_bf16 v[112:115], v[166:169], v[208:211], v[112:115]
	v_mfma_f32_16x16x32_bf16 v[104:107], v[174:177], v[208:211], v[104:107]
	v_mfma_f32_16x16x32_bf16 v[96:99], v[166:169], v[216:219], v[96:99]
	v_mfma_f32_16x16x32_bf16 v[88:91], v[174:177], v[216:219], v[88:91]
	v_mfma_f32_16x16x32_bf16 v[80:83], v[166:169], v[224:227], v[80:83]
	v_mfma_f32_16x16x32_bf16 v[72:75], v[174:177], v[224:227], v[72:75]
	v_mfma_f32_16x16x32_bf16 v[116:119], v[178:181], v[196:199], v[116:119]
	v_mfma_f32_16x16x32_bf16 v[108:111], v[188:191], v[196:199], v[108:111]
	v_mfma_f32_16x16x32_bf16 v[100:103], v[178:181], v[204:207], v[100:103]
	v_mfma_f32_16x16x32_bf16 v[92:95], v[188:191], v[204:207], v[92:95]
	v_mfma_f32_16x16x32_bf16 v[84:87], v[178:181], v[212:215], v[84:87]
	v_mfma_f32_16x16x32_bf16 v[76:79], v[188:191], v[212:215], v[76:79]
	v_mfma_f32_16x16x32_bf16 v[68:71], v[178:181], v[220:223], v[68:71]
	v_mfma_f32_16x16x32_bf16 v[64:67], v[188:191], v[220:223], v[64:67]
	v_mfma_f32_16x16x32_bf16 v[116:119], v[182:185], v[200:203], v[116:119]
	v_mfma_f32_16x16x32_bf16 v[108:111], v[192:195], v[200:203], v[108:111]
	v_mfma_f32_16x16x32_bf16 v[100:103], v[182:185], v[208:211], v[100:103]
	v_mfma_f32_16x16x32_bf16 v[92:95], v[192:195], v[208:211], v[92:95]
	v_mfma_f32_16x16x32_bf16 v[84:87], v[182:185], v[216:219], v[84:87]
	v_mfma_f32_16x16x32_bf16 v[76:79], v[192:195], v[216:219], v[76:79]
	v_mfma_f32_16x16x32_bf16 v[68:71], v[182:185], v[224:227], v[68:71]
	v_mfma_f32_16x16x32_bf16 v[64:67], v[192:195], v[224:227], v[64:67]
	s_barrier
	s_add_i32 s54, s81, s65
	s_mov_b32 m0, s54
	ds_read_b128 v[196:199], v149 offset:49152
	ds_read_b128 v[200:203], v149 offset:50176
	ds_read_b128 v[204:207], v149 offset:51200
	ds_read_b128 v[208:211], v149 offset:52224
	ds_read_b128 v[212:215], v149 offset:53248
	ds_read_b128 v[216:219], v149 offset:54272
	ds_read_b128 v[220:223], v149 offset:55296
	ds_read_b128 v[224:227], v149 offset:56320
	global_load_lds_dwordx4 v130, s[98:99]
	s_add_i32 m0, s54, 0x2000
	s_add_u32 s52, s52, 0x40080
	s_addc_u32 s53, s53, 0
	s_add_i32 s54, s82, s65
	global_load_lds_dwordx4 v134, s[98:99]
	s_mov_b32 m0, s54
	s_nop 0
	global_load_lds_dwordx4 v130, s[52:53]
	s_add_i32 m0, s54, 0x2000
	s_nop 0
	global_load_lds_dwordx4 v134, s[52:53]
	s_mov_b32 m0, s71
	s_nop 0
	global_load_lds_dwordx4 v128, s[100:101]
	s_mov_b32 m0, s72
	s_nop 0
	global_load_lds_dwordx4 v132, s[100:101]
	s_waitcnt vmcnt(8)
	s_waitcnt lgkmcnt(0)
	s_barrier
	s_waitcnt lgkmcnt(0)
	v_mfma_f32_16x16x32_bf16 v[60:63], v[150:153], v[196:199], v[60:63]
	v_mfma_f32_16x16x32_bf16 v[56:59], v[170:173], v[196:199], v[56:59]
	v_mfma_f32_16x16x32_bf16 v[52:55], v[150:153], v[204:207], v[52:55]
	v_mfma_f32_16x16x32_bf16 v[44:47], v[170:173], v[204:207], v[44:47]
	v_mfma_f32_16x16x32_bf16 v[36:39], v[150:153], v[212:215], v[36:39]
	v_mfma_f32_16x16x32_bf16 v[28:31], v[170:173], v[212:215], v[28:31]
	v_mfma_f32_16x16x32_bf16 v[20:23], v[150:153], v[220:223], v[20:23]
	v_mfma_f32_16x16x32_bf16 v[12:15], v[170:173], v[220:223], v[12:15]
	v_mfma_f32_16x16x32_bf16 v[60:63], v[166:169], v[200:203], v[60:63]
	v_mfma_f32_16x16x32_bf16 v[56:59], v[174:177], v[200:203], v[56:59]
	v_mfma_f32_16x16x32_bf16 v[52:55], v[166:169], v[208:211], v[52:55]
	v_mfma_f32_16x16x32_bf16 v[44:47], v[174:177], v[208:211], v[44:47]
	v_mfma_f32_16x16x32_bf16 v[36:39], v[166:169], v[216:219], v[36:39]
	v_mfma_f32_16x16x32_bf16 v[28:31], v[174:177], v[216:219], v[28:31]
	v_mfma_f32_16x16x32_bf16 v[20:23], v[166:169], v[224:227], v[20:23]
	v_mfma_f32_16x16x32_bf16 v[12:15], v[174:177], v[224:227], v[12:15]
	v_mfma_f32_16x16x32_bf16 v[48:51], v[178:181], v[196:199], v[48:51]
	v_mfma_f32_16x16x32_bf16 v[40:43], v[188:191], v[196:199], v[40:43]
	v_mfma_f32_16x16x32_bf16 v[32:35], v[178:181], v[204:207], v[32:35]
	v_mfma_f32_16x16x32_bf16 v[24:27], v[188:191], v[204:207], v[24:27]
	v_mfma_f32_16x16x32_bf16 v[16:19], v[178:181], v[212:215], v[16:19]
	v_mfma_f32_16x16x32_bf16 v[8:11], v[188:191], v[212:215], v[8:11]
	v_mfma_f32_16x16x32_bf16 v[4:7], v[178:181], v[220:223], v[4:7]
	v_mfma_f32_16x16x32_bf16 v[0:3], v[188:191], v[220:223], v[0:3]
	v_mfma_f32_16x16x32_bf16 v[48:51], v[182:185], v[200:203], v[48:51]
	v_mfma_f32_16x16x32_bf16 v[40:43], v[192:195], v[200:203], v[40:43]
	v_mfma_f32_16x16x32_bf16 v[32:35], v[182:185], v[208:211], v[32:35]
	v_mfma_f32_16x16x32_bf16 v[24:27], v[192:195], v[208:211], v[24:27]
	v_mfma_f32_16x16x32_bf16 v[16:19], v[182:185], v[216:219], v[16:19]
	v_mfma_f32_16x16x32_bf16 v[8:11], v[192:195], v[216:219], v[8:11]
	v_mfma_f32_16x16x32_bf16 v[4:7], v[182:185], v[224:227], v[4:7]
	v_mfma_f32_16x16x32_bf16 v[0:3], v[192:195], v[224:227], v[0:3]
	s_barrier
	s_add_i32 s80, s80, 2
	s_add_u32 s50, s50, 0x100
	s_addc_u32 s51, s51, 0
	s_add_u32 s78, s78, 0x100
	s_addc_u32 s79, s79, 0
	s_cmp_gt_u32 s80, 13
	s_cbranch_scc0 .LBB0_204
	s_and_b64 vcc, exec, s[10:11]
	s_cbranch_vccz .LBB0_207
	s_barrier

; #define PG8_STAGE(bufoff, gbase, voff) do { _Pragma("unroll") for (int _i = 0; _i < 2; ++_i) \
;         __builtin_amdgcn_global_load_lds((const unsigned*)((const char*)(gbase) + (voff)[_i]), (PG8_LAS unsigned*)(lds + (bufoff) + ldsw + _i * 8192), 16, 0, 0); } while (0)
; #define PG8_LDA(dst, b, h) do { _Pragma("unroll") for (int m = 0; m < 4; ++m) _Pragma("unroll") for (int k = 0; k < 2; ++k) dst[m][k] = *(const PG8_LAS bf16x8*)(lds + PG8_SA(b, h) + aoff + m * 2048 + k * 1024); } while (0)
; #define PG8_LDB(dst, b, h) do { _Pragma("unroll") for (int n = 0; n < 2; ++n) _Pragma("unroll") for (int k = 0; k < 2; ++k) dst[n][k] = *(const PG8_LAS bf16x8*)(lds + PG8_SB(b, h) + boff + n * 2048 + k * 1024); } while (0)
; #define PG8_MMA(ai, bj, At, Bt) do { __builtin_amdgcn_s_setprio(1); _Pragma("unroll") for (int m = 0; m < 4; ++m) _Pragma("unroll") for (int n = 0; n < 2; ++n) _Pragma("unroll") for (int k = 0; k < 2; ++k) \
;         acc[ai][bj][m][n] = __builtin_amdgcn_mfma_f32_16x16x32_bf16(Bt[n][k], At[m][k], acc[ai][bj][m][n], 0, 0, 0); __builtin_amdgcn_s_setprio(0); } while (0)
; #define PG8_WAIT_V(n) asm volatile("s_waitcnt vmcnt(" #n ")" ::: "memory")
; #define PG8_WAIT_L(n) asm volatile("s_waitcnt lgkmcnt(" #n ")" ::: "memory")
; #define PG8_BAR __builtin_amdgcn_s_barrier()
; #define PG8_SCHED __builtin_amdgcn_sched_barrier(0)
; template <class Epi, class Sched, bool ALIGN_EPI = false, bool SP2 = false>
; __device__ __forceinline__ void gemm_phase(PG8_LAS unsigned char* lds, const Gemm g, const Sched S, const Epi E, const int tid) {
;     ...
;             PG8_LDB(B0, 0, 0); PG8_LDB(B1, 0, 1); PG8_SCHED; PG8_LDA(At, 0, 0); PG8_STAGE(PG8_SA(1, 1), a1 + hstepA, voffA);
;             PG8_WAIT_V(8); PG8_WAIT_L(0); PG8_BAR; PG8_MMA(0, 0, At, B0); PG8_MMA(0, 1, At, B1); PG8_BAR; PG8_SCHED;
;             PG8_LDA(At, 0, 1); PG8_STAGE(PG8_SB(0, 0), b2, voffB); PG8_STAGE(PG8_SB(0, 1), b2 + hstepB, voffB); PG8_STAGE(PG8_SA(0, 0), a2, voffA);
;             PG8_WAIT_V(8); PG8_WAIT_L(0); PG8_BAR; PG8_MMA(1, 0, At, B0); PG8_MMA(1, 1, At, B1); PG8_BAR; PG8_SCHED;
.LBB0_220:
	ds_read_b128 v[148:151], v145
	ds_read_b128 v[152:155], v145 offset:1024
	ds_read_b128 v[156:159], v145 offset:2048
	ds_read_b128 v[160:163], v145 offset:3072
	ds_read_b128 v[164:167], v146
	ds_read_b128 v[168:171], v146 offset:1024
	ds_read_b128 v[172:175], v146 offset:2048
	ds_read_b128 v[176:179], v146 offset:3072
	s_add_u32 s52, s50, 0xfffc0080
	s_addc_u32 s53, s51, -1
	s_cmp_eq_u32 s77, 12
	s_cselect_b32 s55, s37, s53
	s_cselect_b32 s54, s73, s52
	s_cselect_b32 s53, s35, s76
	s_cselect_b32 s52, s74, s75
	s_add_i32 m0, s49, 0xc000
	ds_read_b128 v[180:183], v147
	ds_read_b128 v[188:191], v147 offset:1024
	ds_read_b128 v[192:195], v147 offset:2048
	ds_read_b128 v[196:199], v147 offset:3072
	ds_read_b128 v[200:203], v147 offset:4096
	ds_read_b128 v[204:207], v147 offset:5120
	ds_read_b128 v[208:211], v147 offset:6144
	ds_read_b128 v[212:215], v147 offset:7168
	global_load_lds_dwordx4 v136, s[50:51]
	s_add_i32 m0, s49, 0xe000
	s_nop 0
	global_load_lds_dwordx4 v138, s[50:51]
	s_waitcnt vmcnt(8)
	s_waitcnt lgkmcnt(0)
	s_barrier
	s_waitcnt lgkmcnt(0)
	v_mfma_f32_16x16x32_bf16 v[124:127], v[148:151], v[180:183], v[124:127]
	v_mfma_f32_16x16x32_bf16 v[120:123], v[156:159], v[180:183], v[120:123]
	v_mfma_f32_16x16x32_bf16 v[112:115], v[148:151], v[192:195], v[112:115]
	v_mfma_f32_16x16x32_bf16 v[104:107], v[156:159], v[192:195], v[104:107]
	v_mfma_f32_16x16x32_bf16 v[96:99], v[148:151], v[200:203], v[96:99]
	v_mfma_f32_16x16x32_bf16 v[88:91], v[156:159], v[200:203], v[88:91]
	v_mfma_f32_16x16x32_bf16 v[80:83], v[148:151], v[208:211], v[80:83]
	v_mfma_f32_16x16x32_bf16 v[72:75], v[156:159], v[208:211], v[72:75]
	v_mfma_f32_16x16x32_bf16 v[124:127], v[152:155], v[188:191], v[124:127]
	v_mfma_f32_16x16x32_bf16 v[120:123], v[160:163], v[188:191], v[120:123]
	v_mfma_f32_16x16x32_bf16 v[112:115], v[152:155], v[196:199], v[112:115]
	v_mfma_f32_16x16x32_bf16 v[104:107], v[160:163], v[196:199], v[104:107]
	v_mfma_f32_16x16x32_bf16 v[96:99], v[152:155], v[204:207], v[96:99]
	v_mfma_f32_16x16x32_bf16 v[88:91], v[160:163], v[204:207], v[88:91]
	v_mfma_f32_16x16x32_bf16 v[80:83], v[152:155], v[212:215], v[80:83]
	v_mfma_f32_16x16x32_bf16 v[72:75], v[160:163], v[212:215], v[72:75]
	v_mfma_f32_16x16x32_bf16 v[116:119], v[164:167], v[180:183], v[116:119]
	v_mfma_f32_16x16x32_bf16 v[108:111], v[172:175], v[180:183], v[108:111]
	v_mfma_f32_16x16x32_bf16 v[100:103], v[164:167], v[192:195], v[100:103]
	v_mfma_f32_16x16x32_bf16 v[92:95], v[172:175], v[192:195], v[92:95]
	v_mfma_f32_16x16x32_bf16 v[84:87], v[164:167], v[200:203], v[84:87]
	v_mfma_f32_16x16x32_bf16 v[76:79], v[172:175], v[200:203], v[76:79]
	v_mfma_f32_16x16x32_bf16 v[68:71], v[164:167], v[208:211], v[68:71]
	v_mfma_f32_16x16x32_bf16 v[64:67], v[172:175], v[208:211], v[64:67]
	v_mfma_f32_16x16x32_bf16 v[116:119], v[168:171], v[188:191], v[116:119]
	v_mfma_f32_16x16x32_bf16 v[108:111], v[176:179], v[188:191], v[108:111]
	v_mfma_f32_16x16x32_bf16 v[100:103], v[168:171], v[196:199], v[100:103]
	v_mfma_f32_16x16x32_bf16 v[92:95], v[176:179], v[196:199], v[92:95]
	v_mfma_f32_16x16x32_bf16 v[84:87], v[168:171], v[204:207], v[84:87]
	v_mfma_f32_16x16x32_bf16 v[76:79], v[176:179], v[204:207], v[76:79]
	v_mfma_f32_16x16x32_bf16 v[68:71], v[168:171], v[212:215], v[68:71]
	v_mfma_f32_16x16x32_bf16 v[64:67], v[176:179], v[212:215], v[64:67]
	s_barrier
	s_add_u32 s98, s52, 0x80
	s_addc_u32 s99, s53, 0
	s_add_u32 s100, s54, 0x80
	s_addc_u32 s101, s55, 0
	s_add_i32 s78, s70, s62
	s_mov_b32 m0, s78
	ds_read_b128 v[180:183], v147 offset:16384
	ds_read_b128 v[188:191], v147 offset:17408
	ds_read_b128 v[192:195], v147 offset:18432
	ds_read_b128 v[196:199], v147 offset:19456
	ds_read_b128 v[200:203], v147 offset:20480
	ds_read_b128 v[204:207], v147 offset:21504
	ds_read_b128 v[208:211], v147 offset:22528
	ds_read_b128 v[212:215], v147 offset:23552
	global_load_lds_dwordx4 v130, s[52:53]
	s_add_i32 m0, s78, 0x2000
	s_add_u32 s78, s52, 0x40000
	s_addc_u32 s79, s53, 0
	s_add_i32 s80, s71, s62
	global_load_lds_dwordx4 v134, s[52:53]
	s_mov_b32 m0, s80
	s_nop 0
	global_load_lds_dwordx4 v130, s[78:79]
	s_add_i32 m0, s80, 0x2000
	s_nop 0
	global_load_lds_dwordx4 v134, s[78:79]
	s_mov_b32 m0, s49
	s_nop 0
	global_load_lds_dwordx4 v128, s[54:55]
	s_mov_b32 m0, s63
	s_nop 0
	global_load_lds_dwordx4 v132, s[54:55]
	s_waitcnt vmcnt(8)
	s_waitcnt lgkmcnt(0)
	s_barrier
	s_waitcnt lgkmcnt(0)
	v_mfma_f32_16x16x32_bf16 v[60:63], v[148:151], v[180:183], v[60:63]
	v_mfma_f32_16x16x32_bf16 v[56:59], v[156:159], v[180:183], v[56:59]
	v_mfma_f32_16x16x32_bf16 v[52:55], v[148:151], v[192:195], v[52:55]
	v_mfma_f32_16x16x32_bf16 v[44:47], v[156:159], v[192:195], v[44:47]
	v_mfma_f32_16x16x32_bf16 v[36:39], v[148:151], v[200:203], v[36:39]
	v_mfma_f32_16x16x32_bf16 v[28:31], v[156:159], v[200:203], v[28:31]
	v_mfma_f32_16x16x32_bf16 v[20:23], v[148:151], v[208:211], v[20:23]
	v_mfma_f32_16x16x32_bf16 v[12:15], v[156:159], v[208:211], v[12:15]
	v_mfma_f32_16x16x32_bf16 v[60:63], v[152:155], v[188:191], v[60:63]
	v_mfma_f32_16x16x32_bf16 v[56:59], v[160:163], v[188:191], v[56:59]
	v_mfma_f32_16x16x32_bf16 v[52:55], v[152:155], v[196:199], v[52:55]
	v_mfma_f32_16x16x32_bf16 v[44:47], v[160:163], v[196:199], v[44:47]
	v_mfma_f32_16x16x32_bf16 v[36:39], v[152:155], v[204:207], v[36:39]
	v_mfma_f32_16x16x32_bf16 v[28:31], v[160:163], v[204:207], v[28:31]
	v_mfma_f32_16x16x32_bf16 v[20:23], v[152:155], v[212:215], v[20:23]
	v_mfma_f32_16x16x32_bf16 v[12:15], v[160:163], v[212:215], v[12:15]
	v_mfma_f32_16x16x32_bf16 v[48:51], v[164:167], v[180:183], v[48:51]
	v_mfma_f32_16x16x32_bf16 v[40:43], v[172:175], v[180:183], v[40:43]
	v_mfma_f32_16x16x32_bf16 v[32:35], v[164:167], v[192:195], v[32:35]
	v_mfma_f32_16x16x32_bf16 v[24:27], v[172:175], v[192:195], v[24:27]
	v_mfma_f32_16x16x32_bf16 v[16:19], v[164:167], v[200:203], v[16:19]
	v_mfma_f32_16x16x32_bf16 v[8:11], v[172:175], v[200:203], v[8:11]
	v_mfma_f32_16x16x32_bf16 v[4:7], v[164:167], v[208:211], v[4:7]
	v_mfma_f32_16x16x32_bf16 v[0:3], v[172:175], v[208:211], v[0:3]
	v_mfma_f32_16x16x32_bf16 v[48:51], v[168:171], v[188:191], v[48:51]
	v_mfma_f32_16x16x32_bf16 v[40:43], v[176:179], v[188:191], v[40:43]
	v_mfma_f32_16x16x32_bf16 v[32:35], v[168:171], v[196:199], v[32:35]
	v_mfma_f32_16x16x32_bf16 v[24:27], v[176:179], v[196:199], v[24:27]
	v_mfma_f32_16x16x32_bf16 v[16:19], v[168:171], v[204:207], v[16:19]
	v_mfma_f32_16x16x32_bf16 v[8:11], v[176:179], v[204:207], v[8:11]
	v_mfma_f32_16x16x32_bf16 v[4:7], v[168:171], v[212:215], v[4:7]
	v_mfma_f32_16x16x32_bf16 v[0:3], v[176:179], v[212:215], v[0:3]
	s_barrier
; #define PG8_STAGE(bufoff, gbase, voff) do { _Pragma("unroll") for (int _i = 0; _i < 2; ++_i) \
;         __builtin_amdgcn_global_load_lds((const unsigned*)((const char*)(gbase) + (voff)[_i]), (PG8_LAS unsigned*)(lds + (bufoff) + ldsw + _i * 8192), 16, 0, 0); } while (0)
; #define PG8_LDA(dst, b, h) do { _Pragma("unroll") for (int m = 0; m < 4; ++m) _Pragma("unroll") for (int k = 0; k < 2; ++k) dst[m][k] = *(const PG8_LAS bf16x8*)(lds + PG8_SA(b, h) + aoff + m * 2048 + k * 1024); } while (0)
; #define PG8_LDB(dst, b, h) do { _Pragma("unroll") for (int n = 0; n < 2; ++n) _Pragma("unroll") for (int k = 0; k < 2; ++k) dst[n][k] = *(const PG8_LAS bf16x8*)(lds + PG8_SB(b, h) + boff + n * 2048 + k * 1024); } while (0)
; #define PG8_MMA(ai, bj, At, Bt) do { __builtin_amdgcn_s_setprio(1); _Pragma("unroll") for (int m = 0; m < 4; ++m) _Pragma("unroll") for (int n = 0; n < 2; ++n) _Pragma("unroll") for (int k = 0; k < 2; ++k) \
;         acc[ai][bj][m][n] = __builtin_amdgcn_mfma_f32_16x16x32_bf16(Bt[n][k], At[m][k], acc[ai][bj][m][n], 0, 0, 0); __builtin_amdgcn_s_setprio(0); } while (0)
; #define PG8_WAIT_V(n) asm volatile("s_waitcnt vmcnt(" #n ")" ::: "memory")
; #define PG8_WAIT_L(n) asm volatile("s_waitcnt lgkmcnt(" #n ")" ::: "memory")
; #define PG8_BAR __builtin_amdgcn_s_barrier()
; template <class Epi, class Sched, bool ALIGN_EPI = false, bool SP2 = false>
; __device__ __forceinline__ void gemm_phase(PG8_LAS unsigned char* lds, const Gemm g, const Sched S, const Epi E, const int tid) {
;     ...
;         for (int t = 0; t < nt; t += 2) {
;             const bool last = (t == nt - 2);
;             const char* a1 = cA + (size_t)(t + 1) * kstep;
;             const char* a2 = last ? nA : cA + (size_t)(t + 2) * kstep; const char* b2 = last ? nB : cB + (size_t)(t + 2) * kstep;
;             const char* a3 = a2 + kstep; const char* b3 = b2 + kstep;
;     ...
;             PG8_LDB(B0, 1, 0); PG8_LDB(B1, 1, 1); PG8_SCHED; PG8_LDA(At, 1, 0); PG8_STAGE(PG8_SA(0, 1), a2 + hstepA, voffA);
;             PG8_WAIT_V(8); PG8_WAIT_L(0); PG8_BAR; PG8_MMA(0, 0, At, B0); PG8_MMA(0, 1, At, B1); PG8_BAR; PG8_SCHED;
;             PG8_LDA(At, 1, 1); PG8_STAGE(PG8_SB(1, 0), b3, voffB); PG8_STAGE(PG8_SB(1, 1), b3 + hstepB, voffB); PG8_STAGE(PG8_SA(1, 0), a3, voffA);
;             PG8_WAIT_V(8); PG8_WAIT_L(0); PG8_BAR; PG8_MMA(1, 0, At, B0); PG8_MMA(1, 1, At, B1); PG8_BAR; PG8_SCHED;
	s_add_i32 s78, 0, 0x18000
	s_add_i32 s79, 0, 0x1c000
	v_add_u32_e32 v160, s78, v143
	v_add_u32_e32 v176, s79, v143
	ds_read_b128 v[148:151], v160
	ds_read_b128 v[152:155], v160 offset:1024
	ds_read_b128 v[156:159], v160 offset:2048
	ds_read_b128 v[160:163], v160 offset:3072
	ds_read_b128 v[164:167], v176
	ds_read_b128 v[168:171], v176 offset:1024
	ds_read_b128 v[172:175], v176 offset:2048
	ds_read_b128 v[176:179], v176 offset:3072
	s_add_u32 s54, s54, 0x40000
	s_addc_u32 s55, s55, 0
	s_mov_b32 m0, s64
	ds_read_b128 v[180:183], v147 offset:32768
	ds_read_b128 v[188:191], v147 offset:33792
	ds_read_b128 v[192:195], v147 offset:34816
	ds_read_b128 v[196:199], v147 offset:35840
	ds_read_b128 v[200:203], v147 offset:36864
	ds_read_b128 v[204:207], v147 offset:37888
	ds_read_b128 v[208:211], v147 offset:38912
	ds_read_b128 v[212:215], v147 offset:39936
	global_load_lds_dwordx4 v128, s[54:55]
	s_mov_b32 m0, s65
	s_nop 0
	global_load_lds_dwordx4 v132, s[54:55]
	s_waitcnt vmcnt(8)
	s_waitcnt lgkmcnt(0)
	s_barrier
	s_waitcnt lgkmcnt(0)
	v_mfma_f32_16x16x32_bf16 v[124:127], v[148:151], v[180:183], v[124:127]
	v_mfma_f32_16x16x32_bf16 v[120:123], v[156:159], v[180:183], v[120:123]
	v_mfma_f32_16x16x32_bf16 v[112:115], v[148:151], v[192:195], v[112:115]
	v_mfma_f32_16x16x32_bf16 v[104:107], v[156:159], v[192:195], v[104:107]
	v_mfma_f32_16x16x32_bf16 v[96:99], v[148:151], v[200:203], v[96:99]
	v_mfma_f32_16x16x32_bf16 v[88:91], v[156:159], v[200:203], v[88:91]
	v_mfma_f32_16x16x32_bf16 v[80:83], v[148:151], v[208:211], v[80:83]
	v_mfma_f32_16x16x32_bf16 v[72:75], v[156:159], v[208:211], v[72:75]
	v_mfma_f32_16x16x32_bf16 v[124:127], v[152:155], v[188:191], v[124:127]
	v_mfma_f32_16x16x32_bf16 v[120:123], v[160:163], v[188:191], v[120:123]
	v_mfma_f32_16x16x32_bf16 v[112:115], v[152:155], v[196:199], v[112:115]
	v_mfma_f32_16x16x32_bf16 v[104:107], v[160:163], v[196:199], v[104:107]
	v_mfma_f32_16x16x32_bf16 v[96:99], v[152:155], v[204:207], v[96:99]
	v_mfma_f32_16x16x32_bf16 v[88:91], v[160:163], v[204:207], v[88:91]
	v_mfma_f32_16x16x32_bf16 v[80:83], v[152:155], v[212:215], v[80:83]
	v_mfma_f32_16x16x32_bf16 v[72:75], v[160:163], v[212:215], v[72:75]
	v_mfma_f32_16x16x32_bf16 v[116:119], v[164:167], v[180:183], v[116:119]
	v_mfma_f32_16x16x32_bf16 v[108:111], v[172:175], v[180:183], v[108:111]
	v_mfma_f32_16x16x32_bf16 v[100:103], v[164:167], v[192:195], v[100:103]
	v_mfma_f32_16x16x32_bf16 v[92:95], v[172:175], v[192:195], v[92:95]
	v_mfma_f32_16x16x32_bf16 v[84:87], v[164:167], v[200:203], v[84:87]
	v_mfma_f32_16x16x32_bf16 v[76:79], v[172:175], v[200:203], v[76:79]
	v_mfma_f32_16x16x32_bf16 v[68:71], v[164:167], v[208:211], v[68:71]
	v_mfma_f32_16x16x32_bf16 v[64:67], v[172:175], v[208:211], v[64:67]
	v_mfma_f32_16x16x32_bf16 v[116:119], v[168:171], v[188:191], v[116:119]
	v_mfma_f32_16x16x32_bf16 v[108:111], v[176:179], v[188:191], v[108:111]
	v_mfma_f32_16x16x32_bf16 v[100:103], v[168:171], v[196:199], v[100:103]
	v_mfma_f32_16x16x32_bf16 v[92:95], v[176:179], v[196:199], v[92:95]
	v_mfma_f32_16x16x32_bf16 v[84:87], v[168:171], v[204:207], v[84:87]
	v_mfma_f32_16x16x32_bf16 v[76:79], v[176:179], v[204:207], v[76:79]
	v_mfma_f32_16x16x32_bf16 v[68:71], v[168:171], v[212:215], v[68:71]
	v_mfma_f32_16x16x32_bf16 v[64:67], v[176:179], v[212:215], v[64:67]
	s_barrier
	s_add_i32 s54, s78, s62
	s_mov_b32 m0, s54
	ds_read_b128 v[180:183], v147 offset:49152
	ds_read_b128 v[188:191], v147 offset:50176
	ds_read_b128 v[192:195], v147 offset:51200
	ds_read_b128 v[196:199], v147 offset:52224
	ds_read_b128 v[200:203], v147 offset:53248
	ds_read_b128 v[204:207], v147 offset:54272
	ds_read_b128 v[208:211], v147 offset:55296
	ds_read_b128 v[212:215], v147 offset:56320
	global_load_lds_dwordx4 v130, s[98:99]
	s_add_i32 m0, s54, 0x2000
	s_add_u32 s52, s52, 0x40080
	s_addc_u32 s53, s53, 0
	s_add_i32 s54, s79, s62
	global_load_lds_dwordx4 v134, s[98:99]
	s_mov_b32 m0, s54
	s_nop 0
	global_load_lds_dwordx4 v130, s[52:53]
	s_add_i32 m0, s54, 0x2000
	s_nop 0
	global_load_lds_dwordx4 v134, s[52:53]
	s_mov_b32 m0, s67
	s_nop 0
	global_load_lds_dwordx4 v128, s[100:101]
	s_mov_b32 m0, s69
	s_nop 0
	global_load_lds_dwordx4 v132, s[100:101]
	s_waitcnt vmcnt(8)
	s_waitcnt lgkmcnt(0)
	s_barrier
	s_waitcnt lgkmcnt(0)
	v_mfma_f32_16x16x32_bf16 v[60:63], v[148:151], v[180:183], v[60:63]
	v_mfma_f32_16x16x32_bf16 v[56:59], v[156:159], v[180:183], v[56:59]
	v_mfma_f32_16x16x32_bf16 v[52:55], v[148:151], v[192:195], v[52:55]
	v_mfma_f32_16x16x32_bf16 v[44:47], v[156:159], v[192:195], v[44:47]
	v_mfma_f32_16x16x32_bf16 v[36:39], v[148:151], v[200:203], v[36:39]
	v_mfma_f32_16x16x32_bf16 v[28:31], v[156:159], v[200:203], v[28:31]
	v_mfma_f32_16x16x32_bf16 v[20:23], v[148:151], v[208:211], v[20:23]
	v_mfma_f32_16x16x32_bf16 v[12:15], v[156:159], v[208:211], v[12:15]
	v_mfma_f32_16x16x32_bf16 v[60:63], v[152:155], v[188:191], v[60:63]
	v_mfma_f32_16x16x32_bf16 v[56:59], v[160:163], v[188:191], v[56:59]
	v_mfma_f32_16x16x32_bf16 v[52:55], v[152:155], v[196:199], v[52:55]
	v_mfma_f32_16x16x32_bf16 v[44:47], v[160:163], v[196:199], v[44:47]
	v_mfma_f32_16x16x32_bf16 v[36:39], v[152:155], v[204:207], v[36:39]
	v_mfma_f32_16x16x32_bf16 v[28:31], v[160:163], v[204:207], v[28:31]
	v_mfma_f32_16x16x32_bf16 v[20:23], v[152:155], v[212:215], v[20:23]
	v_mfma_f32_16x16x32_bf16 v[12:15], v[160:163], v[212:215], v[12:15]
	v_mfma_f32_16x16x32_bf16 v[48:51], v[164:167], v[180:183], v[48:51]
	v_mfma_f32_16x16x32_bf16 v[40:43], v[172:175], v[180:183], v[40:43]
	v_mfma_f32_16x16x32_bf16 v[32:35], v[164:167], v[192:195], v[32:35]
	v_mfma_f32_16x16x32_bf16 v[24:27], v[172:175], v[192:195], v[24:27]
	v_mfma_f32_16x16x32_bf16 v[16:19], v[164:167], v[200:203], v[16:19]
	v_mfma_f32_16x16x32_bf16 v[8:11], v[172:175], v[200:203], v[8:11]
	v_mfma_f32_16x16x32_bf16 v[4:7], v[164:167], v[208:211], v[4:7]
	v_mfma_f32_16x16x32_bf16 v[0:3], v[172:175], v[208:211], v[0:3]
	v_mfma_f32_16x16x32_bf16 v[48:51], v[168:171], v[188:191], v[48:51]
	v_mfma_f32_16x16x32_bf16 v[40:43], v[176:179], v[188:191], v[40:43]
	v_mfma_f32_16x16x32_bf16 v[32:35], v[168:171], v[196:199], v[32:35]
	v_mfma_f32_16x16x32_bf16 v[24:27], v[176:179], v[196:199], v[24:27]
	v_mfma_f32_16x16x32_bf16 v[16:19], v[168:171], v[204:207], v[16:19]
	v_mfma_f32_16x16x32_bf16 v[8:11], v[176:179], v[204:207], v[8:11]
	v_mfma_f32_16x16x32_bf16 v[4:7], v[168:171], v[212:215], v[4:7]
	v_mfma_f32_16x16x32_bf16 v[0:3], v[176:179], v[212:215], v[0:3]
	s_barrier
	s_add_i32 s77, s77, 2
	s_add_u32 s50, s50, 0x100
	s_addc_u32 s51, s51, 0
	s_add_u32 s75, s75, 0x100
	s_addc_u32 s76, s76, 0
	s_cmp_gt_u32 s77, 13
	s_cbranch_scc0 .LBB0_220
	s_and_b64 vcc, exec, s[8:9]
	s_cbranch_vccz .LBB0_223
	s_barrier

; #define PG8_STAGE(bufoff, gbase, voff) do { _Pragma("unroll") for (int _i = 0; _i < 2; ++_i) \
;         __builtin_amdgcn_global_load_lds((const unsigned*)((const char*)(gbase) + (voff)[_i]), (PG8_LAS unsigned*)(lds + (bufoff) + ldsw + _i * 8192), 16, 0, 0); } while (0)
; #define PG8_LDA(dst, b, h) do { _Pragma("unroll") for (int m = 0; m < 4; ++m) _Pragma("unroll") for (int k = 0; k < 2; ++k) dst[m][k] = *(const PG8_LAS bf16x8*)(lds + PG8_SA(b, h) + aoff + m * 2048 + k * 1024); } while (0)
; #define PG8_LDB(dst, b, h) do { _Pragma("unroll") for (int n = 0; n < 2; ++n) _Pragma("unroll") for (int k = 0; k < 2; ++k) dst[n][k] = *(const PG8_LAS bf16x8*)(lds + PG8_SB(b, h) + boff + n * 2048 + k * 1024); } while (0)
; #define PG8_MMA(ai, bj, At, Bt) do { __builtin_amdgcn_s_setprio(1); _Pragma("unroll") for (int m = 0; m < 4; ++m) _Pragma("unroll") for (int n = 0; n < 2; ++n) _Pragma("unroll") for (int k = 0; k < 2; ++k) \
;         acc[ai][bj][m][n] = __builtin_amdgcn_mfma_f32_16x16x32_bf16(Bt[n][k], At[m][k], acc[ai][bj][m][n], 0, 0, 0); __builtin_amdgcn_s_setprio(0); } while (0)
; #define PG8_WAIT_V(n) asm volatile("s_waitcnt vmcnt(" #n ")" ::: "memory")
; #define PG8_WAIT_L(n) asm volatile("s_waitcnt lgkmcnt(" #n ")" ::: "memory")
; #define PG8_BAR __builtin_amdgcn_s_barrier()
; #define PG8_SCHED __builtin_amdgcn_sched_barrier(0)
; template <class Epi, class Sched, bool ALIGN_EPI = false, bool SP2 = false>
; __device__ __forceinline__ void gemm_phase(PG8_LAS unsigned char* lds, const Gemm g, const Sched S, const Epi E, const int tid) {
;     ...
;             PG8_LDB(B0, 0, 0); PG8_LDB(B1, 0, 1); PG8_SCHED; PG8_LDA(At, 0, 0); PG8_STAGE(PG8_SA(1, 1), a1 + hstepA, voffA);
;             PG8_WAIT_V(8); PG8_WAIT_L(0); PG8_BAR; PG8_MMA(0, 0, At, B0); PG8_MMA(0, 1, At, B1); PG8_BAR; PG8_SCHED;
;             PG8_LDA(At, 0, 1); PG8_STAGE(PG8_SB(0, 0), b2, voffB); PG8_STAGE(PG8_SB(0, 1), b2 + hstepB, voffB); PG8_STAGE(PG8_SA(0, 0), a2, voffA);
;             PG8_WAIT_V(8); PG8_WAIT_L(0); PG8_BAR; PG8_MMA(1, 0, At, B0); PG8_MMA(1, 1, At, B1); PG8_BAR; PG8_SCHED;
.LBB0_297:
	v_add_u32_e32 v162, s64, v149
	v_add_u32_e32 v178, s65, v149
	ds_read_b128 v[144:147], v162
	ds_read_b128 v[154:157], v162 offset:1024
	ds_read_b128 v[158:161], v162 offset:2048
	ds_read_b128 v[162:165], v162 offset:3072
	ds_read_b128 v[166:169], v178
	ds_read_b128 v[170:173], v178 offset:1024
	ds_read_b128 v[174:177], v178 offset:2048
	ds_read_b128 v[178:181], v178 offset:3072
	s_add_u32 s34, s30, 0x100
	s_addc_u32 s35, s31, 0
	s_cmp_eq_u32 s73, 40
	s_cselect_b32 s39, s7, s35
	s_cselect_b32 s38, s6, s34
	s_cselect_b32 s37, s29, s72
	s_cselect_b32 s36, s28, s71
	s_add_i32 m0, s54, 0xc000
	ds_read_b128 v[182:185], v153
	ds_read_b128 v[188:191], v153 offset:1024
	ds_read_b128 v[192:195], v153 offset:2048
	ds_read_b128 v[196:199], v153 offset:3072
	ds_read_b128 v[200:203], v153 offset:4096
	ds_read_b128 v[204:207], v153 offset:5120
	ds_read_b128 v[208:211], v153 offset:6144
	ds_read_b128 v[212:215], v153 offset:7168
	global_load_lds_dwordx4 v136, s[30:31]
	s_add_i32 m0, s54, 0xe000
	s_nop 0
	global_load_lds_dwordx4 v138, s[30:31]
	s_waitcnt vmcnt(8)
	s_waitcnt lgkmcnt(0)
	s_barrier
	s_waitcnt lgkmcnt(0)
	v_mfma_f32_16x16x32_bf16 v[112:115], v[144:147], v[182:185], v[112:115]
	v_mfma_f32_16x16x32_bf16 v[120:123], v[158:161], v[182:185], v[120:123]
	v_mfma_f32_16x16x32_bf16 v[96:99], v[144:147], v[192:195], v[96:99]
	v_mfma_f32_16x16x32_bf16 v[104:107], v[158:161], v[192:195], v[104:107]
	v_mfma_f32_16x16x32_bf16 v[80:83], v[144:147], v[200:203], v[80:83]
	v_mfma_f32_16x16x32_bf16 v[88:91], v[158:161], v[200:203], v[88:91]
	v_mfma_f32_16x16x32_bf16 v[64:67], v[144:147], v[208:211], v[64:67]
	v_mfma_f32_16x16x32_bf16 v[72:75], v[158:161], v[208:211], v[72:75]
	v_mfma_f32_16x16x32_bf16 v[112:115], v[154:157], v[188:191], v[112:115]
	v_mfma_f32_16x16x32_bf16 v[120:123], v[162:165], v[188:191], v[120:123]
	v_mfma_f32_16x16x32_bf16 v[96:99], v[154:157], v[196:199], v[96:99]
	v_mfma_f32_16x16x32_bf16 v[104:107], v[162:165], v[196:199], v[104:107]
	v_mfma_f32_16x16x32_bf16 v[80:83], v[154:157], v[204:207], v[80:83]
	v_mfma_f32_16x16x32_bf16 v[88:91], v[162:165], v[204:207], v[88:91]
	v_mfma_f32_16x16x32_bf16 v[64:67], v[154:157], v[212:215], v[64:67]
	v_mfma_f32_16x16x32_bf16 v[72:75], v[162:165], v[212:215], v[72:75]
	v_mfma_f32_16x16x32_bf16 v[116:119], v[166:169], v[182:185], v[116:119]
	v_mfma_f32_16x16x32_bf16 v[124:127], v[174:177], v[182:185], v[124:127]
	v_mfma_f32_16x16x32_bf16 v[100:103], v[166:169], v[192:195], v[100:103]
	v_mfma_f32_16x16x32_bf16 v[108:111], v[174:177], v[192:195], v[108:111]
	v_mfma_f32_16x16x32_bf16 v[84:87], v[166:169], v[200:203], v[84:87]
	v_mfma_f32_16x16x32_bf16 v[92:95], v[174:177], v[200:203], v[92:95]
	v_mfma_f32_16x16x32_bf16 v[68:71], v[166:169], v[208:211], v[68:71]
	v_mfma_f32_16x16x32_bf16 v[76:79], v[174:177], v[208:211], v[76:79]
	v_mfma_f32_16x16x32_bf16 v[116:119], v[170:173], v[188:191], v[116:119]
	v_mfma_f32_16x16x32_bf16 v[124:127], v[178:181], v[188:191], v[124:127]
	v_mfma_f32_16x16x32_bf16 v[100:103], v[170:173], v[196:199], v[100:103]
	v_mfma_f32_16x16x32_bf16 v[108:111], v[178:181], v[196:199], v[108:111]
	v_mfma_f32_16x16x32_bf16 v[84:87], v[170:173], v[204:207], v[84:87]
	v_mfma_f32_16x16x32_bf16 v[92:95], v[178:181], v[204:207], v[92:95]
	v_mfma_f32_16x16x32_bf16 v[68:71], v[170:173], v[212:215], v[68:71]
	v_mfma_f32_16x16x32_bf16 v[76:79], v[178:181], v[212:215], v[76:79]
	s_barrier
	s_add_u32 s98, s36, 0x80
	s_addc_u32 s99, s37, 0
	s_add_u32 s100, s38, 0x80
	s_addc_u32 s101, s39, 0
	s_add_i32 s30, s64, s51
	s_mov_b32 m0, s30
	ds_read_b128 v[182:185], v153 offset:16384
	ds_read_b128 v[188:191], v153 offset:17408
	ds_read_b128 v[192:195], v153 offset:18432
	ds_read_b128 v[196:199], v153 offset:19456
	ds_read_b128 v[200:203], v153 offset:20480
	ds_read_b128 v[204:207], v153 offset:21504
	ds_read_b128 v[208:211], v153 offset:22528
	ds_read_b128 v[212:215], v153 offset:23552
	global_load_lds_dwordx4 v130, s[36:37]
	s_add_i32 m0, s30, 0x2000
	s_add_u32 s30, s36, 0xb0000
	s_addc_u32 s31, s37, 0
	s_add_i32 s74, s65, s51
	global_load_lds_dwordx4 v134, s[36:37]
	s_mov_b32 m0, s74
	s_nop 0
	global_load_lds_dwordx4 v130, s[30:31]
	s_add_i32 m0, s74, 0x2000
	s_nop 0
	global_load_lds_dwordx4 v134, s[30:31]
	s_mov_b32 m0, s54
	s_nop 0
	global_load_lds_dwordx4 v128, s[38:39]
	s_mov_b32 m0, s55
	s_nop 0
	global_load_lds_dwordx4 v132, s[38:39]
	s_waitcnt vmcnt(8)
	s_waitcnt lgkmcnt(0)
	s_barrier
	s_waitcnt lgkmcnt(0)
	v_mfma_f32_16x16x32_bf16 v[48:51], v[144:147], v[182:185], v[48:51]
	v_mfma_f32_16x16x32_bf16 v[56:59], v[158:161], v[182:185], v[56:59]
	v_mfma_f32_16x16x32_bf16 v[24:27], v[144:147], v[192:195], v[24:27]
	v_mfma_f32_16x16x32_bf16 v[32:35], v[158:161], v[192:195], v[32:35]
	v_mfma_f32_16x16x32_bf16 v[0:3], v[144:147], v[200:203], v[0:3]
	v_mfma_f32_16x16x32_bf16 v[4:7], v[158:161], v[200:203], v[4:7]
	v_mfma_f32_16x16x32_bf16 v[8:11], v[144:147], v[208:211], v[8:11]
	v_mfma_f32_16x16x32_bf16 v[16:19], v[158:161], v[208:211], v[16:19]
	v_mfma_f32_16x16x32_bf16 v[48:51], v[154:157], v[188:191], v[48:51]
	v_mfma_f32_16x16x32_bf16 v[56:59], v[162:165], v[188:191], v[56:59]
	v_mfma_f32_16x16x32_bf16 v[24:27], v[154:157], v[196:199], v[24:27]
	v_mfma_f32_16x16x32_bf16 v[32:35], v[162:165], v[196:199], v[32:35]
	v_mfma_f32_16x16x32_bf16 v[0:3], v[154:157], v[204:207], v[0:3]
	v_mfma_f32_16x16x32_bf16 v[4:7], v[162:165], v[204:207], v[4:7]
	v_mfma_f32_16x16x32_bf16 v[8:11], v[154:157], v[212:215], v[8:11]
	v_mfma_f32_16x16x32_bf16 v[16:19], v[162:165], v[212:215], v[16:19]
	v_mfma_f32_16x16x32_bf16 v[52:55], v[166:169], v[182:185], v[52:55]
	v_mfma_f32_16x16x32_bf16 v[60:63], v[174:177], v[182:185], v[60:63]
	v_mfma_f32_16x16x32_bf16 v[28:31], v[166:169], v[192:195], v[28:31]
	v_mfma_f32_16x16x32_bf16 v[36:39], v[174:177], v[192:195], v[36:39]
	v_mfma_f32_16x16x32_bf16 v[40:43], v[166:169], v[200:203], v[40:43]
	v_mfma_f32_16x16x32_bf16 v[44:47], v[174:177], v[200:203], v[44:47]
	v_mfma_f32_16x16x32_bf16 v[12:15], v[166:169], v[208:211], v[12:15]
	v_mfma_f32_16x16x32_bf16 v[20:23], v[174:177], v[208:211], v[20:23]
	v_mfma_f32_16x16x32_bf16 v[52:55], v[170:173], v[188:191], v[52:55]
	v_mfma_f32_16x16x32_bf16 v[60:63], v[178:181], v[188:191], v[60:63]
	v_mfma_f32_16x16x32_bf16 v[28:31], v[170:173], v[196:199], v[28:31]
	v_mfma_f32_16x16x32_bf16 v[36:39], v[178:181], v[196:199], v[36:39]
	v_mfma_f32_16x16x32_bf16 v[40:43], v[170:173], v[204:207], v[40:43]
	v_mfma_f32_16x16x32_bf16 v[44:47], v[178:181], v[204:207], v[44:47]
	v_mfma_f32_16x16x32_bf16 v[12:15], v[170:173], v[212:215], v[12:15]
	v_mfma_f32_16x16x32_bf16 v[20:23], v[178:181], v[212:215], v[20:23]
	s_barrier
; #define PG8_STAGE(bufoff, gbase, voff) do { _Pragma("unroll") for (int _i = 0; _i < 2; ++_i) \
;         __builtin_amdgcn_global_load_lds((const unsigned*)((const char*)(gbase) + (voff)[_i]), (PG8_LAS unsigned*)(lds + (bufoff) + ldsw + _i * 8192), 16, 0, 0); } while (0)
; #define PG8_LDA(dst, b, h) do { _Pragma("unroll") for (int m = 0; m < 4; ++m) _Pragma("unroll") for (int k = 0; k < 2; ++k) dst[m][k] = *(const PG8_LAS bf16x8*)(lds + PG8_SA(b, h) + aoff + m * 2048 + k * 1024); } while (0)
; #define PG8_LDB(dst, b, h) do { _Pragma("unroll") for (int n = 0; n < 2; ++n) _Pragma("unroll") for (int k = 0; k < 2; ++k) dst[n][k] = *(const PG8_LAS bf16x8*)(lds + PG8_SB(b, h) + boff + n * 2048 + k * 1024); } while (0)
; #define PG8_MMA(ai, bj, At, Bt) do { __builtin_amdgcn_s_setprio(1); _Pragma("unroll") for (int m = 0; m < 4; ++m) _Pragma("unroll") for (int n = 0; n < 2; ++n) _Pragma("unroll") for (int k = 0; k < 2; ++k) \
;         acc[ai][bj][m][n] = __builtin_amdgcn_mfma_f32_16x16x32_bf16(Bt[n][k], At[m][k], acc[ai][bj][m][n], 0, 0, 0); __builtin_amdgcn_s_setprio(0); } while (0)
; #define PG8_WAIT_V(n) asm volatile("s_waitcnt vmcnt(" #n ")" ::: "memory")
; #define PG8_WAIT_L(n) asm volatile("s_waitcnt lgkmcnt(" #n ")" ::: "memory")
; #define PG8_BAR __builtin_amdgcn_s_barrier()
; template <class Epi, class Sched, bool ALIGN_EPI = false, bool SP2 = false>
; __device__ __forceinline__ void gemm_phase(PG8_LAS unsigned char* lds, const Gemm g, const Sched S, const Epi E, const int tid) {
;     ...
;         for (int t = 0; t < nt; t += 2) {
;             const bool last = (t == nt - 2);
;             const char* a1 = cA + (size_t)(t + 1) * kstep;
;             const char* a2 = last ? nA : cA + (size_t)(t + 2) * kstep; const char* b2 = last ? nB : cB + (size_t)(t + 2) * kstep;
;             const char* a3 = a2 + kstep; const char* b3 = b2 + kstep;
;     ...
;             PG8_LDB(B0, 1, 0); PG8_LDB(B1, 1, 1); PG8_SCHED; PG8_LDA(At, 1, 0); PG8_STAGE(PG8_SA(0, 1), a2 + hstepA, voffA);
;             PG8_WAIT_V(8); PG8_WAIT_L(0); PG8_BAR; PG8_MMA(0, 0, At, B0); PG8_MMA(0, 1, At, B1); PG8_BAR; PG8_SCHED;
;             PG8_LDA(At, 1, 1); PG8_STAGE(PG8_SB(1, 0), b3, voffB); PG8_STAGE(PG8_SB(1, 1), b3 + hstepB, voffB); PG8_STAGE(PG8_SA(1, 0), a3, voffA);
;             PG8_WAIT_V(8); PG8_WAIT_L(0); PG8_BAR; PG8_MMA(1, 0, At, B0); PG8_MMA(1, 1, At, B1); PG8_BAR; PG8_SCHED;
	s_add_i32 s74, 0, 0x18000
	s_add_i32 s75, 0, 0x1c000
	v_add_u32_e32 v162, s74, v149
	v_add_u32_e32 v178, s75, v149
	ds_read_b128 v[144:147], v162
	ds_read_b128 v[154:157], v162 offset:1024
	ds_read_b128 v[158:161], v162 offset:2048
	ds_read_b128 v[162:165], v162 offset:3072
	ds_read_b128 v[166:169], v178
	ds_read_b128 v[170:173], v178 offset:1024
	ds_read_b128 v[174:177], v178 offset:2048
	ds_read_b128 v[178:181], v178 offset:3072
	s_add_u32 s30, s38, 0xb0000
	s_addc_u32 s31, s39, 0
	s_mov_b32 m0, s56
	ds_read_b128 v[182:185], v153 offset:32768
	ds_read_b128 v[188:191], v153 offset:33792
	ds_read_b128 v[192:195], v153 offset:34816
	ds_read_b128 v[196:199], v153 offset:35840
	ds_read_b128 v[200:203], v153 offset:36864
	ds_read_b128 v[204:207], v153 offset:37888
	ds_read_b128 v[208:211], v153 offset:38912
	ds_read_b128 v[212:215], v153 offset:39936
	global_load_lds_dwordx4 v128, s[30:31]
	s_mov_b32 m0, s57
	s_nop 0
	global_load_lds_dwordx4 v132, s[30:31]
	s_waitcnt vmcnt(8)
	s_waitcnt lgkmcnt(0)
	s_barrier
	s_waitcnt lgkmcnt(0)
	v_mfma_f32_16x16x32_bf16 v[112:115], v[144:147], v[182:185], v[112:115]
	v_mfma_f32_16x16x32_bf16 v[120:123], v[158:161], v[182:185], v[120:123]
	v_mfma_f32_16x16x32_bf16 v[96:99], v[144:147], v[192:195], v[96:99]
	v_mfma_f32_16x16x32_bf16 v[104:107], v[158:161], v[192:195], v[104:107]
	v_mfma_f32_16x16x32_bf16 v[80:83], v[144:147], v[200:203], v[80:83]
	v_mfma_f32_16x16x32_bf16 v[88:91], v[158:161], v[200:203], v[88:91]
	v_mfma_f32_16x16x32_bf16 v[64:67], v[144:147], v[208:211], v[64:67]
	v_mfma_f32_16x16x32_bf16 v[72:75], v[158:161], v[208:211], v[72:75]
	v_mfma_f32_16x16x32_bf16 v[112:115], v[154:157], v[188:191], v[112:115]
	v_mfma_f32_16x16x32_bf16 v[120:123], v[162:165], v[188:191], v[120:123]
	v_mfma_f32_16x16x32_bf16 v[96:99], v[154:157], v[196:199], v[96:99]
	v_mfma_f32_16x16x32_bf16 v[104:107], v[162:165], v[196:199], v[104:107]
	v_mfma_f32_16x16x32_bf16 v[80:83], v[154:157], v[204:207], v[80:83]
	v_mfma_f32_16x16x32_bf16 v[88:91], v[162:165], v[204:207], v[88:91]
	v_mfma_f32_16x16x32_bf16 v[64:67], v[154:157], v[212:215], v[64:67]
	v_mfma_f32_16x16x32_bf16 v[72:75], v[162:165], v[212:215], v[72:75]
	v_mfma_f32_16x16x32_bf16 v[116:119], v[166:169], v[182:185], v[116:119]
	v_mfma_f32_16x16x32_bf16 v[124:127], v[174:177], v[182:185], v[124:127]
	v_mfma_f32_16x16x32_bf16 v[100:103], v[166:169], v[192:195], v[100:103]
	v_mfma_f32_16x16x32_bf16 v[108:111], v[174:177], v[192:195], v[108:111]
	v_mfma_f32_16x16x32_bf16 v[84:87], v[166:169], v[200:203], v[84:87]
	v_mfma_f32_16x16x32_bf16 v[92:95], v[174:177], v[200:203], v[92:95]
	v_mfma_f32_16x16x32_bf16 v[68:71], v[166:169], v[208:211], v[68:71]
	v_mfma_f32_16x16x32_bf16 v[76:79], v[174:177], v[208:211], v[76:79]
	v_mfma_f32_16x16x32_bf16 v[116:119], v[170:173], v[188:191], v[116:119]
	v_mfma_f32_16x16x32_bf16 v[124:127], v[178:181], v[188:191], v[124:127]
	v_mfma_f32_16x16x32_bf16 v[100:103], v[170:173], v[196:199], v[100:103]
	v_mfma_f32_16x16x32_bf16 v[108:111], v[178:181], v[196:199], v[108:111]
	v_mfma_f32_16x16x32_bf16 v[84:87], v[170:173], v[204:207], v[84:87]
	v_mfma_f32_16x16x32_bf16 v[92:95], v[178:181], v[204:207], v[92:95]
	v_mfma_f32_16x16x32_bf16 v[68:71], v[170:173], v[212:215], v[68:71]
	v_mfma_f32_16x16x32_bf16 v[76:79], v[178:181], v[212:215], v[76:79]
	s_barrier
	s_add_i32 s30, s74, s51
	s_mov_b32 m0, s30
	ds_read_b128 v[182:185], v153 offset:49152
	ds_read_b128 v[188:191], v153 offset:50176
	ds_read_b128 v[192:195], v153 offset:51200
	ds_read_b128 v[196:199], v153 offset:52224
	ds_read_b128 v[200:203], v153 offset:53248
	ds_read_b128 v[204:207], v153 offset:54272
	ds_read_b128 v[208:211], v153 offset:55296
	ds_read_b128 v[212:215], v153 offset:56320
	global_load_lds_dwordx4 v130, s[98:99]
	s_add_i32 m0, s30, 0x2000
	s_add_u32 s30, s36, 0xb0080
	s_addc_u32 s31, s37, 0
	s_add_i32 s36, s75, s51
	global_load_lds_dwordx4 v134, s[98:99]
	s_mov_b32 m0, s36
	s_nop 0
	global_load_lds_dwordx4 v130, s[30:31]
	s_add_i32 m0, s36, 0x2000
	s_nop 0
	global_load_lds_dwordx4 v134, s[30:31]
	s_mov_b32 m0, s59
	s_nop 0
	global_load_lds_dwordx4 v128, s[100:101]
	s_mov_b32 m0, s60
	s_nop 0
	global_load_lds_dwordx4 v132, s[100:101]
	s_waitcnt vmcnt(8)
	s_waitcnt lgkmcnt(0)
	s_barrier
	s_waitcnt lgkmcnt(0)
	v_mfma_f32_16x16x32_bf16 v[48:51], v[144:147], v[182:185], v[48:51]
	v_mfma_f32_16x16x32_bf16 v[56:59], v[158:161], v[182:185], v[56:59]
	v_mfma_f32_16x16x32_bf16 v[24:27], v[144:147], v[192:195], v[24:27]
	v_mfma_f32_16x16x32_bf16 v[32:35], v[158:161], v[192:195], v[32:35]
	v_mfma_f32_16x16x32_bf16 v[0:3], v[144:147], v[200:203], v[0:3]
	v_mfma_f32_16x16x32_bf16 v[4:7], v[158:161], v[200:203], v[4:7]
	v_mfma_f32_16x16x32_bf16 v[8:11], v[144:147], v[208:211], v[8:11]
	v_mfma_f32_16x16x32_bf16 v[16:19], v[158:161], v[208:211], v[16:19]
	v_mfma_f32_16x16x32_bf16 v[48:51], v[154:157], v[188:191], v[48:51]
	v_mfma_f32_16x16x32_bf16 v[56:59], v[162:165], v[188:191], v[56:59]
	v_mfma_f32_16x16x32_bf16 v[24:27], v[154:157], v[196:199], v[24:27]
	v_mfma_f32_16x16x32_bf16 v[32:35], v[162:165], v[196:199], v[32:35]
	v_mfma_f32_16x16x32_bf16 v[0:3], v[154:157], v[204:207], v[0:3]
	v_mfma_f32_16x16x32_bf16 v[4:7], v[162:165], v[204:207], v[4:7]
	v_mfma_f32_16x16x32_bf16 v[8:11], v[154:157], v[212:215], v[8:11]
	v_mfma_f32_16x16x32_bf16 v[16:19], v[162:165], v[212:215], v[16:19]
	v_mfma_f32_16x16x32_bf16 v[52:55], v[166:169], v[182:185], v[52:55]
	v_mfma_f32_16x16x32_bf16 v[60:63], v[174:177], v[182:185], v[60:63]
	v_mfma_f32_16x16x32_bf16 v[28:31], v[166:169], v[192:195], v[28:31]
	v_mfma_f32_16x16x32_bf16 v[36:39], v[174:177], v[192:195], v[36:39]
	v_mfma_f32_16x16x32_bf16 v[40:43], v[166:169], v[200:203], v[40:43]
	v_mfma_f32_16x16x32_bf16 v[44:47], v[174:177], v[200:203], v[44:47]
	v_mfma_f32_16x16x32_bf16 v[12:15], v[166:169], v[208:211], v[12:15]
	v_mfma_f32_16x16x32_bf16 v[20:23], v[174:177], v[208:211], v[20:23]
	v_mfma_f32_16x16x32_bf16 v[52:55], v[170:173], v[188:191], v[52:55]
	v_mfma_f32_16x16x32_bf16 v[60:63], v[178:181], v[188:191], v[60:63]
	v_mfma_f32_16x16x32_bf16 v[28:31], v[170:173], v[196:199], v[28:31]
	v_mfma_f32_16x16x32_bf16 v[36:39], v[178:181], v[196:199], v[36:39]
	v_mfma_f32_16x16x32_bf16 v[40:43], v[170:173], v[204:207], v[40:43]
	v_mfma_f32_16x16x32_bf16 v[44:47], v[178:181], v[204:207], v[44:47]
	v_mfma_f32_16x16x32_bf16 v[12:15], v[170:173], v[212:215], v[12:15]
	v_mfma_f32_16x16x32_bf16 v[20:23], v[178:181], v[212:215], v[20:23]
	s_barrier
	s_add_i32 s73, s73, 2
	s_add_u32 s71, s71, 0x100
	s_addc_u32 s72, s72, 0
	s_cmp_gt_u32 s73, 41
	s_mov_b64 s[30:31], s[34:35]
	s_cbranch_scc0 .LBB0_297
	s_and_b64 vcc, exec, s[24:25]
	s_cbranch_vccz .LBB0_300
	s_barrier

; #define PG8_STAGE(bufoff, gbase, voff) do { _Pragma("unroll") for (int _i = 0; _i < 2; ++_i) \
;         __builtin_amdgcn_global_load_lds((const unsigned*)((const char*)(gbase) + (voff)[_i]), (PG8_LAS unsigned*)(lds + (bufoff) + ldsw + _i * 8192), 16, 0, 0); } while (0)
; #define PG8_LDA(dst, b, h) do { _Pragma("unroll") for (int m = 0; m < 4; ++m) _Pragma("unroll") for (int k = 0; k < 2; ++k) dst[m][k] = *(const PG8_LAS bf16x8*)(lds + PG8_SA(b, h) + aoff + m * 2048 + k * 1024); } while (0)
; #define PG8_LDB(dst, b, h) do { _Pragma("unroll") for (int n = 0; n < 2; ++n) _Pragma("unroll") for (int k = 0; k < 2; ++k) dst[n][k] = *(const PG8_LAS bf16x8*)(lds + PG8_SB(b, h) + boff + n * 2048 + k * 1024); } while (0)
; #define PG8_MMA(ai, bj, At, Bt) do { __builtin_amdgcn_s_setprio(1); _Pragma("unroll") for (int m = 0; m < 4; ++m) _Pragma("unroll") for (int n = 0; n < 2; ++n) _Pragma("unroll") for (int k = 0; k < 2; ++k) \
;         acc[ai][bj][m][n] = __builtin_amdgcn_mfma_f32_16x16x32_bf16(Bt[n][k], At[m][k], acc[ai][bj][m][n], 0, 0, 0); __builtin_amdgcn_s_setprio(0); } while (0)
; #define PG8_WAIT_V(n) asm volatile("s_waitcnt vmcnt(" #n ")" ::: "memory")
; #define PG8_WAIT_L(n) asm volatile("s_waitcnt lgkmcnt(" #n ")" ::: "memory")
; #define PG8_BAR __builtin_amdgcn_s_barrier()
; #define PG8_SCHED __builtin_amdgcn_sched_barrier(0)
; template <class Epi, class Sched, bool ALIGN_EPI = false, bool SP2 = false>
; __device__ __forceinline__ void gemm_phase(PG8_LAS unsigned char* lds, const Gemm g, const Sched S, const Epi E, const int tid) {
;     ...
;             PG8_LDB(B0, 0, 0); PG8_LDB(B1, 0, 1); PG8_SCHED; PG8_LDA(At, 0, 0); PG8_STAGE(PG8_SA(1, 1), a1 + hstepA, voffA);
;             PG8_WAIT_V(8); PG8_WAIT_L(0); PG8_BAR; PG8_MMA(0, 0, At, B0); PG8_MMA(0, 1, At, B1); PG8_BAR; PG8_SCHED;
;             PG8_LDA(At, 0, 1); PG8_STAGE(PG8_SB(0, 0), b2, voffB); PG8_STAGE(PG8_SB(0, 1), b2 + hstepB, voffB); PG8_STAGE(PG8_SA(0, 0), a2, voffA);
;             PG8_WAIT_V(8); PG8_WAIT_L(0); PG8_BAR; PG8_MMA(1, 0, At, B0); PG8_MMA(1, 1, At, B1); PG8_BAR; PG8_SCHED;
.LBB0_402:
	ds_read_b128 v[146:149], v169
	ds_read_b128 v[150:153], v169 offset:1024
	ds_read_b128 v[154:157], v169 offset:2048
	ds_read_b128 v[174:177], v169 offset:3072
	ds_read_b128 v[178:181], v170
	ds_read_b128 v[182:185], v170 offset:1024
	ds_read_b128 v[188:191], v170 offset:2048
	ds_read_b128 v[192:195], v170 offset:3072
	s_add_u32 s34, s30, 0xfffc0080
	s_addc_u32 s35, s31, -1
	s_cmp_eq_u32 s74, 12
	s_cselect_b32 s37, s25, s35
	s_cselect_b32 s36, s70, s34
	s_cselect_b32 s35, s23, s73
	s_cselect_b32 s34, s71, s72
	s_add_i32 m0, s52, 0xc000
	ds_read_b128 v[196:199], v171
	ds_read_b128 v[200:203], v171 offset:1024
	ds_read_b128 v[204:207], v171 offset:2048
	ds_read_b128 v[208:211], v171 offset:3072
	ds_read_b128 v[212:215], v171 offset:4096
	ds_read_b128 v[216:219], v171 offset:5120
	ds_read_b128 v[220:223], v171 offset:6144
	ds_read_b128 v[224:227], v171 offset:7168
	global_load_lds_dwordx4 v138, s[30:31]
	s_add_i32 m0, s52, 0xe000
	s_nop 0
	global_load_lds_dwordx4 v140, s[30:31]
	s_waitcnt vmcnt(8)
	s_waitcnt lgkmcnt(0)
	s_barrier
	s_waitcnt lgkmcnt(0)
	v_mfma_f32_16x16x32_bf16 v[124:127], v[146:149], v[196:199], v[124:127]
	v_mfma_f32_16x16x32_bf16 v[120:123], v[154:157], v[196:199], v[120:123]
	v_mfma_f32_16x16x32_bf16 v[116:119], v[146:149], v[204:207], v[116:119]
	v_mfma_f32_16x16x32_bf16 v[112:115], v[154:157], v[204:207], v[112:115]
	v_mfma_f32_16x16x32_bf16 v[108:111], v[146:149], v[212:215], v[108:111]
	v_mfma_f32_16x16x32_bf16 v[104:107], v[154:157], v[212:215], v[104:107]
	v_mfma_f32_16x16x32_bf16 v[100:103], v[146:149], v[220:223], v[100:103]
	v_mfma_f32_16x16x32_bf16 v[96:99], v[154:157], v[220:223], v[96:99]
	v_mfma_f32_16x16x32_bf16 v[124:127], v[150:153], v[200:203], v[124:127]
	v_mfma_f32_16x16x32_bf16 v[120:123], v[174:177], v[200:203], v[120:123]
	v_mfma_f32_16x16x32_bf16 v[116:119], v[150:153], v[208:211], v[116:119]
	v_mfma_f32_16x16x32_bf16 v[112:115], v[174:177], v[208:211], v[112:115]
	v_mfma_f32_16x16x32_bf16 v[108:111], v[150:153], v[216:219], v[108:111]
	v_mfma_f32_16x16x32_bf16 v[104:107], v[174:177], v[216:219], v[104:107]
	v_mfma_f32_16x16x32_bf16 v[100:103], v[150:153], v[224:227], v[100:103]
	v_mfma_f32_16x16x32_bf16 v[96:99], v[174:177], v[224:227], v[96:99]
	v_mfma_f32_16x16x32_bf16 v[60:63], v[178:181], v[196:199], v[60:63]
	v_mfma_f32_16x16x32_bf16 v[56:59], v[188:191], v[196:199], v[56:59]
	v_mfma_f32_16x16x32_bf16 v[52:55], v[178:181], v[204:207], v[52:55]
	v_mfma_f32_16x16x32_bf16 v[48:51], v[188:191], v[204:207], v[48:51]
	v_mfma_f32_16x16x32_bf16 v[44:47], v[178:181], v[212:215], v[44:47]
	v_mfma_f32_16x16x32_bf16 v[40:43], v[188:191], v[212:215], v[40:43]
	v_mfma_f32_16x16x32_bf16 v[36:39], v[178:181], v[220:223], v[36:39]
	v_mfma_f32_16x16x32_bf16 v[32:35], v[188:191], v[220:223], v[32:35]
	v_mfma_f32_16x16x32_bf16 v[60:63], v[182:185], v[200:203], v[60:63]
	v_mfma_f32_16x16x32_bf16 v[56:59], v[192:195], v[200:203], v[56:59]
	v_mfma_f32_16x16x32_bf16 v[52:55], v[182:185], v[208:211], v[52:55]
	v_mfma_f32_16x16x32_bf16 v[48:51], v[192:195], v[208:211], v[48:51]
	v_mfma_f32_16x16x32_bf16 v[44:47], v[182:185], v[216:219], v[44:47]
	v_mfma_f32_16x16x32_bf16 v[40:43], v[192:195], v[216:219], v[40:43]
	v_mfma_f32_16x16x32_bf16 v[36:39], v[182:185], v[224:227], v[36:39]
	v_mfma_f32_16x16x32_bf16 v[32:35], v[192:195], v[224:227], v[32:35]
	s_barrier
	s_add_u32 s98, s34, 0x80
	s_addc_u32 s99, s35, 0
	s_add_u32 s100, s36, 0x80
	s_addc_u32 s101, s37, 0
	s_add_i32 s75, s63, s33
	s_mov_b32 m0, s75
	ds_read_b128 v[196:199], v171 offset:16384
	ds_read_b128 v[200:203], v171 offset:17408
	ds_read_b128 v[204:207], v171 offset:18432
	ds_read_b128 v[208:211], v171 offset:19456
	ds_read_b128 v[212:215], v171 offset:20480
	ds_read_b128 v[216:219], v171 offset:21504
	ds_read_b128 v[220:223], v171 offset:22528
	ds_read_b128 v[224:227], v171 offset:23552
	global_load_lds_dwordx4 v134, s[34:35]
	s_add_i32 m0, s75, 0x2000
	s_add_u32 s76, s34, 0x40000
	s_addc_u32 s77, s35, 0
	s_add_i32 s75, s64, s33
	global_load_lds_dwordx4 v130, s[34:35]
	s_mov_b32 m0, s75
	s_nop 0
	global_load_lds_dwordx4 v134, s[76:77]
	s_add_i32 m0, s75, 0x2000
	s_nop 0
	global_load_lds_dwordx4 v130, s[76:77]
	s_mov_b32 m0, s52
	s_nop 0
	global_load_lds_dwordx4 v136, s[36:37]
	s_mov_b32 m0, s54
	s_nop 0
	global_load_lds_dwordx4 v132, s[36:37]
	s_waitcnt vmcnt(8)
	s_waitcnt lgkmcnt(0)
	s_barrier
	s_waitcnt lgkmcnt(0)
	v_mfma_f32_16x16x32_bf16 v[92:95], v[146:149], v[196:199], v[92:95]
	v_mfma_f32_16x16x32_bf16 v[88:91], v[154:157], v[196:199], v[88:91]
	v_mfma_f32_16x16x32_bf16 v[84:87], v[146:149], v[204:207], v[84:87]
	v_mfma_f32_16x16x32_bf16 v[80:83], v[154:157], v[204:207], v[80:83]
	v_mfma_f32_16x16x32_bf16 v[76:79], v[146:149], v[212:215], v[76:79]
	v_mfma_f32_16x16x32_bf16 v[72:75], v[154:157], v[212:215], v[72:75]
	v_mfma_f32_16x16x32_bf16 v[68:71], v[146:149], v[220:223], v[68:71]
	v_mfma_f32_16x16x32_bf16 v[64:67], v[154:157], v[220:223], v[64:67]
	v_mfma_f32_16x16x32_bf16 v[92:95], v[150:153], v[200:203], v[92:95]
	v_mfma_f32_16x16x32_bf16 v[88:91], v[174:177], v[200:203], v[88:91]
	v_mfma_f32_16x16x32_bf16 v[84:87], v[150:153], v[208:211], v[84:87]
	v_mfma_f32_16x16x32_bf16 v[80:83], v[174:177], v[208:211], v[80:83]
	v_mfma_f32_16x16x32_bf16 v[76:79], v[150:153], v[216:219], v[76:79]
	v_mfma_f32_16x16x32_bf16 v[72:75], v[174:177], v[216:219], v[72:75]
	v_mfma_f32_16x16x32_bf16 v[68:71], v[150:153], v[224:227], v[68:71]
	v_mfma_f32_16x16x32_bf16 v[64:67], v[174:177], v[224:227], v[64:67]
	v_mfma_f32_16x16x32_bf16 v[28:31], v[178:181], v[196:199], v[28:31]
	v_mfma_f32_16x16x32_bf16 v[24:27], v[188:191], v[196:199], v[24:27]
	v_mfma_f32_16x16x32_bf16 v[20:23], v[178:181], v[204:207], v[20:23]
	v_mfma_f32_16x16x32_bf16 v[16:19], v[188:191], v[204:207], v[16:19]
	v_mfma_f32_16x16x32_bf16 v[12:15], v[178:181], v[212:215], v[12:15]
	v_mfma_f32_16x16x32_bf16 v[8:11], v[188:191], v[212:215], v[8:11]
	v_mfma_f32_16x16x32_bf16 v[4:7], v[178:181], v[220:223], v[4:7]
	v_mfma_f32_16x16x32_bf16 v[0:3], v[188:191], v[220:223], v[0:3]
	v_mfma_f32_16x16x32_bf16 v[28:31], v[182:185], v[200:203], v[28:31]
	v_mfma_f32_16x16x32_bf16 v[24:27], v[192:195], v[200:203], v[24:27]
	v_mfma_f32_16x16x32_bf16 v[20:23], v[182:185], v[208:211], v[20:23]
	v_mfma_f32_16x16x32_bf16 v[16:19], v[192:195], v[208:211], v[16:19]
	v_mfma_f32_16x16x32_bf16 v[12:15], v[182:185], v[216:219], v[12:15]
	v_mfma_f32_16x16x32_bf16 v[8:11], v[192:195], v[216:219], v[8:11]
	v_mfma_f32_16x16x32_bf16 v[4:7], v[182:185], v[224:227], v[4:7]
	v_mfma_f32_16x16x32_bf16 v[0:3], v[192:195], v[224:227], v[0:3]
	s_barrier
; #define PG8_STAGE(bufoff, gbase, voff) do { _Pragma("unroll") for (int _i = 0; _i < 2; ++_i) \
;         __builtin_amdgcn_global_load_lds((const unsigned*)((const char*)(gbase) + (voff)[_i]), (PG8_LAS unsigned*)(lds + (bufoff) + ldsw + _i * 8192), 16, 0, 0); } while (0)
; #define PG8_LDA(dst, b, h) do { _Pragma("unroll") for (int m = 0; m < 4; ++m) _Pragma("unroll") for (int k = 0; k < 2; ++k) dst[m][k] = *(const PG8_LAS bf16x8*)(lds + PG8_SA(b, h) + aoff + m * 2048 + k * 1024); } while (0)
; #define PG8_LDB(dst, b, h) do { _Pragma("unroll") for (int n = 0; n < 2; ++n) _Pragma("unroll") for (int k = 0; k < 2; ++k) dst[n][k] = *(const PG8_LAS bf16x8*)(lds + PG8_SB(b, h) + boff + n * 2048 + k * 1024); } while (0)
; #define PG8_MMA(ai, bj, At, Bt) do { __builtin_amdgcn_s_setprio(1); _Pragma("unroll") for (int m = 0; m < 4; ++m) _Pragma("unroll") for (int n = 0; n < 2; ++n) _Pragma("unroll") for (int k = 0; k < 2; ++k) \
;         acc[ai][bj][m][n] = __builtin_amdgcn_mfma_f32_16x16x32_bf16(Bt[n][k], At[m][k], acc[ai][bj][m][n], 0, 0, 0); __builtin_amdgcn_s_setprio(0); } while (0)
; #define PG8_WAIT_V(n) asm volatile("s_waitcnt vmcnt(" #n ")" ::: "memory")
; #define PG8_WAIT_L(n) asm volatile("s_waitcnt lgkmcnt(" #n ")" ::: "memory")
; #define PG8_BAR __builtin_amdgcn_s_barrier()
; template <class Epi, class Sched, bool ALIGN_EPI = false, bool SP2 = false>
; __device__ __forceinline__ void gemm_phase(PG8_LAS unsigned char* lds, const Gemm g, const Sched S, const Epi E, const int tid) {
;     ...
;         for (int t = 0; t < nt; t += 2) {
;             const bool last = (t == nt - 2);
;             const char* a1 = cA + (size_t)(t + 1) * kstep;
;             const char* a2 = last ? nA : cA + (size_t)(t + 2) * kstep; const char* b2 = last ? nB : cB + (size_t)(t + 2) * kstep;
;             const char* a3 = a2 + kstep; const char* b3 = b2 + kstep;
;     ...
;             PG8_LDB(B0, 1, 0); PG8_LDB(B1, 1, 1); PG8_SCHED; PG8_LDA(At, 1, 0); PG8_STAGE(PG8_SA(0, 1), a2 + hstepA, voffA);
;             PG8_WAIT_V(8); PG8_WAIT_L(0); PG8_BAR; PG8_MMA(0, 0, At, B0); PG8_MMA(0, 1, At, B1); PG8_BAR; PG8_SCHED;
;             PG8_LDA(At, 1, 1); PG8_STAGE(PG8_SB(1, 0), b3, voffB); PG8_STAGE(PG8_SB(1, 1), b3 + hstepB, voffB); PG8_STAGE(PG8_SA(1, 0), a3, voffA);
;             PG8_WAIT_V(8); PG8_WAIT_L(0); PG8_BAR; PG8_MMA(1, 0, At, B0); PG8_MMA(1, 1, At, B1); PG8_BAR; PG8_SCHED;
	s_add_i32 s75, 0, 0x18000
	v_add_u32_e32 v173, s75, v160
	s_add_i32 s76, 0, 0x1c000
	ds_read_b128 v[146:149], v173
	ds_read_b128 v[150:153], v173 offset:1024
	ds_read_b128 v[154:157], v173 offset:2048
	ds_read_b128 v[174:177], v173 offset:3072
	v_add_u32_e32 v173, s76, v160
	ds_read_b128 v[178:181], v173
	ds_read_b128 v[182:185], v173 offset:1024
	ds_read_b128 v[188:191], v173 offset:2048
	ds_read_b128 v[192:195], v173 offset:3072
	s_add_u32 s36, s36, 0x40000
	s_addc_u32 s37, s37, 0
	s_mov_b32 m0, s55
	ds_read_b128 v[196:199], v171 offset:32768
	ds_read_b128 v[200:203], v171 offset:33792
	ds_read_b128 v[204:207], v171 offset:34816
	ds_read_b128 v[208:211], v171 offset:35840
	ds_read_b128 v[212:215], v171 offset:36864
	ds_read_b128 v[216:219], v171 offset:37888
	ds_read_b128 v[220:223], v171 offset:38912
	ds_read_b128 v[224:227], v171 offset:39936
	global_load_lds_dwordx4 v136, s[36:37]
	s_mov_b32 m0, s57
	s_nop 0
	global_load_lds_dwordx4 v132, s[36:37]
	s_waitcnt vmcnt(8)
	s_waitcnt lgkmcnt(0)
	s_barrier
	s_waitcnt lgkmcnt(0)
	v_mfma_f32_16x16x32_bf16 v[124:127], v[146:149], v[196:199], v[124:127]
	v_mfma_f32_16x16x32_bf16 v[120:123], v[154:157], v[196:199], v[120:123]
	v_mfma_f32_16x16x32_bf16 v[116:119], v[146:149], v[204:207], v[116:119]
	v_mfma_f32_16x16x32_bf16 v[112:115], v[154:157], v[204:207], v[112:115]
	v_mfma_f32_16x16x32_bf16 v[108:111], v[146:149], v[212:215], v[108:111]
	v_mfma_f32_16x16x32_bf16 v[104:107], v[154:157], v[212:215], v[104:107]
	v_mfma_f32_16x16x32_bf16 v[100:103], v[146:149], v[220:223], v[100:103]
	v_mfma_f32_16x16x32_bf16 v[96:99], v[154:157], v[220:223], v[96:99]
	v_mfma_f32_16x16x32_bf16 v[124:127], v[150:153], v[200:203], v[124:127]
	v_mfma_f32_16x16x32_bf16 v[120:123], v[174:177], v[200:203], v[120:123]
	v_mfma_f32_16x16x32_bf16 v[116:119], v[150:153], v[208:211], v[116:119]
	v_mfma_f32_16x16x32_bf16 v[112:115], v[174:177], v[208:211], v[112:115]
	v_mfma_f32_16x16x32_bf16 v[108:111], v[150:153], v[216:219], v[108:111]
	v_mfma_f32_16x16x32_bf16 v[104:107], v[174:177], v[216:219], v[104:107]
	v_mfma_f32_16x16x32_bf16 v[100:103], v[150:153], v[224:227], v[100:103]
	v_mfma_f32_16x16x32_bf16 v[96:99], v[174:177], v[224:227], v[96:99]
	v_mfma_f32_16x16x32_bf16 v[60:63], v[178:181], v[196:199], v[60:63]
	v_mfma_f32_16x16x32_bf16 v[56:59], v[188:191], v[196:199], v[56:59]
	v_mfma_f32_16x16x32_bf16 v[52:55], v[178:181], v[204:207], v[52:55]
	v_mfma_f32_16x16x32_bf16 v[48:51], v[188:191], v[204:207], v[48:51]
	v_mfma_f32_16x16x32_bf16 v[44:47], v[178:181], v[212:215], v[44:47]
	v_mfma_f32_16x16x32_bf16 v[40:43], v[188:191], v[212:215], v[40:43]
	v_mfma_f32_16x16x32_bf16 v[36:39], v[178:181], v[220:223], v[36:39]
	v_mfma_f32_16x16x32_bf16 v[32:35], v[188:191], v[220:223], v[32:35]
	v_mfma_f32_16x16x32_bf16 v[60:63], v[182:185], v[200:203], v[60:63]
	v_mfma_f32_16x16x32_bf16 v[56:59], v[192:195], v[200:203], v[56:59]
	v_mfma_f32_16x16x32_bf16 v[52:55], v[182:185], v[208:211], v[52:55]
	v_mfma_f32_16x16x32_bf16 v[48:51], v[192:195], v[208:211], v[48:51]
	v_mfma_f32_16x16x32_bf16 v[44:47], v[182:185], v[216:219], v[44:47]
	v_mfma_f32_16x16x32_bf16 v[40:43], v[192:195], v[216:219], v[40:43]
	v_mfma_f32_16x16x32_bf16 v[36:39], v[182:185], v[224:227], v[36:39]
	v_mfma_f32_16x16x32_bf16 v[32:35], v[192:195], v[224:227], v[32:35]
	s_barrier
	s_add_i32 s36, s75, s33
	s_mov_b32 m0, s36
	ds_read_b128 v[196:199], v171 offset:49152
	ds_read_b128 v[200:203], v171 offset:50176
	ds_read_b128 v[204:207], v171 offset:51200
	ds_read_b128 v[208:211], v171 offset:52224
	ds_read_b128 v[212:215], v171 offset:53248
	ds_read_b128 v[216:219], v171 offset:54272
	ds_read_b128 v[220:223], v171 offset:55296
	ds_read_b128 v[224:227], v171 offset:56320
	global_load_lds_dwordx4 v134, s[98:99]
	s_add_i32 m0, s36, 0x2000
	s_add_u32 s34, s34, 0x40080
	s_addc_u32 s35, s35, 0
	s_add_i32 s36, s76, s33
	global_load_lds_dwordx4 v130, s[98:99]
	s_mov_b32 m0, s36
	s_nop 0
	global_load_lds_dwordx4 v134, s[34:35]
	s_add_i32 m0, s36, 0x2000
	s_nop 0
	global_load_lds_dwordx4 v130, s[34:35]
	s_mov_b32 m0, s58
	s_nop 0
	global_load_lds_dwordx4 v136, s[100:101]
	s_mov_b32 m0, s59
	s_nop 0
	global_load_lds_dwordx4 v132, s[100:101]
	s_waitcnt vmcnt(8)
	s_waitcnt lgkmcnt(0)
	s_barrier
	s_waitcnt lgkmcnt(0)
	v_mfma_f32_16x16x32_bf16 v[92:95], v[146:149], v[196:199], v[92:95]
	v_mfma_f32_16x16x32_bf16 v[88:91], v[154:157], v[196:199], v[88:91]
	v_mfma_f32_16x16x32_bf16 v[84:87], v[146:149], v[204:207], v[84:87]
	v_mfma_f32_16x16x32_bf16 v[80:83], v[154:157], v[204:207], v[80:83]
	v_mfma_f32_16x16x32_bf16 v[76:79], v[146:149], v[212:215], v[76:79]
	v_mfma_f32_16x16x32_bf16 v[72:75], v[154:157], v[212:215], v[72:75]
	v_mfma_f32_16x16x32_bf16 v[68:71], v[146:149], v[220:223], v[68:71]
	v_mfma_f32_16x16x32_bf16 v[64:67], v[154:157], v[220:223], v[64:67]
	v_mfma_f32_16x16x32_bf16 v[92:95], v[150:153], v[200:203], v[92:95]
	v_mfma_f32_16x16x32_bf16 v[88:91], v[174:177], v[200:203], v[88:91]
	v_mfma_f32_16x16x32_bf16 v[84:87], v[150:153], v[208:211], v[84:87]
	v_mfma_f32_16x16x32_bf16 v[80:83], v[174:177], v[208:211], v[80:83]
	v_mfma_f32_16x16x32_bf16 v[76:79], v[150:153], v[216:219], v[76:79]
	v_mfma_f32_16x16x32_bf16 v[72:75], v[174:177], v[216:219], v[72:75]
	v_mfma_f32_16x16x32_bf16 v[68:71], v[150:153], v[224:227], v[68:71]
	v_mfma_f32_16x16x32_bf16 v[64:67], v[174:177], v[224:227], v[64:67]
	v_mfma_f32_16x16x32_bf16 v[28:31], v[178:181], v[196:199], v[28:31]
	v_mfma_f32_16x16x32_bf16 v[24:27], v[188:191], v[196:199], v[24:27]
	v_mfma_f32_16x16x32_bf16 v[20:23], v[178:181], v[204:207], v[20:23]
	v_mfma_f32_16x16x32_bf16 v[16:19], v[188:191], v[204:207], v[16:19]
	v_mfma_f32_16x16x32_bf16 v[12:15], v[178:181], v[212:215], v[12:15]
	v_mfma_f32_16x16x32_bf16 v[8:11], v[188:191], v[212:215], v[8:11]
	v_mfma_f32_16x16x32_bf16 v[4:7], v[178:181], v[220:223], v[4:7]
	v_mfma_f32_16x16x32_bf16 v[0:3], v[188:191], v[220:223], v[0:3]
	v_mfma_f32_16x16x32_bf16 v[28:31], v[182:185], v[200:203], v[28:31]
	v_mfma_f32_16x16x32_bf16 v[24:27], v[192:195], v[200:203], v[24:27]
	v_mfma_f32_16x16x32_bf16 v[20:23], v[182:185], v[208:211], v[20:23]
	v_mfma_f32_16x16x32_bf16 v[16:19], v[192:195], v[208:211], v[16:19]
	v_mfma_f32_16x16x32_bf16 v[12:15], v[182:185], v[216:219], v[12:15]
	v_mfma_f32_16x16x32_bf16 v[8:11], v[192:195], v[216:219], v[8:11]
	v_mfma_f32_16x16x32_bf16 v[4:7], v[182:185], v[224:227], v[4:7]
	v_mfma_f32_16x16x32_bf16 v[0:3], v[192:195], v[224:227], v[0:3]
	s_barrier
	s_add_i32 s74, s74, 2
	s_add_u32 s30, s30, 0x100
	s_addc_u32 s31, s31, 0
	s_add_u32 s72, s72, 0x100
	s_addc_u32 s73, s73, 0
	s_cmp_gt_u32 s74, 13
	s_cbranch_scc0 .LBB0_402
	s_and_b64 vcc, exec, s[18:19]
	s_cbranch_vccz .LBB0_405
	s_barrier

; #define PG8_STAGE(bufoff, gbase, voff) do { _Pragma("unroll") for (int _i = 0; _i < 2; ++_i) \
;         __builtin_amdgcn_global_load_lds((const unsigned*)((const char*)(gbase) + (voff)[_i]), (PG8_LAS unsigned*)(lds + (bufoff) + ldsw + _i * 8192), 16, 0, 0); } while (0)
; #define PG8_LDA(dst, b, h) do { _Pragma("unroll") for (int m = 0; m < 4; ++m) _Pragma("unroll") for (int k = 0; k < 2; ++k) dst[m][k] = *(const PG8_LAS bf16x8*)(lds + PG8_SA(b, h) + aoff + m * 2048 + k * 1024); } while (0)
; #define PG8_LDB(dst, b, h) do { _Pragma("unroll") for (int n = 0; n < 2; ++n) _Pragma("unroll") for (int k = 0; k < 2; ++k) dst[n][k] = *(const PG8_LAS bf16x8*)(lds + PG8_SB(b, h) + boff + n * 2048 + k * 1024); } while (0)
; #define PG8_MMA(ai, bj, At, Bt) do { __builtin_amdgcn_s_setprio(1); _Pragma("unroll") for (int m = 0; m < 4; ++m) _Pragma("unroll") for (int n = 0; n < 2; ++n) _Pragma("unroll") for (int k = 0; k < 2; ++k) \
;         acc[ai][bj][m][n] = __builtin_amdgcn_mfma_f32_16x16x32_bf16(Bt[n][k], At[m][k], acc[ai][bj][m][n], 0, 0, 0); __builtin_amdgcn_s_setprio(0); } while (0)
; #define PG8_WAIT_V(n) asm volatile("s_waitcnt vmcnt(" #n ")" ::: "memory")
; #define PG8_WAIT_L(n) asm volatile("s_waitcnt lgkmcnt(" #n ")" ::: "memory")
; #define PG8_BAR __builtin_amdgcn_s_barrier()
; #define PG8_SCHED __builtin_amdgcn_sched_barrier(0)
; template <class Epi, class Sched, bool ALIGN_EPI = false, bool SP2 = false>
; __device__ __forceinline__ void gemm_phase(PG8_LAS unsigned char* lds, const Gemm g, const Sched S, const Epi E, const int tid) {
;     ...
;             PG8_LDB(B0, 0, 0); PG8_LDB(B1, 0, 1); PG8_SCHED; PG8_LDA(At, 0, 0); PG8_STAGE(PG8_SA(1, 1), a1 + hstepA, voffA);
;             PG8_WAIT_V(8); PG8_WAIT_L(0); PG8_BAR; PG8_MMA(0, 0, At, B0); PG8_MMA(0, 1, At, B1); PG8_BAR; PG8_SCHED;
;             PG8_LDA(At, 0, 1); PG8_STAGE(PG8_SB(0, 0), b2, voffB); PG8_STAGE(PG8_SB(0, 1), b2 + hstepB, voffB); PG8_STAGE(PG8_SA(0, 0), a2, voffA);
;             PG8_WAIT_V(8); PG8_WAIT_L(0); PG8_BAR; PG8_MMA(1, 0, At, B0); PG8_MMA(1, 1, At, B1); PG8_BAR; PG8_SCHED;
.LBB0_672:
	v_add_u32_e32 v162, s69, v149
	v_add_u32_e32 v178, s70, v149
	ds_read_b128 v[144:147], v162
	ds_read_b128 v[154:157], v162 offset:1024
	ds_read_b128 v[158:161], v162 offset:2048
	ds_read_b128 v[162:165], v162 offset:3072
	ds_read_b128 v[166:169], v178
	ds_read_b128 v[170:173], v178 offset:1024
	ds_read_b128 v[174:177], v178 offset:2048
	ds_read_b128 v[178:181], v178 offset:3072
	s_add_u32 s6, s38, 0x100
	s_addc_u32 s7, s39, 0
	s_cmp_eq_u32 s75, 12
	s_cselect_b32 s47, s31, s7
	s_cselect_b32 s46, s30, s6
	s_cselect_b32 s41, s29, s74
	s_cselect_b32 s40, s37, s73
	s_add_i32 m0, s58, 0xc000
	ds_read_b128 v[182:185], v153
	ds_read_b128 v[188:191], v153 offset:1024
	ds_read_b128 v[192:195], v153 offset:2048
	ds_read_b128 v[196:199], v153 offset:3072
	ds_read_b128 v[200:203], v153 offset:4096
	ds_read_b128 v[204:207], v153 offset:5120
	ds_read_b128 v[208:211], v153 offset:6144
	ds_read_b128 v[212:215], v153 offset:7168
	global_load_lds_dwordx4 v136, s[38:39]
	s_add_i32 m0, s58, 0xe000
	s_nop 0
	global_load_lds_dwordx4 v138, s[38:39]
	s_waitcnt vmcnt(8)
	s_waitcnt lgkmcnt(0)
	s_barrier
	s_waitcnt lgkmcnt(0)
	v_mfma_f32_16x16x32_bf16 v[112:115], v[144:147], v[182:185], v[112:115]
	v_mfma_f32_16x16x32_bf16 v[120:123], v[158:161], v[182:185], v[120:123]
	v_mfma_f32_16x16x32_bf16 v[96:99], v[144:147], v[192:195], v[96:99]
	v_mfma_f32_16x16x32_bf16 v[104:107], v[158:161], v[192:195], v[104:107]
	v_mfma_f32_16x16x32_bf16 v[80:83], v[144:147], v[200:203], v[80:83]
	v_mfma_f32_16x16x32_bf16 v[88:91], v[158:161], v[200:203], v[88:91]
	v_mfma_f32_16x16x32_bf16 v[64:67], v[144:147], v[208:211], v[64:67]
	v_mfma_f32_16x16x32_bf16 v[72:75], v[158:161], v[208:211], v[72:75]
	v_mfma_f32_16x16x32_bf16 v[112:115], v[154:157], v[188:191], v[112:115]
	v_mfma_f32_16x16x32_bf16 v[120:123], v[162:165], v[188:191], v[120:123]
	v_mfma_f32_16x16x32_bf16 v[96:99], v[154:157], v[196:199], v[96:99]
	v_mfma_f32_16x16x32_bf16 v[104:107], v[162:165], v[196:199], v[104:107]
	v_mfma_f32_16x16x32_bf16 v[80:83], v[154:157], v[204:207], v[80:83]
	v_mfma_f32_16x16x32_bf16 v[88:91], v[162:165], v[204:207], v[88:91]
	v_mfma_f32_16x16x32_bf16 v[64:67], v[154:157], v[212:215], v[64:67]
	v_mfma_f32_16x16x32_bf16 v[72:75], v[162:165], v[212:215], v[72:75]
	v_mfma_f32_16x16x32_bf16 v[116:119], v[166:169], v[182:185], v[116:119]
	v_mfma_f32_16x16x32_bf16 v[124:127], v[174:177], v[182:185], v[124:127]
	v_mfma_f32_16x16x32_bf16 v[100:103], v[166:169], v[192:195], v[100:103]
	v_mfma_f32_16x16x32_bf16 v[108:111], v[174:177], v[192:195], v[108:111]
	v_mfma_f32_16x16x32_bf16 v[84:87], v[166:169], v[200:203], v[84:87]
	v_mfma_f32_16x16x32_bf16 v[92:95], v[174:177], v[200:203], v[92:95]
	v_mfma_f32_16x16x32_bf16 v[68:71], v[166:169], v[208:211], v[68:71]
	v_mfma_f32_16x16x32_bf16 v[76:79], v[174:177], v[208:211], v[76:79]
	v_mfma_f32_16x16x32_bf16 v[116:119], v[170:173], v[188:191], v[116:119]
	v_mfma_f32_16x16x32_bf16 v[124:127], v[178:181], v[188:191], v[124:127]
	v_mfma_f32_16x16x32_bf16 v[100:103], v[170:173], v[196:199], v[100:103]
	v_mfma_f32_16x16x32_bf16 v[108:111], v[178:181], v[196:199], v[108:111]
	v_mfma_f32_16x16x32_bf16 v[84:87], v[170:173], v[204:207], v[84:87]
	v_mfma_f32_16x16x32_bf16 v[92:95], v[178:181], v[204:207], v[92:95]
	v_mfma_f32_16x16x32_bf16 v[68:71], v[170:173], v[212:215], v[68:71]
	v_mfma_f32_16x16x32_bf16 v[76:79], v[178:181], v[212:215], v[76:79]
	s_barrier
	s_add_u32 s98, s40, 0x80
	s_addc_u32 s99, s41, 0
	s_add_u32 s100, s46, 0x80
	s_addc_u32 s101, s47, 0
	s_add_i32 s38, s69, s33
	s_mov_b32 m0, s38
	ds_read_b128 v[182:185], v153 offset:16384
	ds_read_b128 v[188:191], v153 offset:17408
	ds_read_b128 v[192:195], v153 offset:18432
	ds_read_b128 v[196:199], v153 offset:19456
	ds_read_b128 v[200:203], v153 offset:20480
	ds_read_b128 v[204:207], v153 offset:21504
	ds_read_b128 v[208:211], v153 offset:22528
	ds_read_b128 v[212:215], v153 offset:23552
	global_load_lds_dwordx4 v130, s[40:41]
	s_add_i32 m0, s38, 0x2000
	s_add_u32 s38, s40, 0x40000
	s_addc_u32 s39, s41, 0
	s_add_i32 s76, s70, s33
	global_load_lds_dwordx4 v134, s[40:41]
	s_mov_b32 m0, s76
	s_nop 0
	global_load_lds_dwordx4 v130, s[38:39]
	s_add_i32 m0, s76, 0x2000
	s_nop 0
	global_load_lds_dwordx4 v134, s[38:39]
	s_mov_b32 m0, s58
	s_nop 0
	global_load_lds_dwordx4 v128, s[46:47]
	s_mov_b32 m0, s59
	s_nop 0
	global_load_lds_dwordx4 v132, s[46:47]
	s_waitcnt vmcnt(8)
	s_waitcnt lgkmcnt(0)
	s_barrier
	s_waitcnt lgkmcnt(0)
	v_mfma_f32_16x16x32_bf16 v[48:51], v[144:147], v[182:185], v[48:51]
	v_mfma_f32_16x16x32_bf16 v[56:59], v[158:161], v[182:185], v[56:59]
	v_mfma_f32_16x16x32_bf16 v[24:27], v[144:147], v[192:195], v[24:27]
	v_mfma_f32_16x16x32_bf16 v[32:35], v[158:161], v[192:195], v[32:35]
	v_mfma_f32_16x16x32_bf16 v[0:3], v[144:147], v[200:203], v[0:3]
	v_mfma_f32_16x16x32_bf16 v[4:7], v[158:161], v[200:203], v[4:7]
	v_mfma_f32_16x16x32_bf16 v[8:11], v[144:147], v[208:211], v[8:11]
	v_mfma_f32_16x16x32_bf16 v[16:19], v[158:161], v[208:211], v[16:19]
	v_mfma_f32_16x16x32_bf16 v[48:51], v[154:157], v[188:191], v[48:51]
	v_mfma_f32_16x16x32_bf16 v[56:59], v[162:165], v[188:191], v[56:59]
	v_mfma_f32_16x16x32_bf16 v[24:27], v[154:157], v[196:199], v[24:27]
	v_mfma_f32_16x16x32_bf16 v[32:35], v[162:165], v[196:199], v[32:35]
	v_mfma_f32_16x16x32_bf16 v[0:3], v[154:157], v[204:207], v[0:3]
	v_mfma_f32_16x16x32_bf16 v[4:7], v[162:165], v[204:207], v[4:7]
	v_mfma_f32_16x16x32_bf16 v[8:11], v[154:157], v[212:215], v[8:11]
	v_mfma_f32_16x16x32_bf16 v[16:19], v[162:165], v[212:215], v[16:19]
	v_mfma_f32_16x16x32_bf16 v[52:55], v[166:169], v[182:185], v[52:55]
	v_mfma_f32_16x16x32_bf16 v[60:63], v[174:177], v[182:185], v[60:63]
	v_mfma_f32_16x16x32_bf16 v[28:31], v[166:169], v[192:195], v[28:31]
	v_mfma_f32_16x16x32_bf16 v[36:39], v[174:177], v[192:195], v[36:39]
	v_mfma_f32_16x16x32_bf16 v[40:43], v[166:169], v[200:203], v[40:43]
	v_mfma_f32_16x16x32_bf16 v[44:47], v[174:177], v[200:203], v[44:47]
	v_mfma_f32_16x16x32_bf16 v[12:15], v[166:169], v[208:211], v[12:15]
	v_mfma_f32_16x16x32_bf16 v[20:23], v[174:177], v[208:211], v[20:23]
	v_mfma_f32_16x16x32_bf16 v[52:55], v[170:173], v[188:191], v[52:55]
	v_mfma_f32_16x16x32_bf16 v[60:63], v[178:181], v[188:191], v[60:63]
	v_mfma_f32_16x16x32_bf16 v[28:31], v[170:173], v[196:199], v[28:31]
	v_mfma_f32_16x16x32_bf16 v[36:39], v[178:181], v[196:199], v[36:39]
	v_mfma_f32_16x16x32_bf16 v[40:43], v[170:173], v[204:207], v[40:43]
	v_mfma_f32_16x16x32_bf16 v[44:47], v[178:181], v[204:207], v[44:47]
	v_mfma_f32_16x16x32_bf16 v[12:15], v[170:173], v[212:215], v[12:15]
	v_mfma_f32_16x16x32_bf16 v[20:23], v[178:181], v[212:215], v[20:23]
	s_barrier
; #define PG8_STAGE(bufoff, gbase, voff) do { _Pragma("unroll") for (int _i = 0; _i < 2; ++_i) \
;         __builtin_amdgcn_global_load_lds((const unsigned*)((const char*)(gbase) + (voff)[_i]), (PG8_LAS unsigned*)(lds + (bufoff) + ldsw + _i * 8192), 16, 0, 0); } while (0)
; #define PG8_LDA(dst, b, h) do { _Pragma("unroll") for (int m = 0; m < 4; ++m) _Pragma("unroll") for (int k = 0; k < 2; ++k) dst[m][k] = *(const PG8_LAS bf16x8*)(lds + PG8_SA(b, h) + aoff + m * 2048 + k * 1024); } while (0)
; #define PG8_LDB(dst, b, h) do { _Pragma("unroll") for (int n = 0; n < 2; ++n) _Pragma("unroll") for (int k = 0; k < 2; ++k) dst[n][k] = *(const PG8_LAS bf16x8*)(lds + PG8_SB(b, h) + boff + n * 2048 + k * 1024); } while (0)
; #define PG8_MMA(ai, bj, At, Bt) do { __builtin_amdgcn_s_setprio(1); _Pragma("unroll") for (int m = 0; m < 4; ++m) _Pragma("unroll") for (int n = 0; n < 2; ++n) _Pragma("unroll") for (int k = 0; k < 2; ++k) \
;         acc[ai][bj][m][n] = __builtin_amdgcn_mfma_f32_16x16x32_bf16(Bt[n][k], At[m][k], acc[ai][bj][m][n], 0, 0, 0); __builtin_amdgcn_s_setprio(0); } while (0)
; #define PG8_WAIT_V(n) asm volatile("s_waitcnt vmcnt(" #n ")" ::: "memory")
; #define PG8_WAIT_L(n) asm volatile("s_waitcnt lgkmcnt(" #n ")" ::: "memory")
; #define PG8_BAR __builtin_amdgcn_s_barrier()
; template <class Epi, class Sched, bool ALIGN_EPI = false, bool SP2 = false>
; __device__ __forceinline__ void gemm_phase(PG8_LAS unsigned char* lds, const Gemm g, const Sched S, const Epi E, const int tid) {
;     ...
;         for (int t = 0; t < nt; t += 2) {
;             const bool last = (t == nt - 2);
;             const char* a1 = cA + (size_t)(t + 1) * kstep;
;             const char* a2 = last ? nA : cA + (size_t)(t + 2) * kstep; const char* b2 = last ? nB : cB + (size_t)(t + 2) * kstep;
;             const char* a3 = a2 + kstep; const char* b3 = b2 + kstep;
;     ...
;             PG8_LDB(B0, 1, 0); PG8_LDB(B1, 1, 1); PG8_SCHED; PG8_LDA(At, 1, 0); PG8_STAGE(PG8_SA(0, 1), a2 + hstepA, voffA);
;             PG8_WAIT_V(8); PG8_WAIT_L(0); PG8_BAR; PG8_MMA(0, 0, At, B0); PG8_MMA(0, 1, At, B1); PG8_BAR; PG8_SCHED;
;             PG8_LDA(At, 1, 1); PG8_STAGE(PG8_SB(1, 0), b3, voffB); PG8_STAGE(PG8_SB(1, 1), b3 + hstepB, voffB); PG8_STAGE(PG8_SA(1, 0), a3, voffA);
;             PG8_WAIT_V(8); PG8_WAIT_L(0); PG8_BAR; PG8_MMA(1, 0, At, B0); PG8_MMA(1, 1, At, B1); PG8_BAR; PG8_SCHED;
	s_add_i32 s76, 0, 0x18000
	s_add_i32 s77, 0, 0x1c000
	v_add_u32_e32 v162, s76, v149
	v_add_u32_e32 v178, s77, v149
	ds_read_b128 v[144:147], v162
	ds_read_b128 v[154:157], v162 offset:1024
	ds_read_b128 v[158:161], v162 offset:2048
	ds_read_b128 v[162:165], v162 offset:3072
	ds_read_b128 v[166:169], v178
	ds_read_b128 v[170:173], v178 offset:1024
	ds_read_b128 v[174:177], v178 offset:2048
	ds_read_b128 v[178:181], v178 offset:3072
	s_add_u32 s38, s46, 0xc0000
	s_addc_u32 s39, s47, 0
	s_mov_b32 m0, s60
	ds_read_b128 v[182:185], v153 offset:32768
	ds_read_b128 v[188:191], v153 offset:33792
	ds_read_b128 v[192:195], v153 offset:34816
	ds_read_b128 v[196:199], v153 offset:35840
	ds_read_b128 v[200:203], v153 offset:36864
	ds_read_b128 v[204:207], v153 offset:37888
	ds_read_b128 v[208:211], v153 offset:38912
	ds_read_b128 v[212:215], v153 offset:39936
	global_load_lds_dwordx4 v128, s[38:39]
	s_mov_b32 m0, s61
	s_nop 0
	global_load_lds_dwordx4 v132, s[38:39]
	s_waitcnt vmcnt(8)
	s_waitcnt lgkmcnt(0)
	s_barrier
	s_waitcnt lgkmcnt(0)
	v_mfma_f32_16x16x32_bf16 v[112:115], v[144:147], v[182:185], v[112:115]
	v_mfma_f32_16x16x32_bf16 v[120:123], v[158:161], v[182:185], v[120:123]
	v_mfma_f32_16x16x32_bf16 v[96:99], v[144:147], v[192:195], v[96:99]
	v_mfma_f32_16x16x32_bf16 v[104:107], v[158:161], v[192:195], v[104:107]
	v_mfma_f32_16x16x32_bf16 v[80:83], v[144:147], v[200:203], v[80:83]
	v_mfma_f32_16x16x32_bf16 v[88:91], v[158:161], v[200:203], v[88:91]
	v_mfma_f32_16x16x32_bf16 v[64:67], v[144:147], v[208:211], v[64:67]
	v_mfma_f32_16x16x32_bf16 v[72:75], v[158:161], v[208:211], v[72:75]
	v_mfma_f32_16x16x32_bf16 v[112:115], v[154:157], v[188:191], v[112:115]
	v_mfma_f32_16x16x32_bf16 v[120:123], v[162:165], v[188:191], v[120:123]
	v_mfma_f32_16x16x32_bf16 v[96:99], v[154:157], v[196:199], v[96:99]
	v_mfma_f32_16x16x32_bf16 v[104:107], v[162:165], v[196:199], v[104:107]
	v_mfma_f32_16x16x32_bf16 v[80:83], v[154:157], v[204:207], v[80:83]
	v_mfma_f32_16x16x32_bf16 v[88:91], v[162:165], v[204:207], v[88:91]
	v_mfma_f32_16x16x32_bf16 v[64:67], v[154:157], v[212:215], v[64:67]
	v_mfma_f32_16x16x32_bf16 v[72:75], v[162:165], v[212:215], v[72:75]
	v_mfma_f32_16x16x32_bf16 v[116:119], v[166:169], v[182:185], v[116:119]
	v_mfma_f32_16x16x32_bf16 v[124:127], v[174:177], v[182:185], v[124:127]
	v_mfma_f32_16x16x32_bf16 v[100:103], v[166:169], v[192:195], v[100:103]
	v_mfma_f32_16x16x32_bf16 v[108:111], v[174:177], v[192:195], v[108:111]
	v_mfma_f32_16x16x32_bf16 v[84:87], v[166:169], v[200:203], v[84:87]
	v_mfma_f32_16x16x32_bf16 v[92:95], v[174:177], v[200:203], v[92:95]
	v_mfma_f32_16x16x32_bf16 v[68:71], v[166:169], v[208:211], v[68:71]
	v_mfma_f32_16x16x32_bf16 v[76:79], v[174:177], v[208:211], v[76:79]
	v_mfma_f32_16x16x32_bf16 v[116:119], v[170:173], v[188:191], v[116:119]
	v_mfma_f32_16x16x32_bf16 v[124:127], v[178:181], v[188:191], v[124:127]
	v_mfma_f32_16x16x32_bf16 v[100:103], v[170:173], v[196:199], v[100:103]
	v_mfma_f32_16x16x32_bf16 v[108:111], v[178:181], v[196:199], v[108:111]
	v_mfma_f32_16x16x32_bf16 v[84:87], v[170:173], v[204:207], v[84:87]
	v_mfma_f32_16x16x32_bf16 v[92:95], v[178:181], v[204:207], v[92:95]
	v_mfma_f32_16x16x32_bf16 v[68:71], v[170:173], v[212:215], v[68:71]
	v_mfma_f32_16x16x32_bf16 v[76:79], v[178:181], v[212:215], v[76:79]
	s_barrier
	s_add_i32 s38, s76, s33
	s_mov_b32 m0, s38
	ds_read_b128 v[182:185], v153 offset:49152
	ds_read_b128 v[188:191], v153 offset:50176
	ds_read_b128 v[192:195], v153 offset:51200
	ds_read_b128 v[196:199], v153 offset:52224
	ds_read_b128 v[200:203], v153 offset:53248
	ds_read_b128 v[204:207], v153 offset:54272
	ds_read_b128 v[208:211], v153 offset:55296
	ds_read_b128 v[212:215], v153 offset:56320
	global_load_lds_dwordx4 v130, s[98:99]
	s_add_i32 m0, s38, 0x2000
	s_add_u32 s38, s40, 0x40080
	s_addc_u32 s39, s41, 0
	s_add_i32 s40, s77, s33
	global_load_lds_dwordx4 v134, s[98:99]
	s_mov_b32 m0, s40
	s_nop 0
	global_load_lds_dwordx4 v130, s[38:39]
	s_add_i32 m0, s40, 0x2000
	s_nop 0
	global_load_lds_dwordx4 v134, s[38:39]
	s_mov_b32 m0, s63
	s_nop 0
	global_load_lds_dwordx4 v128, s[100:101]
	s_mov_b32 m0, s64
	s_nop 0
	global_load_lds_dwordx4 v132, s[100:101]
	s_waitcnt vmcnt(8)
	s_waitcnt lgkmcnt(0)
	s_barrier
	s_waitcnt lgkmcnt(0)
	v_mfma_f32_16x16x32_bf16 v[48:51], v[144:147], v[182:185], v[48:51]
	v_mfma_f32_16x16x32_bf16 v[56:59], v[158:161], v[182:185], v[56:59]
	v_mfma_f32_16x16x32_bf16 v[24:27], v[144:147], v[192:195], v[24:27]
	v_mfma_f32_16x16x32_bf16 v[32:35], v[158:161], v[192:195], v[32:35]
	v_mfma_f32_16x16x32_bf16 v[0:3], v[144:147], v[200:203], v[0:3]
	v_mfma_f32_16x16x32_bf16 v[4:7], v[158:161], v[200:203], v[4:7]
	v_mfma_f32_16x16x32_bf16 v[8:11], v[144:147], v[208:211], v[8:11]
	v_mfma_f32_16x16x32_bf16 v[16:19], v[158:161], v[208:211], v[16:19]
	v_mfma_f32_16x16x32_bf16 v[48:51], v[154:157], v[188:191], v[48:51]
	v_mfma_f32_16x16x32_bf16 v[56:59], v[162:165], v[188:191], v[56:59]
	v_mfma_f32_16x16x32_bf16 v[24:27], v[154:157], v[196:199], v[24:27]
	v_mfma_f32_16x16x32_bf16 v[32:35], v[162:165], v[196:199], v[32:35]
	v_mfma_f32_16x16x32_bf16 v[0:3], v[154:157], v[204:207], v[0:3]
	v_mfma_f32_16x16x32_bf16 v[4:7], v[162:165], v[204:207], v[4:7]
	v_mfma_f32_16x16x32_bf16 v[8:11], v[154:157], v[212:215], v[8:11]
	v_mfma_f32_16x16x32_bf16 v[16:19], v[162:165], v[212:215], v[16:19]
	v_mfma_f32_16x16x32_bf16 v[52:55], v[166:169], v[182:185], v[52:55]
	v_mfma_f32_16x16x32_bf16 v[60:63], v[174:177], v[182:185], v[60:63]
	v_mfma_f32_16x16x32_bf16 v[28:31], v[166:169], v[192:195], v[28:31]
	v_mfma_f32_16x16x32_bf16 v[36:39], v[174:177], v[192:195], v[36:39]
	v_mfma_f32_16x16x32_bf16 v[40:43], v[166:169], v[200:203], v[40:43]
	v_mfma_f32_16x16x32_bf16 v[44:47], v[174:177], v[200:203], v[44:47]
	v_mfma_f32_16x16x32_bf16 v[12:15], v[166:169], v[208:211], v[12:15]
	v_mfma_f32_16x16x32_bf16 v[20:23], v[174:177], v[208:211], v[20:23]
	v_mfma_f32_16x16x32_bf16 v[52:55], v[170:173], v[188:191], v[52:55]
	v_mfma_f32_16x16x32_bf16 v[60:63], v[178:181], v[188:191], v[60:63]
	v_mfma_f32_16x16x32_bf16 v[28:31], v[170:173], v[196:199], v[28:31]
	v_mfma_f32_16x16x32_bf16 v[36:39], v[178:181], v[196:199], v[36:39]
	v_mfma_f32_16x16x32_bf16 v[40:43], v[170:173], v[204:207], v[40:43]
	v_mfma_f32_16x16x32_bf16 v[44:47], v[178:181], v[204:207], v[44:47]
	v_mfma_f32_16x16x32_bf16 v[12:15], v[170:173], v[212:215], v[12:15]
	v_mfma_f32_16x16x32_bf16 v[20:23], v[178:181], v[212:215], v[20:23]
	s_barrier
	s_add_i32 s75, s75, 2
	s_add_u32 s73, s73, 0x100
	s_addc_u32 s74, s74, 0
	s_cmp_gt_u32 s75, 13
	s_mov_b64 s[38:39], s[6:7]
	s_cbranch_scc0 .LBB0_672
	s_and_b64 vcc, exec, s[24:25]
	s_cbranch_vccz .LBB0_675
	s_barrier

; #define PG8_STAGE(bufoff, gbase, voff) do { _Pragma("unroll") for (int _i = 0; _i < 2; ++_i) \
;         __builtin_amdgcn_global_load_lds((const unsigned*)((const char*)(gbase) + (voff)[_i]), (PG8_LAS unsigned*)(lds + (bufoff) + ldsw + _i * 8192), 16, 0, 0); } while (0)
; #define PG8_LDA(dst, b, h) do { _Pragma("unroll") for (int m = 0; m < 4; ++m) _Pragma("unroll") for (int k = 0; k < 2; ++k) dst[m][k] = *(const PG8_LAS bf16x8*)(lds + PG8_SA(b, h) + aoff + m * 2048 + k * 1024); } while (0)
; #define PG8_LDB(dst, b, h) do { _Pragma("unroll") for (int n = 0; n < 2; ++n) _Pragma("unroll") for (int k = 0; k < 2; ++k) dst[n][k] = *(const PG8_LAS bf16x8*)(lds + PG8_SB(b, h) + boff + n * 2048 + k * 1024); } while (0)
; #define PG8_MMA(ai, bj, At, Bt) do { __builtin_amdgcn_s_setprio(1); _Pragma("unroll") for (int m = 0; m < 4; ++m) _Pragma("unroll") for (int n = 0; n < 2; ++n) _Pragma("unroll") for (int k = 0; k < 2; ++k) \
;         acc[ai][bj][m][n] = __builtin_amdgcn_mfma_f32_16x16x32_bf16(Bt[n][k], At[m][k], acc[ai][bj][m][n], 0, 0, 0); __builtin_amdgcn_s_setprio(0); } while (0)
; #define PG8_WAIT_V(n) asm volatile("s_waitcnt vmcnt(" #n ")" ::: "memory")
; #define PG8_WAIT_L(n) asm volatile("s_waitcnt lgkmcnt(" #n ")" ::: "memory")
; #define PG8_BAR __builtin_amdgcn_s_barrier()
; #define PG8_SCHED __builtin_amdgcn_sched_barrier(0)
; template <class Epi, class Sched, bool ALIGN_EPI = false, bool SP2 = false>
; __device__ __forceinline__ void gemm_phase(PG8_LAS unsigned char* lds, const Gemm g, const Sched S, const Epi E, const int tid) {
;     ...
;             PG8_LDB(B0, 0, 0); PG8_LDB(B1, 0, 1); PG8_SCHED; PG8_LDA(At, 0, 0); PG8_STAGE(PG8_SA(1, 1), a1 + hstepA, voffA);
;             PG8_WAIT_V(8); PG8_WAIT_L(0); PG8_BAR; PG8_MMA(0, 0, At, B0); PG8_MMA(0, 1, At, B1); PG8_BAR; PG8_SCHED;
;             PG8_LDA(At, 0, 1); PG8_STAGE(PG8_SB(0, 0), b2, voffB); PG8_STAGE(PG8_SB(0, 1), b2 + hstepB, voffB); PG8_STAGE(PG8_SA(0, 0), a2, voffA);
;             PG8_WAIT_V(8); PG8_WAIT_L(0); PG8_BAR; PG8_MMA(1, 0, At, B0); PG8_MMA(1, 1, At, B1); PG8_BAR; PG8_SCHED;
.LBB0_757:
	ds_read_b128 v[128:131], v206
	ds_read_b128 v[132:135], v206 offset:1024
	ds_read_b128 v[136:139], v206 offset:2048
	ds_read_b128 v[156:159], v206 offset:3072
	ds_read_b128 v[160:163], v207
	ds_read_b128 v[164:167], v207 offset:1024
	ds_read_b128 v[168:171], v207 offset:2048
	ds_read_b128 v[172:175], v207 offset:3072
	s_add_u32 s38, s36, 0xfffc0080
	s_addc_u32 s39, s37, -1
	s_cmp_eq_u32 s61, 12
	s_cselect_b32 s41, s5, s39
	s_cselect_b32 s40, s29, s38
	s_cselect_b32 s39, s27, s60
	s_cselect_b32 s38, s58, s59
	s_add_i32 m0, s47, 0xc000
	ds_read_b128 v[210:213], v208
	ds_read_b128 v[214:217], v208 offset:1024
	ds_read_b128 v[218:221], v208 offset:2048
	ds_read_b128 v[222:225], v208 offset:3072
	ds_read_b128 v[226:229], v208 offset:4096
	ds_read_b128 v[230:233], v208 offset:5120
	ds_read_b128 v[234:237], v208 offset:6144
	ds_read_b128 v[238:241], v208 offset:7168
	global_load_lds_dwordx4 v148, s[36:37]
	s_add_i32 m0, s47, 0xe000
	s_nop 0
	global_load_lds_dwordx4 v150, s[36:37]
	s_waitcnt vmcnt(8)
	s_waitcnt lgkmcnt(0)
	s_barrier
	s_waitcnt lgkmcnt(0)
	v_mfma_f32_16x16x32_bf16 v[124:127], v[128:131], v[210:213], v[124:127]
	v_mfma_f32_16x16x32_bf16 v[120:123], v[136:139], v[210:213], v[120:123]
	v_mfma_f32_16x16x32_bf16 v[112:115], v[128:131], v[218:221], v[112:115]
	v_mfma_f32_16x16x32_bf16 v[104:107], v[136:139], v[218:221], v[104:107]
	v_mfma_f32_16x16x32_bf16 v[96:99], v[128:131], v[226:229], v[96:99]
	v_mfma_f32_16x16x32_bf16 v[88:91], v[136:139], v[226:229], v[88:91]
	v_mfma_f32_16x16x32_bf16 v[80:83], v[128:131], v[234:237], v[80:83]
	v_mfma_f32_16x16x32_bf16 v[72:75], v[136:139], v[234:237], v[72:75]
	v_mfma_f32_16x16x32_bf16 v[124:127], v[132:135], v[214:217], v[124:127]
	v_mfma_f32_16x16x32_bf16 v[120:123], v[156:159], v[214:217], v[120:123]
	v_mfma_f32_16x16x32_bf16 v[112:115], v[132:135], v[222:225], v[112:115]
	v_mfma_f32_16x16x32_bf16 v[104:107], v[156:159], v[222:225], v[104:107]
	v_mfma_f32_16x16x32_bf16 v[96:99], v[132:135], v[230:233], v[96:99]
	v_mfma_f32_16x16x32_bf16 v[88:91], v[156:159], v[230:233], v[88:91]
	v_mfma_f32_16x16x32_bf16 v[80:83], v[132:135], v[238:241], v[80:83]
	v_mfma_f32_16x16x32_bf16 v[72:75], v[156:159], v[238:241], v[72:75]
	v_mfma_f32_16x16x32_bf16 v[116:119], v[160:163], v[210:213], v[116:119]
	v_mfma_f32_16x16x32_bf16 v[108:111], v[168:171], v[210:213], v[108:111]
	v_mfma_f32_16x16x32_bf16 v[100:103], v[160:163], v[218:221], v[100:103]
	v_mfma_f32_16x16x32_bf16 v[92:95], v[168:171], v[218:221], v[92:95]
	v_mfma_f32_16x16x32_bf16 v[84:87], v[160:163], v[226:229], v[84:87]
	v_mfma_f32_16x16x32_bf16 v[76:79], v[168:171], v[226:229], v[76:79]
	v_mfma_f32_16x16x32_bf16 v[68:71], v[160:163], v[234:237], v[68:71]
	v_mfma_f32_16x16x32_bf16 v[64:67], v[168:171], v[234:237], v[64:67]
	v_mfma_f32_16x16x32_bf16 v[116:119], v[164:167], v[214:217], v[116:119]
	v_mfma_f32_16x16x32_bf16 v[108:111], v[172:175], v[214:217], v[108:111]
	v_mfma_f32_16x16x32_bf16 v[100:103], v[164:167], v[222:225], v[100:103]
	v_mfma_f32_16x16x32_bf16 v[92:95], v[172:175], v[222:225], v[92:95]
	v_mfma_f32_16x16x32_bf16 v[84:87], v[164:167], v[230:233], v[84:87]
	v_mfma_f32_16x16x32_bf16 v[76:79], v[172:175], v[230:233], v[76:79]
	v_mfma_f32_16x16x32_bf16 v[68:71], v[164:167], v[238:241], v[68:71]
	v_mfma_f32_16x16x32_bf16 v[64:67], v[172:175], v[238:241], v[64:67]
	s_barrier
	s_add_u32 s98, s38, 0x80
	s_addc_u32 s99, s39, 0
	s_add_u32 s100, s40, 0x80
	s_addc_u32 s101, s41, 0
	s_add_i32 s62, s55, s46
	s_mov_b32 m0, s62
	ds_read_b128 v[210:213], v208 offset:16384
	ds_read_b128 v[214:217], v208 offset:17408
	ds_read_b128 v[218:221], v208 offset:18432
	ds_read_b128 v[222:225], v208 offset:19456
	ds_read_b128 v[226:229], v208 offset:20480
	ds_read_b128 v[230:233], v208 offset:21504
	ds_read_b128 v[234:237], v208 offset:22528
	ds_read_b128 v[238:241], v208 offset:23552
	global_load_lds_dwordx4 v142, s[38:39]
	s_add_i32 m0, s62, 0x2000
	s_add_u32 s62, s38, 0x40000
	s_addc_u32 s63, s39, 0
	s_add_i32 s64, s56, s46
	global_load_lds_dwordx4 v146, s[38:39]
	s_mov_b32 m0, s64
	s_nop 0
	global_load_lds_dwordx4 v142, s[62:63]
	s_add_i32 m0, s64, 0x2000
	s_nop 0
	global_load_lds_dwordx4 v146, s[62:63]
	s_mov_b32 m0, s47
	s_nop 0
	global_load_lds_dwordx4 v140, s[40:41]
	s_mov_b32 m0, s48
	s_nop 0
	global_load_lds_dwordx4 v144, s[40:41]
	s_waitcnt vmcnt(8)
	s_waitcnt lgkmcnt(0)
	s_barrier
	s_waitcnt lgkmcnt(0)
	v_mfma_f32_16x16x32_bf16 v[60:63], v[128:131], v[210:213], v[60:63]
	v_mfma_f32_16x16x32_bf16 v[56:59], v[136:139], v[210:213], v[56:59]
	v_mfma_f32_16x16x32_bf16 v[48:51], v[128:131], v[218:221], v[48:51]
	v_mfma_f32_16x16x32_bf16 v[40:43], v[136:139], v[218:221], v[40:43]
	v_mfma_f32_16x16x32_bf16 v[32:35], v[128:131], v[226:229], v[32:35]
	v_mfma_f32_16x16x32_bf16 v[24:27], v[136:139], v[226:229], v[24:27]
	v_mfma_f32_16x16x32_bf16 v[16:19], v[128:131], v[234:237], v[16:19]
	v_mfma_f32_16x16x32_bf16 v[8:11], v[136:139], v[234:237], v[8:11]
	v_mfma_f32_16x16x32_bf16 v[60:63], v[132:135], v[214:217], v[60:63]
	v_mfma_f32_16x16x32_bf16 v[56:59], v[156:159], v[214:217], v[56:59]
	v_mfma_f32_16x16x32_bf16 v[48:51], v[132:135], v[222:225], v[48:51]
	v_mfma_f32_16x16x32_bf16 v[40:43], v[156:159], v[222:225], v[40:43]
	v_mfma_f32_16x16x32_bf16 v[32:35], v[132:135], v[230:233], v[32:35]
	v_mfma_f32_16x16x32_bf16 v[24:27], v[156:159], v[230:233], v[24:27]
	v_mfma_f32_16x16x32_bf16 v[16:19], v[132:135], v[238:241], v[16:19]
	v_mfma_f32_16x16x32_bf16 v[8:11], v[156:159], v[238:241], v[8:11]
	v_mfma_f32_16x16x32_bf16 v[52:55], v[160:163], v[210:213], v[52:55]
	v_mfma_f32_16x16x32_bf16 v[44:47], v[168:171], v[210:213], v[44:47]
	v_mfma_f32_16x16x32_bf16 v[36:39], v[160:163], v[218:221], v[36:39]
	v_mfma_f32_16x16x32_bf16 v[28:31], v[168:171], v[218:221], v[28:31]
	v_mfma_f32_16x16x32_bf16 v[20:23], v[160:163], v[226:229], v[20:23]
	v_mfma_f32_16x16x32_bf16 v[12:15], v[168:171], v[226:229], v[12:15]
	v_mfma_f32_16x16x32_bf16 v[4:7], v[160:163], v[234:237], v[4:7]
	v_mfma_f32_16x16x32_bf16 v[0:3], v[168:171], v[234:237], v[0:3]
	v_mfma_f32_16x16x32_bf16 v[52:55], v[164:167], v[214:217], v[52:55]
	v_mfma_f32_16x16x32_bf16 v[44:47], v[172:175], v[214:217], v[44:47]
	v_mfma_f32_16x16x32_bf16 v[36:39], v[164:167], v[222:225], v[36:39]
	v_mfma_f32_16x16x32_bf16 v[28:31], v[172:175], v[222:225], v[28:31]
	v_mfma_f32_16x16x32_bf16 v[20:23], v[164:167], v[230:233], v[20:23]
	v_mfma_f32_16x16x32_bf16 v[12:15], v[172:175], v[230:233], v[12:15]
	v_mfma_f32_16x16x32_bf16 v[4:7], v[164:167], v[238:241], v[4:7]
	v_mfma_f32_16x16x32_bf16 v[0:3], v[172:175], v[238:241], v[0:3]
	s_barrier
; #define PG8_STAGE(bufoff, gbase, voff) do { _Pragma("unroll") for (int _i = 0; _i < 2; ++_i) \
;         __builtin_amdgcn_global_load_lds((const unsigned*)((const char*)(gbase) + (voff)[_i]), (PG8_LAS unsigned*)(lds + (bufoff) + ldsw + _i * 8192), 16, 0, 0); } while (0)
; #define PG8_LDA(dst, b, h) do { _Pragma("unroll") for (int m = 0; m < 4; ++m) _Pragma("unroll") for (int k = 0; k < 2; ++k) dst[m][k] = *(const PG8_LAS bf16x8*)(lds + PG8_SA(b, h) + aoff + m * 2048 + k * 1024); } while (0)
; #define PG8_LDB(dst, b, h) do { _Pragma("unroll") for (int n = 0; n < 2; ++n) _Pragma("unroll") for (int k = 0; k < 2; ++k) dst[n][k] = *(const PG8_LAS bf16x8*)(lds + PG8_SB(b, h) + boff + n * 2048 + k * 1024); } while (0)
; #define PG8_MMA(ai, bj, At, Bt) do { __builtin_amdgcn_s_setprio(1); _Pragma("unroll") for (int m = 0; m < 4; ++m) _Pragma("unroll") for (int n = 0; n < 2; ++n) _Pragma("unroll") for (int k = 0; k < 2; ++k) \
;         acc[ai][bj][m][n] = __builtin_amdgcn_mfma_f32_16x16x32_bf16(Bt[n][k], At[m][k], acc[ai][bj][m][n], 0, 0, 0); __builtin_amdgcn_s_setprio(0); } while (0)
; #define PG8_WAIT_V(n) asm volatile("s_waitcnt vmcnt(" #n ")" ::: "memory")
; #define PG8_WAIT_L(n) asm volatile("s_waitcnt lgkmcnt(" #n ")" ::: "memory")
; #define PG8_BAR __builtin_amdgcn_s_barrier()
; template <class Epi, class Sched, bool ALIGN_EPI = false, bool SP2 = false>
; __device__ __forceinline__ void gemm_phase(PG8_LAS unsigned char* lds, const Gemm g, const Sched S, const Epi E, const int tid) {
;     ...
;         for (int t = 0; t < nt; t += 2) {
;             const bool last = (t == nt - 2);
;             const char* a1 = cA + (size_t)(t + 1) * kstep;
;             const char* a2 = last ? nA : cA + (size_t)(t + 2) * kstep; const char* b2 = last ? nB : cB + (size_t)(t + 2) * kstep;
;             const char* a3 = a2 + kstep; const char* b3 = b2 + kstep;
;     ...
;             PG8_LDB(B0, 1, 0); PG8_LDB(B1, 1, 1); PG8_SCHED; PG8_LDA(At, 1, 0); PG8_STAGE(PG8_SA(0, 1), a2 + hstepA, voffA);
;             PG8_WAIT_V(8); PG8_WAIT_L(0); PG8_BAR; PG8_MMA(0, 0, At, B0); PG8_MMA(0, 1, At, B1); PG8_BAR; PG8_SCHED;
;             PG8_LDA(At, 1, 1); PG8_STAGE(PG8_SB(1, 0), b3, voffB); PG8_STAGE(PG8_SB(1, 1), b3 + hstepB, voffB); PG8_STAGE(PG8_SA(1, 0), a3, voffA);
;             PG8_WAIT_V(8); PG8_WAIT_L(0); PG8_BAR; PG8_MMA(1, 0, At, B0); PG8_MMA(1, 1, At, B1); PG8_BAR; PG8_SCHED;
	s_add_i32 s62, 0, 0x18000
	s_add_i32 s63, 0, 0x1c000
	v_add_u32_e32 v156, s62, v204
	v_add_u32_e32 v172, s63, v204
	ds_read_b128 v[128:131], v156
	ds_read_b128 v[132:135], v156 offset:1024
	ds_read_b128 v[136:139], v156 offset:2048
	ds_read_b128 v[156:159], v156 offset:3072
	ds_read_b128 v[160:163], v172
	ds_read_b128 v[164:167], v172 offset:1024
	ds_read_b128 v[168:171], v172 offset:2048
	ds_read_b128 v[172:175], v172 offset:3072
	s_add_u32 s40, s40, 0x40000
	s_addc_u32 s41, s41, 0
	s_mov_b32 m0, s49
	ds_read_b128 v[210:213], v208 offset:32768
	ds_read_b128 v[214:217], v208 offset:33792
	ds_read_b128 v[218:221], v208 offset:34816
	ds_read_b128 v[222:225], v208 offset:35840
	ds_read_b128 v[226:229], v208 offset:36864
	ds_read_b128 v[230:233], v208 offset:37888
	ds_read_b128 v[234:237], v208 offset:38912
	ds_read_b128 v[238:241], v208 offset:39936
	global_load_lds_dwordx4 v140, s[40:41]
	s_mov_b32 m0, s50
	s_nop 0
	global_load_lds_dwordx4 v144, s[40:41]
	s_waitcnt vmcnt(8)
	s_waitcnt lgkmcnt(0)
	s_barrier
	s_waitcnt lgkmcnt(0)
	v_mfma_f32_16x16x32_bf16 v[124:127], v[128:131], v[210:213], v[124:127]
	v_mfma_f32_16x16x32_bf16 v[120:123], v[136:139], v[210:213], v[120:123]
	v_mfma_f32_16x16x32_bf16 v[112:115], v[128:131], v[218:221], v[112:115]
	v_mfma_f32_16x16x32_bf16 v[104:107], v[136:139], v[218:221], v[104:107]
	v_mfma_f32_16x16x32_bf16 v[96:99], v[128:131], v[226:229], v[96:99]
	v_mfma_f32_16x16x32_bf16 v[88:91], v[136:139], v[226:229], v[88:91]
	v_mfma_f32_16x16x32_bf16 v[80:83], v[128:131], v[234:237], v[80:83]
	v_mfma_f32_16x16x32_bf16 v[72:75], v[136:139], v[234:237], v[72:75]
	v_mfma_f32_16x16x32_bf16 v[124:127], v[132:135], v[214:217], v[124:127]
	v_mfma_f32_16x16x32_bf16 v[120:123], v[156:159], v[214:217], v[120:123]
	v_mfma_f32_16x16x32_bf16 v[112:115], v[132:135], v[222:225], v[112:115]
	v_mfma_f32_16x16x32_bf16 v[104:107], v[156:159], v[222:225], v[104:107]
	v_mfma_f32_16x16x32_bf16 v[96:99], v[132:135], v[230:233], v[96:99]
	v_mfma_f32_16x16x32_bf16 v[88:91], v[156:159], v[230:233], v[88:91]
	v_mfma_f32_16x16x32_bf16 v[80:83], v[132:135], v[238:241], v[80:83]
	v_mfma_f32_16x16x32_bf16 v[72:75], v[156:159], v[238:241], v[72:75]
	v_mfma_f32_16x16x32_bf16 v[116:119], v[160:163], v[210:213], v[116:119]
	v_mfma_f32_16x16x32_bf16 v[108:111], v[168:171], v[210:213], v[108:111]
	v_mfma_f32_16x16x32_bf16 v[100:103], v[160:163], v[218:221], v[100:103]
	v_mfma_f32_16x16x32_bf16 v[92:95], v[168:171], v[218:221], v[92:95]
	v_mfma_f32_16x16x32_bf16 v[84:87], v[160:163], v[226:229], v[84:87]
	v_mfma_f32_16x16x32_bf16 v[76:79], v[168:171], v[226:229], v[76:79]
	v_mfma_f32_16x16x32_bf16 v[68:71], v[160:163], v[234:237], v[68:71]
	v_mfma_f32_16x16x32_bf16 v[64:67], v[168:171], v[234:237], v[64:67]
	v_mfma_f32_16x16x32_bf16 v[116:119], v[164:167], v[214:217], v[116:119]
	v_mfma_f32_16x16x32_bf16 v[108:111], v[172:175], v[214:217], v[108:111]
	v_mfma_f32_16x16x32_bf16 v[100:103], v[164:167], v[222:225], v[100:103]
	v_mfma_f32_16x16x32_bf16 v[92:95], v[172:175], v[222:225], v[92:95]
	v_mfma_f32_16x16x32_bf16 v[84:87], v[164:167], v[230:233], v[84:87]
	v_mfma_f32_16x16x32_bf16 v[76:79], v[172:175], v[230:233], v[76:79]
	v_mfma_f32_16x16x32_bf16 v[68:71], v[164:167], v[238:241], v[68:71]
	v_mfma_f32_16x16x32_bf16 v[64:67], v[172:175], v[238:241], v[64:67]
	s_barrier
	s_add_i32 s40, s62, s46
	s_mov_b32 m0, s40
	ds_read_b128 v[210:213], v208 offset:49152
	ds_read_b128 v[214:217], v208 offset:50176
	ds_read_b128 v[218:221], v208 offset:51200
	ds_read_b128 v[222:225], v208 offset:52224
	ds_read_b128 v[226:229], v208 offset:53248
	ds_read_b128 v[230:233], v208 offset:54272
	ds_read_b128 v[234:237], v208 offset:55296
	ds_read_b128 v[238:241], v208 offset:56320
	global_load_lds_dwordx4 v142, s[98:99]
	s_add_i32 m0, s40, 0x2000
	s_add_u32 s38, s38, 0x40080
	s_addc_u32 s39, s39, 0
	s_add_i32 s40, s63, s46
	global_load_lds_dwordx4 v146, s[98:99]
	s_mov_b32 m0, s40
	s_nop 0
	global_load_lds_dwordx4 v142, s[38:39]
	s_add_i32 m0, s40, 0x2000
	s_nop 0
	global_load_lds_dwordx4 v146, s[38:39]
	s_mov_b32 m0, s52
	s_nop 0
	global_load_lds_dwordx4 v140, s[100:101]
	s_mov_b32 m0, s53
	s_nop 0
	global_load_lds_dwordx4 v144, s[100:101]
	s_waitcnt vmcnt(8)
	s_waitcnt lgkmcnt(0)
	s_barrier
	s_waitcnt lgkmcnt(0)
	v_mfma_f32_16x16x32_bf16 v[60:63], v[128:131], v[210:213], v[60:63]
	v_mfma_f32_16x16x32_bf16 v[56:59], v[136:139], v[210:213], v[56:59]
	v_mfma_f32_16x16x32_bf16 v[48:51], v[128:131], v[218:221], v[48:51]
	v_mfma_f32_16x16x32_bf16 v[40:43], v[136:139], v[218:221], v[40:43]
	v_mfma_f32_16x16x32_bf16 v[32:35], v[128:131], v[226:229], v[32:35]
	v_mfma_f32_16x16x32_bf16 v[24:27], v[136:139], v[226:229], v[24:27]
	v_mfma_f32_16x16x32_bf16 v[16:19], v[128:131], v[234:237], v[16:19]
	v_mfma_f32_16x16x32_bf16 v[8:11], v[136:139], v[234:237], v[8:11]
	v_mfma_f32_16x16x32_bf16 v[60:63], v[132:135], v[214:217], v[60:63]
	v_mfma_f32_16x16x32_bf16 v[56:59], v[156:159], v[214:217], v[56:59]
	v_mfma_f32_16x16x32_bf16 v[48:51], v[132:135], v[222:225], v[48:51]
	v_mfma_f32_16x16x32_bf16 v[40:43], v[156:159], v[222:225], v[40:43]
	v_mfma_f32_16x16x32_bf16 v[32:35], v[132:135], v[230:233], v[32:35]
	v_mfma_f32_16x16x32_bf16 v[24:27], v[156:159], v[230:233], v[24:27]
	v_mfma_f32_16x16x32_bf16 v[16:19], v[132:135], v[238:241], v[16:19]
	v_mfma_f32_16x16x32_bf16 v[8:11], v[156:159], v[238:241], v[8:11]
	v_mfma_f32_16x16x32_bf16 v[52:55], v[160:163], v[210:213], v[52:55]
	v_mfma_f32_16x16x32_bf16 v[44:47], v[168:171], v[210:213], v[44:47]
	v_mfma_f32_16x16x32_bf16 v[36:39], v[160:163], v[218:221], v[36:39]
	v_mfma_f32_16x16x32_bf16 v[28:31], v[168:171], v[218:221], v[28:31]
	v_mfma_f32_16x16x32_bf16 v[20:23], v[160:163], v[226:229], v[20:23]
	v_mfma_f32_16x16x32_bf16 v[12:15], v[168:171], v[226:229], v[12:15]
	v_mfma_f32_16x16x32_bf16 v[4:7], v[160:163], v[234:237], v[4:7]
	v_mfma_f32_16x16x32_bf16 v[0:3], v[168:171], v[234:237], v[0:3]
	v_mfma_f32_16x16x32_bf16 v[52:55], v[164:167], v[214:217], v[52:55]
	v_mfma_f32_16x16x32_bf16 v[44:47], v[172:175], v[214:217], v[44:47]
	v_mfma_f32_16x16x32_bf16 v[36:39], v[164:167], v[222:225], v[36:39]
	v_mfma_f32_16x16x32_bf16 v[28:31], v[172:175], v[222:225], v[28:31]
	v_mfma_f32_16x16x32_bf16 v[20:23], v[164:167], v[230:233], v[20:23]
	v_mfma_f32_16x16x32_bf16 v[12:15], v[172:175], v[230:233], v[12:15]
	v_mfma_f32_16x16x32_bf16 v[4:7], v[164:167], v[238:241], v[4:7]
	v_mfma_f32_16x16x32_bf16 v[0:3], v[172:175], v[238:241], v[0:3]
	s_barrier
	s_add_i32 s61, s61, 2
	s_add_u32 s36, s36, 0x100
	s_addc_u32 s37, s37, 0
	s_add_u32 s59, s59, 0x100
	s_addc_u32 s60, s60, 0
	s_cmp_gt_u32 s61, 13
	s_cbranch_scc0 .LBB0_757
	s_and_b64 vcc, exec, s[20:21]
	s_cbranch_vccz .LBB0_760
	s_barrier

; #define PG8_STAGE(bufoff, gbase, voff) do { _Pragma("unroll") for (int _i = 0; _i < 2; ++_i) \
;         __builtin_amdgcn_global_load_lds((const unsigned*)((const char*)(gbase) + (voff)[_i]), (PG8_LAS unsigned*)(lds + (bufoff) + ldsw + _i * 8192), 16, 0, 0); } while (0)
; #define PG8_LDA(dst, b, h) do { _Pragma("unroll") for (int m = 0; m < 4; ++m) _Pragma("unroll") for (int k = 0; k < 2; ++k) dst[m][k] = *(const PG8_LAS bf16x8*)(lds + PG8_SA(b, h) + aoff + m * 2048 + k * 1024); } while (0)
; #define PG8_LDB(dst, b, h) do { _Pragma("unroll") for (int n = 0; n < 2; ++n) _Pragma("unroll") for (int k = 0; k < 2; ++k) dst[n][k] = *(const PG8_LAS bf16x8*)(lds + PG8_SB(b, h) + boff + n * 2048 + k * 1024); } while (0)
; #define PG8_MMA(ai, bj, At, Bt) do { __builtin_amdgcn_s_setprio(1); _Pragma("unroll") for (int m = 0; m < 4; ++m) _Pragma("unroll") for (int n = 0; n < 2; ++n) _Pragma("unroll") for (int k = 0; k < 2; ++k) \
;         acc[ai][bj][m][n] = __builtin_amdgcn_mfma_f32_16x16x32_bf16(Bt[n][k], At[m][k], acc[ai][bj][m][n], 0, 0, 0); __builtin_amdgcn_s_setprio(0); } while (0)
; #define PG8_WAIT_V(n) asm volatile("s_waitcnt vmcnt(" #n ")" ::: "memory")
; #define PG8_WAIT_L(n) asm volatile("s_waitcnt lgkmcnt(" #n ")" ::: "memory")
; #define PG8_BAR __builtin_amdgcn_s_barrier()
; #define PG8_SCHED __builtin_amdgcn_sched_barrier(0)
; template <class Epi, class Sched, bool ALIGN_EPI = false, bool SP2 = false>
; __device__ __forceinline__ void gemm_phase(PG8_LAS unsigned char* lds, const Gemm g, const Sched S, const Epi E, const int tid) {
;     ...
;             PG8_LDB(B0, 0, 0); PG8_LDB(B1, 0, 1); PG8_SCHED; PG8_LDA(At, 0, 0); PG8_STAGE(PG8_SA(1, 1), a1 + hstepA, voffA);
;             PG8_WAIT_V(8); PG8_WAIT_L(0); PG8_BAR; PG8_MMA(0, 0, At, B0); PG8_MMA(0, 1, At, B1); PG8_BAR; PG8_SCHED;
;             PG8_LDA(At, 0, 1); PG8_STAGE(PG8_SB(0, 0), b2, voffB); PG8_STAGE(PG8_SB(0, 1), b2 + hstepB, voffB); PG8_STAGE(PG8_SA(0, 0), a2, voffA);
;             PG8_WAIT_V(8); PG8_WAIT_L(0); PG8_BAR; PG8_MMA(1, 0, At, B0); PG8_MMA(1, 1, At, B1); PG8_BAR; PG8_SCHED;
.LBB0_886:
	v_add_u32_e32 v162, s66, v149
	v_add_u32_e32 v178, s67, v149
	ds_read_b128 v[136:139], v162
	ds_read_b128 v[154:157], v162 offset:1024
	ds_read_b128 v[158:161], v162 offset:2048
	ds_read_b128 v[162:165], v162 offset:3072
	ds_read_b128 v[166:169], v178
	ds_read_b128 v[170:173], v178 offset:1024
	ds_read_b128 v[174:177], v178 offset:2048
	ds_read_b128 v[178:181], v178 offset:3072
	s_add_u32 s46, s48, 0xfffc0080
	s_addc_u32 s47, s49, -1
	s_cmp_eq_u32 s75, 12
	s_cselect_b32 s51, s31, s47
	s_cselect_b32 s50, s39, s46
	s_cselect_b32 s47, s29, s74
	s_cselect_b32 s46, s41, s69
	s_add_i32 m0, s56, 0xc000
	ds_read_b128 v[182:185], v153
	ds_read_b128 v[188:191], v153 offset:1024
	ds_read_b128 v[192:195], v153 offset:2048
	ds_read_b128 v[196:199], v153 offset:3072
	ds_read_b128 v[200:203], v153 offset:4096
	ds_read_b128 v[204:207], v153 offset:5120
	ds_read_b128 v[208:211], v153 offset:6144
	ds_read_b128 v[212:215], v153 offset:7168
	global_load_lds_dwordx4 v128, s[48:49]
	s_add_i32 m0, s56, 0xe000
	s_nop 0
	global_load_lds_dwordx4 v130, s[48:49]
	s_waitcnt vmcnt(8)
	s_waitcnt lgkmcnt(0)
	s_barrier
	s_waitcnt lgkmcnt(0)
	v_mfma_f32_16x16x32_bf16 v[112:115], v[136:139], v[182:185], v[112:115]
	v_mfma_f32_16x16x32_bf16 v[120:123], v[158:161], v[182:185], v[120:123]
	v_mfma_f32_16x16x32_bf16 v[96:99], v[136:139], v[192:195], v[96:99]
	v_mfma_f32_16x16x32_bf16 v[104:107], v[158:161], v[192:195], v[104:107]
	v_mfma_f32_16x16x32_bf16 v[80:83], v[136:139], v[200:203], v[80:83]
	v_mfma_f32_16x16x32_bf16 v[88:91], v[158:161], v[200:203], v[88:91]
	v_mfma_f32_16x16x32_bf16 v[64:67], v[136:139], v[208:211], v[64:67]
	v_mfma_f32_16x16x32_bf16 v[72:75], v[158:161], v[208:211], v[72:75]
	v_mfma_f32_16x16x32_bf16 v[112:115], v[154:157], v[188:191], v[112:115]
	v_mfma_f32_16x16x32_bf16 v[120:123], v[162:165], v[188:191], v[120:123]
	v_mfma_f32_16x16x32_bf16 v[96:99], v[154:157], v[196:199], v[96:99]
	v_mfma_f32_16x16x32_bf16 v[104:107], v[162:165], v[196:199], v[104:107]
	v_mfma_f32_16x16x32_bf16 v[80:83], v[154:157], v[204:207], v[80:83]
	v_mfma_f32_16x16x32_bf16 v[88:91], v[162:165], v[204:207], v[88:91]
	v_mfma_f32_16x16x32_bf16 v[64:67], v[154:157], v[212:215], v[64:67]
	v_mfma_f32_16x16x32_bf16 v[72:75], v[162:165], v[212:215], v[72:75]
	v_mfma_f32_16x16x32_bf16 v[116:119], v[166:169], v[182:185], v[116:119]
	v_mfma_f32_16x16x32_bf16 v[124:127], v[174:177], v[182:185], v[124:127]
	v_mfma_f32_16x16x32_bf16 v[100:103], v[166:169], v[192:195], v[100:103]
	v_mfma_f32_16x16x32_bf16 v[108:111], v[174:177], v[192:195], v[108:111]
	v_mfma_f32_16x16x32_bf16 v[84:87], v[166:169], v[200:203], v[84:87]
	v_mfma_f32_16x16x32_bf16 v[92:95], v[174:177], v[200:203], v[92:95]
	v_mfma_f32_16x16x32_bf16 v[68:71], v[166:169], v[208:211], v[68:71]
	v_mfma_f32_16x16x32_bf16 v[76:79], v[174:177], v[208:211], v[76:79]
	v_mfma_f32_16x16x32_bf16 v[116:119], v[170:173], v[188:191], v[116:119]
	v_mfma_f32_16x16x32_bf16 v[124:127], v[178:181], v[188:191], v[124:127]
	v_mfma_f32_16x16x32_bf16 v[100:103], v[170:173], v[196:199], v[100:103]
	v_mfma_f32_16x16x32_bf16 v[108:111], v[178:181], v[196:199], v[108:111]
	v_mfma_f32_16x16x32_bf16 v[84:87], v[170:173], v[204:207], v[84:87]
	v_mfma_f32_16x16x32_bf16 v[92:95], v[178:181], v[204:207], v[92:95]
	v_mfma_f32_16x16x32_bf16 v[68:71], v[170:173], v[212:215], v[68:71]
	v_mfma_f32_16x16x32_bf16 v[76:79], v[178:181], v[212:215], v[76:79]
	s_barrier
	s_add_u32 s98, s46, 0x80
	s_addc_u32 s99, s47, 0
	s_add_u32 s100, s50, 0x80
	s_addc_u32 s101, s51, 0
	s_add_i32 s70, s66, s53
	s_mov_b32 m0, s70
	ds_read_b128 v[182:185], v153 offset:16384
	ds_read_b128 v[188:191], v153 offset:17408
	ds_read_b128 v[192:195], v153 offset:18432
	ds_read_b128 v[196:199], v153 offset:19456
	ds_read_b128 v[200:203], v153 offset:20480
	ds_read_b128 v[204:207], v153 offset:21504
	ds_read_b128 v[208:211], v153 offset:22528
	ds_read_b128 v[212:215], v153 offset:23552
	global_load_lds_dwordx4 v142, s[46:47]
	s_add_i32 m0, s70, 0x2000
	s_add_u32 s76, s46, 0x40000
	s_addc_u32 s77, s47, 0
	s_add_i32 s70, s67, s53
	global_load_lds_dwordx4 v146, s[46:47]
	s_mov_b32 m0, s70
	s_nop 0
	global_load_lds_dwordx4 v142, s[76:77]
	s_add_i32 m0, s70, 0x2000
	s_nop 0
	global_load_lds_dwordx4 v146, s[76:77]
	s_mov_b32 m0, s56
	s_nop 0
	global_load_lds_dwordx4 v140, s[50:51]
	s_mov_b32 m0, s57
	s_nop 0
	global_load_lds_dwordx4 v144, s[50:51]
	s_waitcnt vmcnt(8)
	s_waitcnt lgkmcnt(0)
	s_barrier
	s_waitcnt lgkmcnt(0)
	v_mfma_f32_16x16x32_bf16 v[48:51], v[136:139], v[182:185], v[48:51]
	v_mfma_f32_16x16x32_bf16 v[56:59], v[158:161], v[182:185], v[56:59]
	v_mfma_f32_16x16x32_bf16 v[16:19], v[136:139], v[192:195], v[16:19]
	v_mfma_f32_16x16x32_bf16 v[24:27], v[158:161], v[192:195], v[24:27]
	v_mfma_f32_16x16x32_bf16 v[32:35], v[136:139], v[200:203], v[32:35]
	v_mfma_f32_16x16x32_bf16 v[40:43], v[158:161], v[200:203], v[40:43]
	v_mfma_f32_16x16x32_bf16 v[0:3], v[136:139], v[208:211], v[0:3]
	v_mfma_f32_16x16x32_bf16 v[8:11], v[158:161], v[208:211], v[8:11]
	v_mfma_f32_16x16x32_bf16 v[48:51], v[154:157], v[188:191], v[48:51]
	v_mfma_f32_16x16x32_bf16 v[56:59], v[162:165], v[188:191], v[56:59]
	v_mfma_f32_16x16x32_bf16 v[16:19], v[154:157], v[196:199], v[16:19]
	v_mfma_f32_16x16x32_bf16 v[24:27], v[162:165], v[196:199], v[24:27]
	v_mfma_f32_16x16x32_bf16 v[32:35], v[154:157], v[204:207], v[32:35]
	v_mfma_f32_16x16x32_bf16 v[40:43], v[162:165], v[204:207], v[40:43]
	v_mfma_f32_16x16x32_bf16 v[0:3], v[154:157], v[212:215], v[0:3]
	v_mfma_f32_16x16x32_bf16 v[8:11], v[162:165], v[212:215], v[8:11]
	v_mfma_f32_16x16x32_bf16 v[52:55], v[166:169], v[182:185], v[52:55]
	v_mfma_f32_16x16x32_bf16 v[60:63], v[174:177], v[182:185], v[60:63]
	v_mfma_f32_16x16x32_bf16 v[20:23], v[166:169], v[192:195], v[20:23]
	v_mfma_f32_16x16x32_bf16 v[28:31], v[174:177], v[192:195], v[28:31]
	v_mfma_f32_16x16x32_bf16 v[36:39], v[166:169], v[200:203], v[36:39]
	v_mfma_f32_16x16x32_bf16 v[44:47], v[174:177], v[200:203], v[44:47]
	v_mfma_f32_16x16x32_bf16 v[4:7], v[166:169], v[208:211], v[4:7]
	v_mfma_f32_16x16x32_bf16 v[12:15], v[174:177], v[208:211], v[12:15]
	v_mfma_f32_16x16x32_bf16 v[52:55], v[170:173], v[188:191], v[52:55]
	v_mfma_f32_16x16x32_bf16 v[60:63], v[178:181], v[188:191], v[60:63]
	v_mfma_f32_16x16x32_bf16 v[20:23], v[170:173], v[196:199], v[20:23]
	v_mfma_f32_16x16x32_bf16 v[28:31], v[178:181], v[196:199], v[28:31]
	v_mfma_f32_16x16x32_bf16 v[36:39], v[170:173], v[204:207], v[36:39]
	v_mfma_f32_16x16x32_bf16 v[44:47], v[178:181], v[204:207], v[44:47]
	v_mfma_f32_16x16x32_bf16 v[4:7], v[170:173], v[212:215], v[4:7]
	v_mfma_f32_16x16x32_bf16 v[12:15], v[178:181], v[212:215], v[12:15]
	s_barrier
; #define PG8_STAGE(bufoff, gbase, voff) do { _Pragma("unroll") for (int _i = 0; _i < 2; ++_i) \
;         __builtin_amdgcn_global_load_lds((const unsigned*)((const char*)(gbase) + (voff)[_i]), (PG8_LAS unsigned*)(lds + (bufoff) + ldsw + _i * 8192), 16, 0, 0); } while (0)
; #define PG8_LDA(dst, b, h) do { _Pragma("unroll") for (int m = 0; m < 4; ++m) _Pragma("unroll") for (int k = 0; k < 2; ++k) dst[m][k] = *(const PG8_LAS bf16x8*)(lds + PG8_SA(b, h) + aoff + m * 2048 + k * 1024); } while (0)
; #define PG8_LDB(dst, b, h) do { _Pragma("unroll") for (int n = 0; n < 2; ++n) _Pragma("unroll") for (int k = 0; k < 2; ++k) dst[n][k] = *(const PG8_LAS bf16x8*)(lds + PG8_SB(b, h) + boff + n * 2048 + k * 1024); } while (0)
; #define PG8_MMA(ai, bj, At, Bt) do { __builtin_amdgcn_s_setprio(1); _Pragma("unroll") for (int m = 0; m < 4; ++m) _Pragma("unroll") for (int n = 0; n < 2; ++n) _Pragma("unroll") for (int k = 0; k < 2; ++k) \
;         acc[ai][bj][m][n] = __builtin_amdgcn_mfma_f32_16x16x32_bf16(Bt[n][k], At[m][k], acc[ai][bj][m][n], 0, 0, 0); __builtin_amdgcn_s_setprio(0); } while (0)
; #define PG8_WAIT_V(n) asm volatile("s_waitcnt vmcnt(" #n ")" ::: "memory")
; #define PG8_WAIT_L(n) asm volatile("s_waitcnt lgkmcnt(" #n ")" ::: "memory")
; #define PG8_BAR __builtin_amdgcn_s_barrier()
; template <class Epi, class Sched, bool ALIGN_EPI = false, bool SP2 = false>
; __device__ __forceinline__ void gemm_phase(PG8_LAS unsigned char* lds, const Gemm g, const Sched S, const Epi E, const int tid) {
;     ...
;         for (int t = 0; t < nt; t += 2) {
;             const bool last = (t == nt - 2);
;             const char* a1 = cA + (size_t)(t + 1) * kstep;
;             const char* a2 = last ? nA : cA + (size_t)(t + 2) * kstep; const char* b2 = last ? nB : cB + (size_t)(t + 2) * kstep;
;             const char* a3 = a2 + kstep; const char* b3 = b2 + kstep;
;     ...
;             PG8_LDB(B0, 1, 0); PG8_LDB(B1, 1, 1); PG8_SCHED; PG8_LDA(At, 1, 0); PG8_STAGE(PG8_SA(0, 1), a2 + hstepA, voffA);
;             PG8_WAIT_V(8); PG8_WAIT_L(0); PG8_BAR; PG8_MMA(0, 0, At, B0); PG8_MMA(0, 1, At, B1); PG8_BAR; PG8_SCHED;
;             PG8_LDA(At, 1, 1); PG8_STAGE(PG8_SB(1, 0), b3, voffB); PG8_STAGE(PG8_SB(1, 1), b3 + hstepB, voffB); PG8_STAGE(PG8_SA(1, 0), a3, voffA);
;             PG8_WAIT_V(8); PG8_WAIT_L(0); PG8_BAR; PG8_MMA(1, 0, At, B0); PG8_MMA(1, 1, At, B1); PG8_BAR; PG8_SCHED;
	s_add_i32 s70, 0, 0x18000
	s_add_i32 s76, 0, 0x1c000
	v_add_u32_e32 v162, s70, v149
	v_add_u32_e32 v178, s76, v149
	ds_read_b128 v[136:139], v162
	ds_read_b128 v[154:157], v162 offset:1024
	ds_read_b128 v[158:161], v162 offset:2048
	ds_read_b128 v[162:165], v162 offset:3072
	ds_read_b128 v[166:169], v178
	ds_read_b128 v[170:173], v178 offset:1024
	ds_read_b128 v[174:177], v178 offset:2048
	ds_read_b128 v[178:181], v178 offset:3072
	s_add_u32 s50, s50, 0x40000
	s_addc_u32 s51, s51, 0
	s_mov_b32 m0, s58
	ds_read_b128 v[182:185], v153 offset:32768
	ds_read_b128 v[188:191], v153 offset:33792
	ds_read_b128 v[192:195], v153 offset:34816
	ds_read_b128 v[196:199], v153 offset:35840
	ds_read_b128 v[200:203], v153 offset:36864
	ds_read_b128 v[204:207], v153 offset:37888
	ds_read_b128 v[208:211], v153 offset:38912
	ds_read_b128 v[212:215], v153 offset:39936
	global_load_lds_dwordx4 v140, s[50:51]
	s_mov_b32 m0, s59
	s_nop 0
	global_load_lds_dwordx4 v144, s[50:51]
	s_waitcnt vmcnt(8)
	s_waitcnt lgkmcnt(0)
	s_barrier
	s_waitcnt lgkmcnt(0)
	v_mfma_f32_16x16x32_bf16 v[112:115], v[136:139], v[182:185], v[112:115]
	v_mfma_f32_16x16x32_bf16 v[120:123], v[158:161], v[182:185], v[120:123]
	v_mfma_f32_16x16x32_bf16 v[96:99], v[136:139], v[192:195], v[96:99]
	v_mfma_f32_16x16x32_bf16 v[104:107], v[158:161], v[192:195], v[104:107]
	v_mfma_f32_16x16x32_bf16 v[80:83], v[136:139], v[200:203], v[80:83]
	v_mfma_f32_16x16x32_bf16 v[88:91], v[158:161], v[200:203], v[88:91]
	v_mfma_f32_16x16x32_bf16 v[64:67], v[136:139], v[208:211], v[64:67]
	v_mfma_f32_16x16x32_bf16 v[72:75], v[158:161], v[208:211], v[72:75]
	v_mfma_f32_16x16x32_bf16 v[112:115], v[154:157], v[188:191], v[112:115]
	v_mfma_f32_16x16x32_bf16 v[120:123], v[162:165], v[188:191], v[120:123]
	v_mfma_f32_16x16x32_bf16 v[96:99], v[154:157], v[196:199], v[96:99]
	v_mfma_f32_16x16x32_bf16 v[104:107], v[162:165], v[196:199], v[104:107]
	v_mfma_f32_16x16x32_bf16 v[80:83], v[154:157], v[204:207], v[80:83]
	v_mfma_f32_16x16x32_bf16 v[88:91], v[162:165], v[204:207], v[88:91]
	v_mfma_f32_16x16x32_bf16 v[64:67], v[154:157], v[212:215], v[64:67]
	v_mfma_f32_16x16x32_bf16 v[72:75], v[162:165], v[212:215], v[72:75]
	v_mfma_f32_16x16x32_bf16 v[116:119], v[166:169], v[182:185], v[116:119]
	v_mfma_f32_16x16x32_bf16 v[124:127], v[174:177], v[182:185], v[124:127]
	v_mfma_f32_16x16x32_bf16 v[100:103], v[166:169], v[192:195], v[100:103]
	v_mfma_f32_16x16x32_bf16 v[108:111], v[174:177], v[192:195], v[108:111]
	v_mfma_f32_16x16x32_bf16 v[84:87], v[166:169], v[200:203], v[84:87]
	v_mfma_f32_16x16x32_bf16 v[92:95], v[174:177], v[200:203], v[92:95]
	v_mfma_f32_16x16x32_bf16 v[68:71], v[166:169], v[208:211], v[68:71]
	v_mfma_f32_16x16x32_bf16 v[76:79], v[174:177], v[208:211], v[76:79]
	v_mfma_f32_16x16x32_bf16 v[116:119], v[170:173], v[188:191], v[116:119]
	v_mfma_f32_16x16x32_bf16 v[124:127], v[178:181], v[188:191], v[124:127]
	v_mfma_f32_16x16x32_bf16 v[100:103], v[170:173], v[196:199], v[100:103]
	v_mfma_f32_16x16x32_bf16 v[108:111], v[178:181], v[196:199], v[108:111]
	v_mfma_f32_16x16x32_bf16 v[84:87], v[170:173], v[204:207], v[84:87]
	v_mfma_f32_16x16x32_bf16 v[92:95], v[178:181], v[204:207], v[92:95]
	v_mfma_f32_16x16x32_bf16 v[68:71], v[170:173], v[212:215], v[68:71]
	v_mfma_f32_16x16x32_bf16 v[76:79], v[178:181], v[212:215], v[76:79]
	s_barrier
	s_add_i32 s50, s70, s53
	s_mov_b32 m0, s50
	ds_read_b128 v[182:185], v153 offset:49152
	ds_read_b128 v[188:191], v153 offset:50176
	ds_read_b128 v[192:195], v153 offset:51200
	ds_read_b128 v[196:199], v153 offset:52224
	ds_read_b128 v[200:203], v153 offset:53248
	ds_read_b128 v[204:207], v153 offset:54272
	ds_read_b128 v[208:211], v153 offset:55296
	ds_read_b128 v[212:215], v153 offset:56320
	global_load_lds_dwordx4 v142, s[98:99]
	s_add_i32 m0, s50, 0x2000
	s_add_u32 s46, s46, 0x40080
	s_addc_u32 s47, s47, 0
	s_add_i32 s50, s76, s53
	global_load_lds_dwordx4 v146, s[98:99]
	s_mov_b32 m0, s50
	s_nop 0
	global_load_lds_dwordx4 v142, s[46:47]
	s_add_i32 m0, s50, 0x2000
	s_nop 0
	global_load_lds_dwordx4 v146, s[46:47]
	s_mov_b32 m0, s61
	s_nop 0
	global_load_lds_dwordx4 v140, s[100:101]
	s_mov_b32 m0, s62
	s_nop 0
	global_load_lds_dwordx4 v144, s[100:101]
	s_waitcnt vmcnt(8)
	s_waitcnt lgkmcnt(0)
	s_barrier
	s_waitcnt lgkmcnt(0)
	v_mfma_f32_16x16x32_bf16 v[48:51], v[136:139], v[182:185], v[48:51]
	v_mfma_f32_16x16x32_bf16 v[56:59], v[158:161], v[182:185], v[56:59]
	v_mfma_f32_16x16x32_bf16 v[16:19], v[136:139], v[192:195], v[16:19]
	v_mfma_f32_16x16x32_bf16 v[24:27], v[158:161], v[192:195], v[24:27]
	v_mfma_f32_16x16x32_bf16 v[32:35], v[136:139], v[200:203], v[32:35]
	v_mfma_f32_16x16x32_bf16 v[40:43], v[158:161], v[200:203], v[40:43]
	v_mfma_f32_16x16x32_bf16 v[0:3], v[136:139], v[208:211], v[0:3]
	v_mfma_f32_16x16x32_bf16 v[8:11], v[158:161], v[208:211], v[8:11]
	v_mfma_f32_16x16x32_bf16 v[48:51], v[154:157], v[188:191], v[48:51]
	v_mfma_f32_16x16x32_bf16 v[56:59], v[162:165], v[188:191], v[56:59]
	v_mfma_f32_16x16x32_bf16 v[16:19], v[154:157], v[196:199], v[16:19]
	v_mfma_f32_16x16x32_bf16 v[24:27], v[162:165], v[196:199], v[24:27]
	v_mfma_f32_16x16x32_bf16 v[32:35], v[154:157], v[204:207], v[32:35]
	v_mfma_f32_16x16x32_bf16 v[40:43], v[162:165], v[204:207], v[40:43]
	v_mfma_f32_16x16x32_bf16 v[0:3], v[154:157], v[212:215], v[0:3]
	v_mfma_f32_16x16x32_bf16 v[8:11], v[162:165], v[212:215], v[8:11]
	v_mfma_f32_16x16x32_bf16 v[52:55], v[166:169], v[182:185], v[52:55]
	v_mfma_f32_16x16x32_bf16 v[60:63], v[174:177], v[182:185], v[60:63]
	v_mfma_f32_16x16x32_bf16 v[20:23], v[166:169], v[192:195], v[20:23]
	v_mfma_f32_16x16x32_bf16 v[28:31], v[174:177], v[192:195], v[28:31]
	v_mfma_f32_16x16x32_bf16 v[36:39], v[166:169], v[200:203], v[36:39]
	v_mfma_f32_16x16x32_bf16 v[44:47], v[174:177], v[200:203], v[44:47]
	v_mfma_f32_16x16x32_bf16 v[4:7], v[166:169], v[208:211], v[4:7]
	v_mfma_f32_16x16x32_bf16 v[12:15], v[174:177], v[208:211], v[12:15]
	v_mfma_f32_16x16x32_bf16 v[52:55], v[170:173], v[188:191], v[52:55]
	v_mfma_f32_16x16x32_bf16 v[60:63], v[178:181], v[188:191], v[60:63]
	v_mfma_f32_16x16x32_bf16 v[20:23], v[170:173], v[196:199], v[20:23]
	v_mfma_f32_16x16x32_bf16 v[28:31], v[178:181], v[196:199], v[28:31]
	v_mfma_f32_16x16x32_bf16 v[36:39], v[170:173], v[204:207], v[36:39]
	v_mfma_f32_16x16x32_bf16 v[44:47], v[178:181], v[204:207], v[44:47]
	v_mfma_f32_16x16x32_bf16 v[4:7], v[170:173], v[212:215], v[4:7]
	v_mfma_f32_16x16x32_bf16 v[12:15], v[178:181], v[212:215], v[12:15]
	s_barrier
	s_add_i32 s75, s75, 2
	s_add_u32 s48, s48, 0x100
	s_addc_u32 s49, s49, 0
	s_add_u32 s69, s69, 0x100
	s_addc_u32 s74, s74, 0
	s_cmp_gt_u32 s75, 13
	s_cbranch_scc0 .LBB0_886
	s_and_b64 vcc, exec, s[26:27]
	s_cbranch_vccz .LBB0_889
	s_barrier

; #define PG8_STAGE(bufoff, gbase, voff) do { _Pragma("unroll") for (int _i = 0; _i < 2; ++_i) \
;         __builtin_amdgcn_global_load_lds((const unsigned*)((const char*)(gbase) + (voff)[_i]), (PG8_LAS unsigned*)(lds + (bufoff) + ldsw + _i * 8192), 16, 0, 0); } while (0)
; #define PG8_LDA(dst, b, h) do { _Pragma("unroll") for (int m = 0; m < 4; ++m) _Pragma("unroll") for (int k = 0; k < 2; ++k) dst[m][k] = *(const PG8_LAS bf16x8*)(lds + PG8_SA(b, h) + aoff + m * 2048 + k * 1024); } while (0)
; #define PG8_LDB(dst, b, h) do { _Pragma("unroll") for (int n = 0; n < 2; ++n) _Pragma("unroll") for (int k = 0; k < 2; ++k) dst[n][k] = *(const PG8_LAS bf16x8*)(lds + PG8_SB(b, h) + boff + n * 2048 + k * 1024); } while (0)
; #define PG8_MMA(ai, bj, At, Bt) do { __builtin_amdgcn_s_setprio(1); _Pragma("unroll") for (int m = 0; m < 4; ++m) _Pragma("unroll") for (int n = 0; n < 2; ++n) _Pragma("unroll") for (int k = 0; k < 2; ++k) \
;         acc[ai][bj][m][n] = __builtin_amdgcn_mfma_f32_16x16x32_bf16(Bt[n][k], At[m][k], acc[ai][bj][m][n], 0, 0, 0); __builtin_amdgcn_s_setprio(0); } while (0)
; #define PG8_WAIT_V(n) asm volatile("s_waitcnt vmcnt(" #n ")" ::: "memory")
; #define PG8_WAIT_L(n) asm volatile("s_waitcnt lgkmcnt(" #n ")" ::: "memory")
; #define PG8_BAR __builtin_amdgcn_s_barrier()
; #define PG8_SCHED __builtin_amdgcn_sched_barrier(0)
; template <class Epi, class Sched, bool ALIGN_EPI = false, bool SP2 = false>
; __device__ __forceinline__ void gemm_phase(PG8_LAS unsigned char* lds, const Gemm g, const Sched S, const Epi E, const int tid) {
;     ...
;             PG8_LDB(B0, 0, 0); PG8_LDB(B1, 0, 1); PG8_SCHED; PG8_LDA(At, 0, 0); PG8_STAGE(PG8_SA(1, 1), a1 + hstepA, voffA);
;             PG8_WAIT_V(8); PG8_WAIT_L(0); PG8_BAR; PG8_MMA(0, 0, At, B0); PG8_MMA(0, 1, At, B1); PG8_BAR; PG8_SCHED;
;             PG8_LDA(At, 0, 1); PG8_STAGE(PG8_SB(0, 0), b2, voffB); PG8_STAGE(PG8_SB(0, 1), b2 + hstepB, voffB); PG8_STAGE(PG8_SA(0, 0), a2, voffA);
;             PG8_WAIT_V(8); PG8_WAIT_L(0); PG8_BAR; PG8_MMA(1, 0, At, B0); PG8_MMA(1, 1, At, B1); PG8_BAR; PG8_SCHED;
.LBB0_991:
	ds_read_b128 v[144:147], v159
	ds_read_b128 v[148:151], v159 offset:1024
	ds_read_b128 v[162:165], v159 offset:2048
	ds_read_b128 v[166:169], v159 offset:3072
	ds_read_b128 v[170:173], v160
	ds_read_b128 v[174:177], v160 offset:1024
	ds_read_b128 v[178:181], v160 offset:2048
	ds_read_b128 v[182:185], v160 offset:3072
	s_add_u32 s34, s30, 0xfffc0080
	s_addc_u32 s35, s31, -1
	s_cmp_eq_u32 s65, 12
	s_cselect_b32 s37, s23, s35
	s_cselect_b32 s36, s61, s34
	s_cselect_b32 s35, s21, s64
	s_cselect_b32 s34, s62, s63
	s_add_i32 m0, s29, 0xc000
	ds_read_b128 v[188:191], v161
	ds_read_b128 v[192:195], v161 offset:1024
	ds_read_b128 v[196:199], v161 offset:2048
	ds_read_b128 v[200:203], v161 offset:3072
	ds_read_b128 v[204:207], v161 offset:4096
	ds_read_b128 v[208:211], v161 offset:5120
	ds_read_b128 v[212:215], v161 offset:6144
	ds_read_b128 v[216:219], v161 offset:7168
	global_load_lds_dwordx4 v136, s[30:31]
	s_add_i32 m0, s29, 0xe000
	s_nop 0
	global_load_lds_dwordx4 v138, s[30:31]
	s_waitcnt vmcnt(8)
	s_waitcnt lgkmcnt(0)
	s_barrier
	s_waitcnt lgkmcnt(0)
	v_mfma_f32_16x16x32_bf16 v[124:127], v[144:147], v[188:191], v[124:127]
	v_mfma_f32_16x16x32_bf16 v[120:123], v[162:165], v[188:191], v[120:123]
	v_mfma_f32_16x16x32_bf16 v[108:111], v[144:147], v[196:199], v[108:111]
	v_mfma_f32_16x16x32_bf16 v[104:107], v[162:165], v[196:199], v[104:107]
	v_mfma_f32_16x16x32_bf16 v[92:95], v[144:147], v[204:207], v[92:95]
	v_mfma_f32_16x16x32_bf16 v[88:91], v[162:165], v[204:207], v[88:91]
	v_mfma_f32_16x16x32_bf16 v[76:79], v[144:147], v[212:215], v[76:79]
	v_mfma_f32_16x16x32_bf16 v[72:75], v[162:165], v[212:215], v[72:75]
	v_mfma_f32_16x16x32_bf16 v[124:127], v[148:151], v[192:195], v[124:127]
	v_mfma_f32_16x16x32_bf16 v[120:123], v[166:169], v[192:195], v[120:123]
	v_mfma_f32_16x16x32_bf16 v[108:111], v[148:151], v[200:203], v[108:111]
	v_mfma_f32_16x16x32_bf16 v[104:107], v[166:169], v[200:203], v[104:107]
	v_mfma_f32_16x16x32_bf16 v[92:95], v[148:151], v[208:211], v[92:95]
	v_mfma_f32_16x16x32_bf16 v[88:91], v[166:169], v[208:211], v[88:91]
	v_mfma_f32_16x16x32_bf16 v[76:79], v[148:151], v[216:219], v[76:79]
	v_mfma_f32_16x16x32_bf16 v[72:75], v[166:169], v[216:219], v[72:75]
	v_mfma_f32_16x16x32_bf16 v[116:119], v[170:173], v[188:191], v[116:119]
	v_mfma_f32_16x16x32_bf16 v[112:115], v[178:181], v[188:191], v[112:115]
	v_mfma_f32_16x16x32_bf16 v[100:103], v[170:173], v[196:199], v[100:103]
	v_mfma_f32_16x16x32_bf16 v[96:99], v[178:181], v[196:199], v[96:99]
	v_mfma_f32_16x16x32_bf16 v[84:87], v[170:173], v[204:207], v[84:87]
	v_mfma_f32_16x16x32_bf16 v[80:83], v[178:181], v[204:207], v[80:83]
	v_mfma_f32_16x16x32_bf16 v[68:71], v[170:173], v[212:215], v[68:71]
	v_mfma_f32_16x16x32_bf16 v[64:67], v[178:181], v[212:215], v[64:67]
	v_mfma_f32_16x16x32_bf16 v[116:119], v[174:177], v[192:195], v[116:119]
	v_mfma_f32_16x16x32_bf16 v[112:115], v[182:185], v[192:195], v[112:115]
	v_mfma_f32_16x16x32_bf16 v[100:103], v[174:177], v[200:203], v[100:103]
	v_mfma_f32_16x16x32_bf16 v[96:99], v[182:185], v[200:203], v[96:99]
	v_mfma_f32_16x16x32_bf16 v[84:87], v[174:177], v[208:211], v[84:87]
	v_mfma_f32_16x16x32_bf16 v[80:83], v[182:185], v[208:211], v[80:83]
	v_mfma_f32_16x16x32_bf16 v[68:71], v[174:177], v[216:219], v[68:71]
	v_mfma_f32_16x16x32_bf16 v[64:67], v[182:185], v[216:219], v[64:67]
	s_barrier
	s_add_u32 s98, s34, 0x80
	s_addc_u32 s99, s35, 0
	s_add_u32 s100, s36, 0x80
	s_addc_u32 s101, s37, 0
	s_add_i32 s66, s55, s19
	s_mov_b32 m0, s66
	ds_read_b128 v[188:191], v161 offset:16384
	ds_read_b128 v[192:195], v161 offset:17408
	ds_read_b128 v[196:199], v161 offset:18432
	ds_read_b128 v[200:203], v161 offset:19456
	ds_read_b128 v[204:207], v161 offset:20480
	ds_read_b128 v[208:211], v161 offset:21504
	ds_read_b128 v[212:215], v161 offset:22528
	ds_read_b128 v[216:219], v161 offset:23552
	global_load_lds_dwordx4 v132, s[34:35]
	s_add_i32 m0, s66, 0x2000
	s_add_u32 s66, s34, 0x40000
	s_addc_u32 s67, s35, 0
	s_add_i32 s69, s56, s19
	global_load_lds_dwordx4 v128, s[34:35]
	s_mov_b32 m0, s69
	s_nop 0
	global_load_lds_dwordx4 v132, s[66:67]
	s_add_i32 m0, s69, 0x2000
	s_nop 0
	global_load_lds_dwordx4 v128, s[66:67]
	s_mov_b32 m0, s29
	s_nop 0
	global_load_lds_dwordx4 v134, s[36:37]
	s_mov_b32 m0, s50
	s_nop 0
	global_load_lds_dwordx4 v130, s[36:37]
	s_waitcnt vmcnt(8)
	s_waitcnt lgkmcnt(0)
	s_barrier
	s_waitcnt lgkmcnt(0)
	v_mfma_f32_16x16x32_bf16 v[60:63], v[144:147], v[188:191], v[60:63]
	v_mfma_f32_16x16x32_bf16 v[56:59], v[162:165], v[188:191], v[56:59]
	v_mfma_f32_16x16x32_bf16 v[44:47], v[144:147], v[196:199], v[44:47]
	v_mfma_f32_16x16x32_bf16 v[40:43], v[162:165], v[196:199], v[40:43]
	v_mfma_f32_16x16x32_bf16 v[28:31], v[144:147], v[204:207], v[28:31]
	v_mfma_f32_16x16x32_bf16 v[24:27], v[162:165], v[204:207], v[24:27]
	v_mfma_f32_16x16x32_bf16 v[12:15], v[144:147], v[212:215], v[12:15]
	v_mfma_f32_16x16x32_bf16 v[8:11], v[162:165], v[212:215], v[8:11]
	v_mfma_f32_16x16x32_bf16 v[60:63], v[148:151], v[192:195], v[60:63]
	v_mfma_f32_16x16x32_bf16 v[56:59], v[166:169], v[192:195], v[56:59]
	v_mfma_f32_16x16x32_bf16 v[44:47], v[148:151], v[200:203], v[44:47]
	v_mfma_f32_16x16x32_bf16 v[40:43], v[166:169], v[200:203], v[40:43]
	v_mfma_f32_16x16x32_bf16 v[28:31], v[148:151], v[208:211], v[28:31]
	v_mfma_f32_16x16x32_bf16 v[24:27], v[166:169], v[208:211], v[24:27]
	v_mfma_f32_16x16x32_bf16 v[12:15], v[148:151], v[216:219], v[12:15]
	v_mfma_f32_16x16x32_bf16 v[8:11], v[166:169], v[216:219], v[8:11]
	v_mfma_f32_16x16x32_bf16 v[52:55], v[170:173], v[188:191], v[52:55]
	v_mfma_f32_16x16x32_bf16 v[48:51], v[178:181], v[188:191], v[48:51]
	v_mfma_f32_16x16x32_bf16 v[36:39], v[170:173], v[196:199], v[36:39]
	v_mfma_f32_16x16x32_bf16 v[32:35], v[178:181], v[196:199], v[32:35]
	v_mfma_f32_16x16x32_bf16 v[20:23], v[170:173], v[204:207], v[20:23]
	v_mfma_f32_16x16x32_bf16 v[16:19], v[178:181], v[204:207], v[16:19]
	v_mfma_f32_16x16x32_bf16 v[4:7], v[170:173], v[212:215], v[4:7]
	v_mfma_f32_16x16x32_bf16 v[0:3], v[178:181], v[212:215], v[0:3]
	v_mfma_f32_16x16x32_bf16 v[52:55], v[174:177], v[192:195], v[52:55]
	v_mfma_f32_16x16x32_bf16 v[48:51], v[182:185], v[192:195], v[48:51]
	v_mfma_f32_16x16x32_bf16 v[36:39], v[174:177], v[200:203], v[36:39]
	v_mfma_f32_16x16x32_bf16 v[32:35], v[182:185], v[200:203], v[32:35]
	v_mfma_f32_16x16x32_bf16 v[20:23], v[174:177], v[208:211], v[20:23]
	v_mfma_f32_16x16x32_bf16 v[16:19], v[182:185], v[208:211], v[16:19]
	v_mfma_f32_16x16x32_bf16 v[4:7], v[174:177], v[216:219], v[4:7]
	v_mfma_f32_16x16x32_bf16 v[0:3], v[182:185], v[216:219], v[0:3]
	s_barrier
; #define PG8_STAGE(bufoff, gbase, voff) do { _Pragma("unroll") for (int _i = 0; _i < 2; ++_i) \
;         __builtin_amdgcn_global_load_lds((const unsigned*)((const char*)(gbase) + (voff)[_i]), (PG8_LAS unsigned*)(lds + (bufoff) + ldsw + _i * 8192), 16, 0, 0); } while (0)
; #define PG8_LDA(dst, b, h) do { _Pragma("unroll") for (int m = 0; m < 4; ++m) _Pragma("unroll") for (int k = 0; k < 2; ++k) dst[m][k] = *(const PG8_LAS bf16x8*)(lds + PG8_SA(b, h) + aoff + m * 2048 + k * 1024); } while (0)
; #define PG8_LDB(dst, b, h) do { _Pragma("unroll") for (int n = 0; n < 2; ++n) _Pragma("unroll") for (int k = 0; k < 2; ++k) dst[n][k] = *(const PG8_LAS bf16x8*)(lds + PG8_SB(b, h) + boff + n * 2048 + k * 1024); } while (0)
; #define PG8_MMA(ai, bj, At, Bt) do { __builtin_amdgcn_s_setprio(1); _Pragma("unroll") for (int m = 0; m < 4; ++m) _Pragma("unroll") for (int n = 0; n < 2; ++n) _Pragma("unroll") for (int k = 0; k < 2; ++k) \
;         acc[ai][bj][m][n] = __builtin_amdgcn_mfma_f32_16x16x32_bf16(Bt[n][k], At[m][k], acc[ai][bj][m][n], 0, 0, 0); __builtin_amdgcn_s_setprio(0); } while (0)
; #define PG8_WAIT_V(n) asm volatile("s_waitcnt vmcnt(" #n ")" ::: "memory")
; #define PG8_WAIT_L(n) asm volatile("s_waitcnt lgkmcnt(" #n ")" ::: "memory")
; #define PG8_BAR __builtin_amdgcn_s_barrier()
; #define PG8_SCHED __builtin_amdgcn_sched_barrier(0)
; template <class Epi, class Sched, bool ALIGN_EPI = false, bool SP2 = false>
; __device__ __forceinline__ void gemm_phase(PG8_LAS unsigned char* lds, const Gemm g, const Sched S, const Epi E, const int tid) {
;     ...
;             PG8_LDB(B0, 1, 0); PG8_LDB(B1, 1, 1); PG8_SCHED; PG8_LDA(At, 1, 0); PG8_STAGE(PG8_SA(0, 1), a2 + hstepA, voffA);
;             PG8_WAIT_V(8); PG8_WAIT_L(0); PG8_BAR; PG8_MMA(0, 0, At, B0); PG8_MMA(0, 1, At, B1); PG8_BAR; PG8_SCHED;
;             PG8_LDA(At, 1, 1); PG8_STAGE(PG8_SB(1, 0), b3, voffB); PG8_STAGE(PG8_SB(1, 1), b3 + hstepB, voffB); PG8_STAGE(PG8_SA(1, 0), a3, voffA);
;             PG8_WAIT_V(8); PG8_WAIT_L(0); PG8_BAR; PG8_MMA(1, 0, At, B0); PG8_MMA(1, 1, At, B1); PG8_BAR; PG8_SCHED;
	s_add_i32 s66, 0, 0x18000
	s_add_i32 s67, 0, 0x1c000
	v_add_u32_e32 v166, s66, v156
	v_add_u32_e32 v182, s67, v156
	ds_read_b128 v[144:147], v166
	ds_read_b128 v[148:151], v166 offset:1024
	ds_read_b128 v[162:165], v166 offset:2048
	ds_read_b128 v[166:169], v166 offset:3072
	ds_read_b128 v[170:173], v182
	ds_read_b128 v[174:177], v182 offset:1024
	ds_read_b128 v[178:181], v182 offset:2048
	ds_read_b128 v[182:185], v182 offset:3072
	s_add_u32 s36, s36, 0x40000
	s_addc_u32 s37, s37, 0
	s_mov_b32 m0, s51
	ds_read_b128 v[188:191], v161 offset:32768
	ds_read_b128 v[192:195], v161 offset:33792
	ds_read_b128 v[196:199], v161 offset:34816
	ds_read_b128 v[200:203], v161 offset:35840
	ds_read_b128 v[204:207], v161 offset:36864
	ds_read_b128 v[208:211], v161 offset:37888
	ds_read_b128 v[212:215], v161 offset:38912
	ds_read_b128 v[216:219], v161 offset:39936
	global_load_lds_dwordx4 v134, s[36:37]
	s_mov_b32 m0, s52
	s_nop 0
	global_load_lds_dwordx4 v130, s[36:37]
	s_waitcnt vmcnt(8)
	s_waitcnt lgkmcnt(0)
	s_barrier
	s_waitcnt lgkmcnt(0)
	v_mfma_f32_16x16x32_bf16 v[124:127], v[144:147], v[188:191], v[124:127]
	v_mfma_f32_16x16x32_bf16 v[120:123], v[162:165], v[188:191], v[120:123]
	v_mfma_f32_16x16x32_bf16 v[108:111], v[144:147], v[196:199], v[108:111]
	v_mfma_f32_16x16x32_bf16 v[104:107], v[162:165], v[196:199], v[104:107]
	v_mfma_f32_16x16x32_bf16 v[92:95], v[144:147], v[204:207], v[92:95]
	v_mfma_f32_16x16x32_bf16 v[88:91], v[162:165], v[204:207], v[88:91]
	v_mfma_f32_16x16x32_bf16 v[76:79], v[144:147], v[212:215], v[76:79]
	v_mfma_f32_16x16x32_bf16 v[72:75], v[162:165], v[212:215], v[72:75]
	v_mfma_f32_16x16x32_bf16 v[124:127], v[148:151], v[192:195], v[124:127]
	v_mfma_f32_16x16x32_bf16 v[120:123], v[166:169], v[192:195], v[120:123]
	v_mfma_f32_16x16x32_bf16 v[108:111], v[148:151], v[200:203], v[108:111]
	v_mfma_f32_16x16x32_bf16 v[104:107], v[166:169], v[200:203], v[104:107]
	v_mfma_f32_16x16x32_bf16 v[92:95], v[148:151], v[208:211], v[92:95]
	v_mfma_f32_16x16x32_bf16 v[88:91], v[166:169], v[208:211], v[88:91]
	v_mfma_f32_16x16x32_bf16 v[76:79], v[148:151], v[216:219], v[76:79]
	v_mfma_f32_16x16x32_bf16 v[72:75], v[166:169], v[216:219], v[72:75]
	v_mfma_f32_16x16x32_bf16 v[116:119], v[170:173], v[188:191], v[116:119]
	v_mfma_f32_16x16x32_bf16 v[112:115], v[178:181], v[188:191], v[112:115]
	v_mfma_f32_16x16x32_bf16 v[100:103], v[170:173], v[196:199], v[100:103]
	v_mfma_f32_16x16x32_bf16 v[96:99], v[178:181], v[196:199], v[96:99]
	v_mfma_f32_16x16x32_bf16 v[84:87], v[170:173], v[204:207], v[84:87]
	v_mfma_f32_16x16x32_bf16 v[80:83], v[178:181], v[204:207], v[80:83]
	v_mfma_f32_16x16x32_bf16 v[68:71], v[170:173], v[212:215], v[68:71]
	v_mfma_f32_16x16x32_bf16 v[64:67], v[178:181], v[212:215], v[64:67]
	v_mfma_f32_16x16x32_bf16 v[116:119], v[174:177], v[192:195], v[116:119]
	v_mfma_f32_16x16x32_bf16 v[112:115], v[182:185], v[192:195], v[112:115]
	v_mfma_f32_16x16x32_bf16 v[100:103], v[174:177], v[200:203], v[100:103]
	v_mfma_f32_16x16x32_bf16 v[96:99], v[182:185], v[200:203], v[96:99]
	v_mfma_f32_16x16x32_bf16 v[84:87], v[174:177], v[208:211], v[84:87]
	v_mfma_f32_16x16x32_bf16 v[80:83], v[182:185], v[208:211], v[80:83]
	v_mfma_f32_16x16x32_bf16 v[68:71], v[174:177], v[216:219], v[68:71]
	v_mfma_f32_16x16x32_bf16 v[64:67], v[182:185], v[216:219], v[64:67]
	s_barrier
	s_add_i32 s36, s66, s19
	s_mov_b32 m0, s36
	ds_read_b128 v[188:191], v161 offset:49152
	ds_read_b128 v[192:195], v161 offset:50176
	ds_read_b128 v[196:199], v161 offset:51200
	ds_read_b128 v[200:203], v161 offset:52224
	ds_read_b128 v[204:207], v161 offset:53248
	ds_read_b128 v[208:211], v161 offset:54272
	ds_read_b128 v[212:215], v161 offset:55296
	ds_read_b128 v[216:219], v161 offset:56320
	global_load_lds_dwordx4 v132, s[98:99]
	s_add_i32 m0, s36, 0x2000
	s_add_u32 s34, s34, 0x40080
	s_addc_u32 s35, s35, 0
	s_add_i32 s36, s67, s19
	global_load_lds_dwordx4 v128, s[98:99]
	s_mov_b32 m0, s36
	s_nop 0
	global_load_lds_dwordx4 v132, s[34:35]
	s_add_i32 m0, s36, 0x2000
	s_nop 0
	global_load_lds_dwordx4 v128, s[34:35]
	s_mov_b32 m0, s53
	s_nop 0
	global_load_lds_dwordx4 v134, s[100:101]
	s_mov_b32 m0, s54
	s_nop 0
	global_load_lds_dwordx4 v130, s[100:101]
	s_waitcnt vmcnt(8)
	s_waitcnt lgkmcnt(0)
	s_barrier
	s_waitcnt lgkmcnt(0)
	v_mfma_f32_16x16x32_bf16 v[60:63], v[144:147], v[188:191], v[60:63]
	v_mfma_f32_16x16x32_bf16 v[56:59], v[162:165], v[188:191], v[56:59]
	v_mfma_f32_16x16x32_bf16 v[44:47], v[144:147], v[196:199], v[44:47]
	v_mfma_f32_16x16x32_bf16 v[40:43], v[162:165], v[196:199], v[40:43]
	v_mfma_f32_16x16x32_bf16 v[28:31], v[144:147], v[204:207], v[28:31]
	v_mfma_f32_16x16x32_bf16 v[24:27], v[162:165], v[204:207], v[24:27]
	v_mfma_f32_16x16x32_bf16 v[12:15], v[144:147], v[212:215], v[12:15]
	v_mfma_f32_16x16x32_bf16 v[8:11], v[162:165], v[212:215], v[8:11]
	v_mfma_f32_16x16x32_bf16 v[60:63], v[148:151], v[192:195], v[60:63]
	v_mfma_f32_16x16x32_bf16 v[56:59], v[166:169], v[192:195], v[56:59]
	v_mfma_f32_16x16x32_bf16 v[44:47], v[148:151], v[200:203], v[44:47]
	v_mfma_f32_16x16x32_bf16 v[40:43], v[166:169], v[200:203], v[40:43]
	v_mfma_f32_16x16x32_bf16 v[28:31], v[148:151], v[208:211], v[28:31]
	v_mfma_f32_16x16x32_bf16 v[24:27], v[166:169], v[208:211], v[24:27]
	v_mfma_f32_16x16x32_bf16 v[12:15], v[148:151], v[216:219], v[12:15]
	v_mfma_f32_16x16x32_bf16 v[8:11], v[166:169], v[216:219], v[8:11]
	v_mfma_f32_16x16x32_bf16 v[52:55], v[170:173], v[188:191], v[52:55]
	v_mfma_f32_16x16x32_bf16 v[48:51], v[178:181], v[188:191], v[48:51]
	v_mfma_f32_16x16x32_bf16 v[36:39], v[170:173], v[196:199], v[36:39]
	v_mfma_f32_16x16x32_bf16 v[32:35], v[178:181], v[196:199], v[32:35]
	v_mfma_f32_16x16x32_bf16 v[20:23], v[170:173], v[204:207], v[20:23]
	v_mfma_f32_16x16x32_bf16 v[16:19], v[178:181], v[204:207], v[16:19]
	v_mfma_f32_16x16x32_bf16 v[4:7], v[170:173], v[212:215], v[4:7]
	v_mfma_f32_16x16x32_bf16 v[0:3], v[178:181], v[212:215], v[0:3]
	v_mfma_f32_16x16x32_bf16 v[52:55], v[174:177], v[192:195], v[52:55]
	v_mfma_f32_16x16x32_bf16 v[48:51], v[182:185], v[192:195], v[48:51]
	v_mfma_f32_16x16x32_bf16 v[36:39], v[174:177], v[200:203], v[36:39]
	v_mfma_f32_16x16x32_bf16 v[32:35], v[182:185], v[200:203], v[32:35]
	v_mfma_f32_16x16x32_bf16 v[20:23], v[174:177], v[208:211], v[20:23]
	v_mfma_f32_16x16x32_bf16 v[16:19], v[182:185], v[208:211], v[16:19]
	v_mfma_f32_16x16x32_bf16 v[4:7], v[174:177], v[216:219], v[4:7]
	v_mfma_f32_16x16x32_bf16 v[0:3], v[182:185], v[216:219], v[0:3]
	s_barrier
	s_add_i32 s65, s65, 2
	s_add_u32 s30, s30, 0x100
	s_addc_u32 s31, s31, 0
	s_add_u32 s63, s63, 0x100
	s_addc_u32 s64, s64, 0
	s_cmp_gt_u32 s65, 13
	s_cbranch_scc0 .LBB0_991
	s_and_b64 vcc, exec, s[16:17]
	s_cbranch_vccz .LBB0_994
	s_barrier

; #define PG8_STAGE(bufoff, gbase, voff) do { _Pragma("unroll") for (int _i = 0; _i < 2; ++_i) \
;         __builtin_amdgcn_global_load_lds((const unsigned*)((const char*)(gbase) + (voff)[_i]), (PG8_LAS unsigned*)(lds + (bufoff) + ldsw + _i * 8192), 16, 0, 0); } while (0)
; #define PG8_LDA(dst, b, h) do { _Pragma("unroll") for (int m = 0; m < 4; ++m) _Pragma("unroll") for (int k = 0; k < 2; ++k) dst[m][k] = *(const PG8_LAS bf16x8*)(lds + PG8_SA(b, h) + aoff + m * 2048 + k * 1024); } while (0)
; #define PG8_LDB(dst, b, h) do { _Pragma("unroll") for (int n = 0; n < 2; ++n) _Pragma("unroll") for (int k = 0; k < 2; ++k) dst[n][k] = *(const PG8_LAS bf16x8*)(lds + PG8_SB(b, h) + boff + n * 2048 + k * 1024); } while (0)
; #define PG8_MMA(ai, bj, At, Bt) do { __builtin_amdgcn_s_setprio(1); _Pragma("unroll") for (int m = 0; m < 4; ++m) _Pragma("unroll") for (int n = 0; n < 2; ++n) _Pragma("unroll") for (int k = 0; k < 2; ++k) \
;         acc[ai][bj][m][n] = __builtin_amdgcn_mfma_f32_16x16x32_bf16(Bt[n][k], At[m][k], acc[ai][bj][m][n], 0, 0, 0); __builtin_amdgcn_s_setprio(0); } while (0)
; #define PG8_WAIT_V(n) asm volatile("s_waitcnt vmcnt(" #n ")" ::: "memory")
; #define PG8_WAIT_L(n) asm volatile("s_waitcnt lgkmcnt(" #n ")" ::: "memory")
; #define PG8_BAR __builtin_amdgcn_s_barrier()
; #define PG8_SCHED __builtin_amdgcn_sched_barrier(0)
; template <class Epi, class Sched, bool ALIGN_EPI = false, bool SP2 = false>
; __device__ __forceinline__ void gemm_phase(PG8_LAS unsigned char* lds, const Gemm g, const Sched S, const Epi E, const int tid) {
;     ...
;             PG8_LDB(B0, 0, 0); PG8_LDB(B1, 0, 1); PG8_SCHED; PG8_LDA(At, 0, 0); PG8_STAGE(PG8_SA(1, 1), a1 + hstepA, voffA);
;             PG8_WAIT_V(8); PG8_WAIT_L(0); PG8_BAR; PG8_MMA(0, 0, At, B0); PG8_MMA(0, 1, At, B1); PG8_BAR; PG8_SCHED;
;             PG8_LDA(At, 0, 1); PG8_STAGE(PG8_SB(0, 0), b2, voffB); PG8_STAGE(PG8_SB(0, 1), b2 + hstepB, voffB); PG8_STAGE(PG8_SA(0, 0), a2, voffA);
;             PG8_WAIT_V(8); PG8_WAIT_L(0); PG8_BAR; PG8_MMA(1, 0, At, B0); PG8_MMA(1, 1, At, B1); PG8_BAR; PG8_SCHED;
.LBB0_1196:
	ds_read_b128 v[146:149], v169
	ds_read_b128 v[150:153], v169 offset:1024
	ds_read_b128 v[172:175], v169 offset:2048
	ds_read_b128 v[176:179], v169 offset:3072
	ds_read_b128 v[180:183], v170
	ds_read_b128 v[188:191], v170 offset:1024
	ds_read_b128 v[192:195], v170 offset:2048
	ds_read_b128 v[196:199], v170 offset:3072
	s_add_u32 s34, s30, 0xfffc0080
	s_addc_u32 s35, s31, -1
	s_cmp_eq_u32 s64, 12
	s_cselect_b32 s37, s23, s35
	s_cselect_b32 s36, s60, s34
	s_cselect_b32 s35, s15, s63
	s_cselect_b32 s34, s61, s62
	s_add_i32 m0, s29, 0xc000
	ds_read_b128 v[200:203], v171
	ds_read_b128 v[204:207], v171 offset:1024
	ds_read_b128 v[208:211], v171 offset:2048
	ds_read_b128 v[212:215], v171 offset:3072
	ds_read_b128 v[216:219], v171 offset:4096
	ds_read_b128 v[220:223], v171 offset:5120
	ds_read_b128 v[224:227], v171 offset:6144
	ds_read_b128 v[228:231], v171 offset:7168
	global_load_lds_dwordx4 v138, s[30:31]
	s_add_i32 m0, s29, 0xe000
	s_nop 0
	global_load_lds_dwordx4 v140, s[30:31]
	s_waitcnt vmcnt(8)
	s_waitcnt lgkmcnt(0)
	s_barrier
	s_waitcnt lgkmcnt(0)
	v_mfma_f32_16x16x32_bf16 v[124:127], v[146:149], v[200:203], v[124:127]
	v_mfma_f32_16x16x32_bf16 v[120:123], v[172:175], v[200:203], v[120:123]
	v_mfma_f32_16x16x32_bf16 v[108:111], v[146:149], v[208:211], v[108:111]
	v_mfma_f32_16x16x32_bf16 v[104:107], v[172:175], v[208:211], v[104:107]
	v_mfma_f32_16x16x32_bf16 v[92:95], v[146:149], v[216:219], v[92:95]
	v_mfma_f32_16x16x32_bf16 v[88:91], v[172:175], v[216:219], v[88:91]
	v_mfma_f32_16x16x32_bf16 v[76:79], v[146:149], v[224:227], v[76:79]
	v_mfma_f32_16x16x32_bf16 v[72:75], v[172:175], v[224:227], v[72:75]
	v_mfma_f32_16x16x32_bf16 v[124:127], v[150:153], v[204:207], v[124:127]
	v_mfma_f32_16x16x32_bf16 v[120:123], v[176:179], v[204:207], v[120:123]
	v_mfma_f32_16x16x32_bf16 v[108:111], v[150:153], v[212:215], v[108:111]
	v_mfma_f32_16x16x32_bf16 v[104:107], v[176:179], v[212:215], v[104:107]
	v_mfma_f32_16x16x32_bf16 v[92:95], v[150:153], v[220:223], v[92:95]
	v_mfma_f32_16x16x32_bf16 v[88:91], v[176:179], v[220:223], v[88:91]
	v_mfma_f32_16x16x32_bf16 v[76:79], v[150:153], v[228:231], v[76:79]
	v_mfma_f32_16x16x32_bf16 v[72:75], v[176:179], v[228:231], v[72:75]
	v_mfma_f32_16x16x32_bf16 v[116:119], v[180:183], v[200:203], v[116:119]
	v_mfma_f32_16x16x32_bf16 v[112:115], v[192:195], v[200:203], v[112:115]
	v_mfma_f32_16x16x32_bf16 v[100:103], v[180:183], v[208:211], v[100:103]
	v_mfma_f32_16x16x32_bf16 v[96:99], v[192:195], v[208:211], v[96:99]
	v_mfma_f32_16x16x32_bf16 v[84:87], v[180:183], v[216:219], v[84:87]
	v_mfma_f32_16x16x32_bf16 v[80:83], v[192:195], v[216:219], v[80:83]
	v_mfma_f32_16x16x32_bf16 v[68:71], v[180:183], v[224:227], v[68:71]
	v_mfma_f32_16x16x32_bf16 v[64:67], v[192:195], v[224:227], v[64:67]
	v_mfma_f32_16x16x32_bf16 v[116:119], v[188:191], v[204:207], v[116:119]
	v_mfma_f32_16x16x32_bf16 v[112:115], v[196:199], v[204:207], v[112:115]
	v_mfma_f32_16x16x32_bf16 v[100:103], v[188:191], v[212:215], v[100:103]
	v_mfma_f32_16x16x32_bf16 v[96:99], v[196:199], v[212:215], v[96:99]
	v_mfma_f32_16x16x32_bf16 v[84:87], v[188:191], v[220:223], v[84:87]
	v_mfma_f32_16x16x32_bf16 v[80:83], v[196:199], v[220:223], v[80:83]
	v_mfma_f32_16x16x32_bf16 v[68:71], v[188:191], v[228:231], v[68:71]
	v_mfma_f32_16x16x32_bf16 v[64:67], v[196:199], v[228:231], v[64:67]
	s_barrier
	s_add_u32 s98, s34, 0x80
	s_addc_u32 s99, s35, 0
	s_add_u32 s100, s36, 0x80
	s_addc_u32 s101, s37, 0
	s_add_i32 s65, s52, s13
	s_mov_b32 m0, s65
	ds_read_b128 v[200:203], v171 offset:16384
	ds_read_b128 v[204:207], v171 offset:17408
	ds_read_b128 v[208:211], v171 offset:18432
	ds_read_b128 v[212:215], v171 offset:19456
	ds_read_b128 v[216:219], v171 offset:20480
	ds_read_b128 v[220:223], v171 offset:21504
	ds_read_b128 v[224:227], v171 offset:22528
	ds_read_b128 v[228:231], v171 offset:23552
	global_load_lds_dwordx4 v130, s[34:35]
	s_add_i32 m0, s65, 0x2000
	s_add_u32 s66, s34, 0x40000
	s_addc_u32 s67, s35, 0
	s_add_i32 s65, s53, s13
	global_load_lds_dwordx4 v134, s[34:35]
	s_mov_b32 m0, s65
	s_nop 0
	global_load_lds_dwordx4 v130, s[66:67]
	s_add_i32 m0, s65, 0x2000
	s_nop 0
	global_load_lds_dwordx4 v134, s[66:67]
	s_mov_b32 m0, s29
	s_nop 0
	global_load_lds_dwordx4 v128, s[36:37]
	s_mov_b32 m0, s47
	s_nop 0
	global_load_lds_dwordx4 v132, s[36:37]
	s_waitcnt vmcnt(8)
	s_waitcnt lgkmcnt(0)
	s_barrier
	s_waitcnt lgkmcnt(0)
	v_mfma_f32_16x16x32_bf16 v[60:63], v[146:149], v[200:203], v[60:63]
	v_mfma_f32_16x16x32_bf16 v[56:59], v[172:175], v[200:203], v[56:59]
	v_mfma_f32_16x16x32_bf16 v[44:47], v[146:149], v[208:211], v[44:47]
	v_mfma_f32_16x16x32_bf16 v[40:43], v[172:175], v[208:211], v[40:43]
	v_mfma_f32_16x16x32_bf16 v[28:31], v[146:149], v[216:219], v[28:31]
	v_mfma_f32_16x16x32_bf16 v[24:27], v[172:175], v[216:219], v[24:27]
	v_mfma_f32_16x16x32_bf16 v[12:15], v[146:149], v[224:227], v[12:15]
	v_mfma_f32_16x16x32_bf16 v[8:11], v[172:175], v[224:227], v[8:11]
	v_mfma_f32_16x16x32_bf16 v[60:63], v[150:153], v[204:207], v[60:63]
	v_mfma_f32_16x16x32_bf16 v[56:59], v[176:179], v[204:207], v[56:59]
	v_mfma_f32_16x16x32_bf16 v[44:47], v[150:153], v[212:215], v[44:47]
	v_mfma_f32_16x16x32_bf16 v[40:43], v[176:179], v[212:215], v[40:43]
	v_mfma_f32_16x16x32_bf16 v[28:31], v[150:153], v[220:223], v[28:31]
	v_mfma_f32_16x16x32_bf16 v[24:27], v[176:179], v[220:223], v[24:27]
	v_mfma_f32_16x16x32_bf16 v[12:15], v[150:153], v[228:231], v[12:15]
	v_mfma_f32_16x16x32_bf16 v[8:11], v[176:179], v[228:231], v[8:11]
	v_mfma_f32_16x16x32_bf16 v[52:55], v[180:183], v[200:203], v[52:55]
	v_mfma_f32_16x16x32_bf16 v[48:51], v[192:195], v[200:203], v[48:51]
	v_mfma_f32_16x16x32_bf16 v[36:39], v[180:183], v[208:211], v[36:39]
	v_mfma_f32_16x16x32_bf16 v[32:35], v[192:195], v[208:211], v[32:35]
	v_mfma_f32_16x16x32_bf16 v[20:23], v[180:183], v[216:219], v[20:23]
	v_mfma_f32_16x16x32_bf16 v[16:19], v[192:195], v[216:219], v[16:19]
	v_mfma_f32_16x16x32_bf16 v[4:7], v[180:183], v[224:227], v[4:7]
	v_mfma_f32_16x16x32_bf16 v[0:3], v[192:195], v[224:227], v[0:3]
	v_mfma_f32_16x16x32_bf16 v[52:55], v[188:191], v[204:207], v[52:55]
	v_mfma_f32_16x16x32_bf16 v[48:51], v[196:199], v[204:207], v[48:51]
	v_mfma_f32_16x16x32_bf16 v[36:39], v[188:191], v[212:215], v[36:39]
	v_mfma_f32_16x16x32_bf16 v[32:35], v[196:199], v[212:215], v[32:35]
	v_mfma_f32_16x16x32_bf16 v[20:23], v[188:191], v[220:223], v[20:23]
	v_mfma_f32_16x16x32_bf16 v[16:19], v[196:199], v[220:223], v[16:19]
	v_mfma_f32_16x16x32_bf16 v[4:7], v[188:191], v[228:231], v[4:7]
	v_mfma_f32_16x16x32_bf16 v[0:3], v[196:199], v[228:231], v[0:3]
	s_barrier
; #define PG8_STAGE(bufoff, gbase, voff) do { _Pragma("unroll") for (int _i = 0; _i < 2; ++_i) \
;         __builtin_amdgcn_global_load_lds((const unsigned*)((const char*)(gbase) + (voff)[_i]), (PG8_LAS unsigned*)(lds + (bufoff) + ldsw + _i * 8192), 16, 0, 0); } while (0)
; #define PG8_LDA(dst, b, h) do { _Pragma("unroll") for (int m = 0; m < 4; ++m) _Pragma("unroll") for (int k = 0; k < 2; ++k) dst[m][k] = *(const PG8_LAS bf16x8*)(lds + PG8_SA(b, h) + aoff + m * 2048 + k * 1024); } while (0)
; #define PG8_LDB(dst, b, h) do { _Pragma("unroll") for (int n = 0; n < 2; ++n) _Pragma("unroll") for (int k = 0; k < 2; ++k) dst[n][k] = *(const PG8_LAS bf16x8*)(lds + PG8_SB(b, h) + boff + n * 2048 + k * 1024); } while (0)
; #define PG8_MMA(ai, bj, At, Bt) do { __builtin_amdgcn_s_setprio(1); _Pragma("unroll") for (int m = 0; m < 4; ++m) _Pragma("unroll") for (int n = 0; n < 2; ++n) _Pragma("unroll") for (int k = 0; k < 2; ++k) \
;         acc[ai][bj][m][n] = __builtin_amdgcn_mfma_f32_16x16x32_bf16(Bt[n][k], At[m][k], acc[ai][bj][m][n], 0, 0, 0); __builtin_amdgcn_s_setprio(0); } while (0)
; #define PG8_WAIT_V(n) asm volatile("s_waitcnt vmcnt(" #n ")" ::: "memory")
; #define PG8_WAIT_L(n) asm volatile("s_waitcnt lgkmcnt(" #n ")" ::: "memory")
; #define PG8_BAR __builtin_amdgcn_s_barrier()
; #define PG8_SCHED __builtin_amdgcn_sched_barrier(0)
; template <class Epi, class Sched, bool ALIGN_EPI = false, bool SP2 = false>
; __device__ __forceinline__ void gemm_phase(PG8_LAS unsigned char* lds, const Gemm g, const Sched S, const Epi E, const int tid) {
;     ...
;             PG8_LDB(B0, 1, 0); PG8_LDB(B1, 1, 1); PG8_SCHED; PG8_LDA(At, 1, 0); PG8_STAGE(PG8_SA(0, 1), a2 + hstepA, voffA);
;             PG8_WAIT_V(8); PG8_WAIT_L(0); PG8_BAR; PG8_MMA(0, 0, At, B0); PG8_MMA(0, 1, At, B1); PG8_BAR; PG8_SCHED;
;             PG8_LDA(At, 1, 1); PG8_STAGE(PG8_SB(1, 0), b3, voffB); PG8_STAGE(PG8_SB(1, 1), b3 + hstepB, voffB); PG8_STAGE(PG8_SA(1, 0), a3, voffA);
;             PG8_WAIT_V(8); PG8_WAIT_L(0); PG8_BAR; PG8_MMA(1, 0, At, B0); PG8_MMA(1, 1, At, B1); PG8_BAR; PG8_SCHED;
	s_add_i32 s65, 0, 0x18000
	s_add_i32 s66, 0, 0x1c000
	v_add_u32_e32 v176, s65, v166
	v_add_u32_e32 v187, s66, v166
	ds_read_b128 v[146:149], v176
	ds_read_b128 v[150:153], v176 offset:1024
	ds_read_b128 v[172:175], v176 offset:2048
	ds_read_b128 v[176:179], v176 offset:3072
	ds_read_b128 v[180:183], v187
	ds_read_b128 v[188:191], v187 offset:1024
	ds_read_b128 v[192:195], v187 offset:2048
	ds_read_b128 v[196:199], v187 offset:3072
	s_add_u32 s36, s36, 0x40000
	s_addc_u32 s37, s37, 0
	s_mov_b32 m0, s48
	ds_read_b128 v[200:203], v171 offset:32768
	ds_read_b128 v[204:207], v171 offset:33792
	ds_read_b128 v[208:211], v171 offset:34816
	ds_read_b128 v[212:215], v171 offset:35840
	ds_read_b128 v[216:219], v171 offset:36864
	ds_read_b128 v[220:223], v171 offset:37888
	ds_read_b128 v[224:227], v171 offset:38912
	ds_read_b128 v[228:231], v171 offset:39936
	global_load_lds_dwordx4 v128, s[36:37]
	s_mov_b32 m0, s49
	s_nop 0
	global_load_lds_dwordx4 v132, s[36:37]
	s_waitcnt vmcnt(8)
	s_waitcnt lgkmcnt(0)
	s_barrier
	s_waitcnt lgkmcnt(0)
	v_mfma_f32_16x16x32_bf16 v[124:127], v[146:149], v[200:203], v[124:127]
	v_mfma_f32_16x16x32_bf16 v[120:123], v[172:175], v[200:203], v[120:123]
	v_mfma_f32_16x16x32_bf16 v[108:111], v[146:149], v[208:211], v[108:111]
	v_mfma_f32_16x16x32_bf16 v[104:107], v[172:175], v[208:211], v[104:107]
	v_mfma_f32_16x16x32_bf16 v[92:95], v[146:149], v[216:219], v[92:95]
	v_mfma_f32_16x16x32_bf16 v[88:91], v[172:175], v[216:219], v[88:91]
	v_mfma_f32_16x16x32_bf16 v[76:79], v[146:149], v[224:227], v[76:79]
	v_mfma_f32_16x16x32_bf16 v[72:75], v[172:175], v[224:227], v[72:75]
	v_mfma_f32_16x16x32_bf16 v[124:127], v[150:153], v[204:207], v[124:127]
	v_mfma_f32_16x16x32_bf16 v[120:123], v[176:179], v[204:207], v[120:123]
	v_mfma_f32_16x16x32_bf16 v[108:111], v[150:153], v[212:215], v[108:111]
	v_mfma_f32_16x16x32_bf16 v[104:107], v[176:179], v[212:215], v[104:107]
	v_mfma_f32_16x16x32_bf16 v[92:95], v[150:153], v[220:223], v[92:95]
	v_mfma_f32_16x16x32_bf16 v[88:91], v[176:179], v[220:223], v[88:91]
	v_mfma_f32_16x16x32_bf16 v[76:79], v[150:153], v[228:231], v[76:79]
	v_mfma_f32_16x16x32_bf16 v[72:75], v[176:179], v[228:231], v[72:75]
	v_mfma_f32_16x16x32_bf16 v[116:119], v[180:183], v[200:203], v[116:119]
	v_mfma_f32_16x16x32_bf16 v[112:115], v[192:195], v[200:203], v[112:115]
	v_mfma_f32_16x16x32_bf16 v[100:103], v[180:183], v[208:211], v[100:103]
	v_mfma_f32_16x16x32_bf16 v[96:99], v[192:195], v[208:211], v[96:99]
	v_mfma_f32_16x16x32_bf16 v[84:87], v[180:183], v[216:219], v[84:87]
	v_mfma_f32_16x16x32_bf16 v[80:83], v[192:195], v[216:219], v[80:83]
	v_mfma_f32_16x16x32_bf16 v[68:71], v[180:183], v[224:227], v[68:71]
	v_mfma_f32_16x16x32_bf16 v[64:67], v[192:195], v[224:227], v[64:67]
	v_mfma_f32_16x16x32_bf16 v[116:119], v[188:191], v[204:207], v[116:119]
	v_mfma_f32_16x16x32_bf16 v[112:115], v[196:199], v[204:207], v[112:115]
	v_mfma_f32_16x16x32_bf16 v[100:103], v[188:191], v[212:215], v[100:103]
	v_mfma_f32_16x16x32_bf16 v[96:99], v[196:199], v[212:215], v[96:99]
	v_mfma_f32_16x16x32_bf16 v[84:87], v[188:191], v[220:223], v[84:87]
	v_mfma_f32_16x16x32_bf16 v[80:83], v[196:199], v[220:223], v[80:83]
	v_mfma_f32_16x16x32_bf16 v[68:71], v[188:191], v[228:231], v[68:71]
	v_mfma_f32_16x16x32_bf16 v[64:67], v[196:199], v[228:231], v[64:67]
	s_barrier
	s_add_i32 s36, s65, s13
	s_mov_b32 m0, s36
	ds_read_b128 v[200:203], v171 offset:49152
	ds_read_b128 v[204:207], v171 offset:50176
	ds_read_b128 v[208:211], v171 offset:51200
	ds_read_b128 v[212:215], v171 offset:52224
	ds_read_b128 v[216:219], v171 offset:53248
	ds_read_b128 v[220:223], v171 offset:54272
	ds_read_b128 v[224:227], v171 offset:55296
	ds_read_b128 v[228:231], v171 offset:56320
	global_load_lds_dwordx4 v130, s[98:99]
	s_add_i32 m0, s36, 0x2000
	s_add_u32 s34, s34, 0x40080
	s_addc_u32 s35, s35, 0
	s_add_i32 s36, s66, s13
	global_load_lds_dwordx4 v134, s[98:99]
	s_mov_b32 m0, s36
	s_nop 0
	global_load_lds_dwordx4 v130, s[34:35]
	s_add_i32 m0, s36, 0x2000
	s_nop 0
	global_load_lds_dwordx4 v134, s[34:35]
	s_mov_b32 m0, s50
	s_nop 0
	global_load_lds_dwordx4 v128, s[100:101]
	s_mov_b32 m0, s51
	s_nop 0
	global_load_lds_dwordx4 v132, s[100:101]
	s_waitcnt vmcnt(8)
	s_waitcnt lgkmcnt(0)
	s_barrier
	s_waitcnt lgkmcnt(0)
	v_mfma_f32_16x16x32_bf16 v[60:63], v[146:149], v[200:203], v[60:63]
	v_mfma_f32_16x16x32_bf16 v[56:59], v[172:175], v[200:203], v[56:59]
	v_mfma_f32_16x16x32_bf16 v[44:47], v[146:149], v[208:211], v[44:47]
	v_mfma_f32_16x16x32_bf16 v[40:43], v[172:175], v[208:211], v[40:43]
	v_mfma_f32_16x16x32_bf16 v[28:31], v[146:149], v[216:219], v[28:31]
	v_mfma_f32_16x16x32_bf16 v[24:27], v[172:175], v[216:219], v[24:27]
	v_mfma_f32_16x16x32_bf16 v[12:15], v[146:149], v[224:227], v[12:15]
	v_mfma_f32_16x16x32_bf16 v[8:11], v[172:175], v[224:227], v[8:11]
	v_mfma_f32_16x16x32_bf16 v[60:63], v[150:153], v[204:207], v[60:63]
	v_mfma_f32_16x16x32_bf16 v[56:59], v[176:179], v[204:207], v[56:59]
	v_mfma_f32_16x16x32_bf16 v[44:47], v[150:153], v[212:215], v[44:47]
	v_mfma_f32_16x16x32_bf16 v[40:43], v[176:179], v[212:215], v[40:43]
	v_mfma_f32_16x16x32_bf16 v[28:31], v[150:153], v[220:223], v[28:31]
	v_mfma_f32_16x16x32_bf16 v[24:27], v[176:179], v[220:223], v[24:27]
	v_mfma_f32_16x16x32_bf16 v[12:15], v[150:153], v[228:231], v[12:15]
	v_mfma_f32_16x16x32_bf16 v[8:11], v[176:179], v[228:231], v[8:11]
	v_mfma_f32_16x16x32_bf16 v[52:55], v[180:183], v[200:203], v[52:55]
	v_mfma_f32_16x16x32_bf16 v[48:51], v[192:195], v[200:203], v[48:51]
	v_mfma_f32_16x16x32_bf16 v[36:39], v[180:183], v[208:211], v[36:39]
	v_mfma_f32_16x16x32_bf16 v[32:35], v[192:195], v[208:211], v[32:35]
	v_mfma_f32_16x16x32_bf16 v[20:23], v[180:183], v[216:219], v[20:23]
	v_mfma_f32_16x16x32_bf16 v[16:19], v[192:195], v[216:219], v[16:19]
	v_mfma_f32_16x16x32_bf16 v[4:7], v[180:183], v[224:227], v[4:7]
	v_mfma_f32_16x16x32_bf16 v[0:3], v[192:195], v[224:227], v[0:3]
	v_mfma_f32_16x16x32_bf16 v[52:55], v[188:191], v[204:207], v[52:55]
	v_mfma_f32_16x16x32_bf16 v[48:51], v[196:199], v[204:207], v[48:51]
	v_mfma_f32_16x16x32_bf16 v[36:39], v[188:191], v[212:215], v[36:39]
	v_mfma_f32_16x16x32_bf16 v[32:35], v[196:199], v[212:215], v[32:35]
	v_mfma_f32_16x16x32_bf16 v[20:23], v[188:191], v[220:223], v[20:23]
	v_mfma_f32_16x16x32_bf16 v[16:19], v[196:199], v[220:223], v[16:19]
	v_mfma_f32_16x16x32_bf16 v[4:7], v[188:191], v[228:231], v[4:7]
	v_mfma_f32_16x16x32_bf16 v[0:3], v[196:199], v[228:231], v[0:3]
	s_barrier
	s_add_i32 s64, s64, 2
	s_add_u32 s30, s30, 0x100
	s_addc_u32 s31, s31, 0
	s_add_u32 s62, s62, 0x100
	s_addc_u32 s63, s63, 0
	s_cmp_gt_u32 s64, 13
	s_cbranch_scc0 .LBB0_1196
	s_and_b64 vcc, exec, s[10:11]
	s_cbranch_vccz .LBB0_1199
	s_barrier

; #define PG8_STAGE(bufoff, gbase, voff) do { _Pragma("unroll") for (int _i = 0; _i < 2; ++_i) \
;         __builtin_amdgcn_global_load_lds((const unsigned*)((const char*)(gbase) + (voff)[_i]), (PG8_LAS unsigned*)(lds + (bufoff) + ldsw + _i * 8192), 16, 0, 0); } while (0)
; #define PG8_LDA(dst, b, h) do { _Pragma("unroll") for (int m = 0; m < 4; ++m) _Pragma("unroll") for (int k = 0; k < 2; ++k) dst[m][k] = *(const PG8_LAS bf16x8*)(lds + PG8_SA(b, h) + aoff + m * 2048 + k * 1024); } while (0)
; #define PG8_LDB(dst, b, h) do { _Pragma("unroll") for (int n = 0; n < 2; ++n) _Pragma("unroll") for (int k = 0; k < 2; ++k) dst[n][k] = *(const PG8_LAS bf16x8*)(lds + PG8_SB(b, h) + boff + n * 2048 + k * 1024); } while (0)
; #define PG8_MMA(ai, bj, At, Bt) do { __builtin_amdgcn_s_setprio(1); _Pragma("unroll") for (int m = 0; m < 4; ++m) _Pragma("unroll") for (int n = 0; n < 2; ++n) _Pragma("unroll") for (int k = 0; k < 2; ++k) \
;         acc[ai][bj][m][n] = __builtin_amdgcn_mfma_f32_16x16x32_bf16(Bt[n][k], At[m][k], acc[ai][bj][m][n], 0, 0, 0); __builtin_amdgcn_s_setprio(0); } while (0)
; #define PG8_WAIT_V(n) asm volatile("s_waitcnt vmcnt(" #n ")" ::: "memory")
; #define PG8_WAIT_L(n) asm volatile("s_waitcnt lgkmcnt(" #n ")" ::: "memory")
; #define PG8_BAR __builtin_amdgcn_s_barrier()
; #define PG8_SCHED __builtin_amdgcn_sched_barrier(0)
; template <class Epi, class Sched, bool ALIGN_EPI = false, bool SP2 = false>
; __device__ __forceinline__ void gemm_phase(PG8_LAS unsigned char* lds, const Gemm g, const Sched S, const Epi E, const int tid) {
;     ...
;             PG8_LDB(B0, 0, 0); PG8_LDB(B1, 0, 1); PG8_SCHED; PG8_LDA(At, 0, 0); PG8_STAGE(PG8_SA(1, 1), a1 + hstepA, voffA);
;             PG8_WAIT_V(8); PG8_WAIT_L(0); PG8_BAR; PG8_MMA(0, 0, At, B0); PG8_MMA(0, 1, At, B1); PG8_BAR; PG8_SCHED;
;             PG8_LDA(At, 0, 1); PG8_STAGE(PG8_SB(0, 0), b2, voffB); PG8_STAGE(PG8_SB(0, 1), b2 + hstepB, voffB); PG8_STAGE(PG8_SA(0, 0), a2, voffA);
;             PG8_WAIT_V(8); PG8_WAIT_L(0); PG8_BAR; PG8_MMA(1, 0, At, B0); PG8_MMA(1, 1, At, B1); PG8_BAR; PG8_SCHED;
.LBB0_1239:
	ds_read_b128 v[150:153], v147
	ds_read_b128 v[166:169], v147 offset:1024
	ds_read_b128 v[170:173], v147 offset:2048
	ds_read_b128 v[174:177], v147 offset:3072
	ds_read_b128 v[178:181], v148
	ds_read_b128 v[182:185], v148 offset:1024
	ds_read_b128 v[188:191], v148 offset:2048
	ds_read_b128 v[192:195], v148 offset:3072
	s_add_u32 s52, s50, 0xfffc0080
	s_addc_u32 s53, s51, -1
	s_cmp_eq_u32 s79, 12
	s_cselect_b32 s55, s37, s53
	s_cselect_b32 s54, s75, s52
	s_cselect_b32 s53, s35, s78
	s_cselect_b32 s52, s76, s77
	s_add_i32 m0, s49, 0xc000
	ds_read_b128 v[196:199], v149
	ds_read_b128 v[200:203], v149 offset:1024
	ds_read_b128 v[204:207], v149 offset:2048
	ds_read_b128 v[208:211], v149 offset:3072
	ds_read_b128 v[212:215], v149 offset:4096
	ds_read_b128 v[216:219], v149 offset:5120
	ds_read_b128 v[220:223], v149 offset:6144
	ds_read_b128 v[224:227], v149 offset:7168
	global_load_lds_dwordx4 v138, s[50:51]
	s_add_i32 m0, s49, 0xe000
	s_nop 0
	global_load_lds_dwordx4 v140, s[50:51]
	s_waitcnt vmcnt(8)
	s_waitcnt lgkmcnt(0)
	s_barrier
	s_waitcnt lgkmcnt(0)
	v_mfma_f32_16x16x32_bf16 v[124:127], v[150:153], v[196:199], v[124:127]
	v_mfma_f32_16x16x32_bf16 v[120:123], v[170:173], v[196:199], v[120:123]
	v_mfma_f32_16x16x32_bf16 v[112:115], v[150:153], v[204:207], v[112:115]
	v_mfma_f32_16x16x32_bf16 v[104:107], v[170:173], v[204:207], v[104:107]
	v_mfma_f32_16x16x32_bf16 v[96:99], v[150:153], v[212:215], v[96:99]
	v_mfma_f32_16x16x32_bf16 v[88:91], v[170:173], v[212:215], v[88:91]
	v_mfma_f32_16x16x32_bf16 v[80:83], v[150:153], v[220:223], v[80:83]
	v_mfma_f32_16x16x32_bf16 v[72:75], v[170:173], v[220:223], v[72:75]
	v_mfma_f32_16x16x32_bf16 v[124:127], v[166:169], v[200:203], v[124:127]
	v_mfma_f32_16x16x32_bf16 v[120:123], v[174:177], v[200:203], v[120:123]
	v_mfma_f32_16x16x32_bf16 v[112:115], v[166:169], v[208:211], v[112:115]
	v_mfma_f32_16x16x32_bf16 v[104:107], v[174:177], v[208:211], v[104:107]
	v_mfma_f32_16x16x32_bf16 v[96:99], v[166:169], v[216:219], v[96:99]
	v_mfma_f32_16x16x32_bf16 v[88:91], v[174:177], v[216:219], v[88:91]
	v_mfma_f32_16x16x32_bf16 v[80:83], v[166:169], v[224:227], v[80:83]
	v_mfma_f32_16x16x32_bf16 v[72:75], v[174:177], v[224:227], v[72:75]
	v_mfma_f32_16x16x32_bf16 v[116:119], v[178:181], v[196:199], v[116:119]
	v_mfma_f32_16x16x32_bf16 v[108:111], v[188:191], v[196:199], v[108:111]
	v_mfma_f32_16x16x32_bf16 v[100:103], v[178:181], v[204:207], v[100:103]
	v_mfma_f32_16x16x32_bf16 v[92:95], v[188:191], v[204:207], v[92:95]
	v_mfma_f32_16x16x32_bf16 v[84:87], v[178:181], v[212:215], v[84:87]
	v_mfma_f32_16x16x32_bf16 v[76:79], v[188:191], v[212:215], v[76:79]
	v_mfma_f32_16x16x32_bf16 v[68:71], v[178:181], v[220:223], v[68:71]
	v_mfma_f32_16x16x32_bf16 v[64:67], v[188:191], v[220:223], v[64:67]
	v_mfma_f32_16x16x32_bf16 v[116:119], v[182:185], v[200:203], v[116:119]
	v_mfma_f32_16x16x32_bf16 v[108:111], v[192:195], v[200:203], v[108:111]
	v_mfma_f32_16x16x32_bf16 v[100:103], v[182:185], v[208:211], v[100:103]
	v_mfma_f32_16x16x32_bf16 v[92:95], v[192:195], v[208:211], v[92:95]
	v_mfma_f32_16x16x32_bf16 v[84:87], v[182:185], v[216:219], v[84:87]
	v_mfma_f32_16x16x32_bf16 v[76:79], v[192:195], v[216:219], v[76:79]
	v_mfma_f32_16x16x32_bf16 v[68:71], v[182:185], v[224:227], v[68:71]
	v_mfma_f32_16x16x32_bf16 v[64:67], v[192:195], v[224:227], v[64:67]
	s_barrier
	s_add_u32 s98, s52, 0x80
	s_addc_u32 s99, s53, 0
	s_add_u32 s100, s54, 0x80
	s_addc_u32 s101, s55, 0
	s_add_i32 s80, s72, s64
	s_mov_b32 m0, s80
	ds_read_b128 v[196:199], v149 offset:16384
	ds_read_b128 v[200:203], v149 offset:17408
	ds_read_b128 v[204:207], v149 offset:18432
	ds_read_b128 v[208:211], v149 offset:19456
	ds_read_b128 v[212:215], v149 offset:20480
	ds_read_b128 v[216:219], v149 offset:21504
	ds_read_b128 v[220:223], v149 offset:22528
	ds_read_b128 v[224:227], v149 offset:23552
	global_load_lds_dwordx4 v130, s[52:53]
	s_add_i32 m0, s80, 0x2000
	s_add_u32 s80, s52, 0x40000
	s_addc_u32 s81, s53, 0
	s_add_i32 s82, s73, s64
	global_load_lds_dwordx4 v134, s[52:53]
	s_mov_b32 m0, s82
	s_nop 0
	global_load_lds_dwordx4 v130, s[80:81]
	s_add_i32 m0, s82, 0x2000
	s_nop 0
	global_load_lds_dwordx4 v134, s[80:81]
	s_mov_b32 m0, s49
	s_nop 0
	global_load_lds_dwordx4 v128, s[54:55]
	s_mov_b32 m0, s65
	s_nop 0
	global_load_lds_dwordx4 v132, s[54:55]
	s_waitcnt vmcnt(8)
	s_waitcnt lgkmcnt(0)
	s_barrier
	s_waitcnt lgkmcnt(0)
	v_mfma_f32_16x16x32_bf16 v[60:63], v[150:153], v[196:199], v[60:63]
	v_mfma_f32_16x16x32_bf16 v[56:59], v[170:173], v[196:199], v[56:59]
	v_mfma_f32_16x16x32_bf16 v[52:55], v[150:153], v[204:207], v[52:55]
	v_mfma_f32_16x16x32_bf16 v[44:47], v[170:173], v[204:207], v[44:47]
	v_mfma_f32_16x16x32_bf16 v[36:39], v[150:153], v[212:215], v[36:39]
	v_mfma_f32_16x16x32_bf16 v[28:31], v[170:173], v[212:215], v[28:31]
	v_mfma_f32_16x16x32_bf16 v[20:23], v[150:153], v[220:223], v[20:23]
	v_mfma_f32_16x16x32_bf16 v[12:15], v[170:173], v[220:223], v[12:15]
	v_mfma_f32_16x16x32_bf16 v[60:63], v[166:169], v[200:203], v[60:63]
	v_mfma_f32_16x16x32_bf16 v[56:59], v[174:177], v[200:203], v[56:59]
	v_mfma_f32_16x16x32_bf16 v[52:55], v[166:169], v[208:211], v[52:55]
	v_mfma_f32_16x16x32_bf16 v[44:47], v[174:177], v[208:211], v[44:47]
	v_mfma_f32_16x16x32_bf16 v[36:39], v[166:169], v[216:219], v[36:39]
	v_mfma_f32_16x16x32_bf16 v[28:31], v[174:177], v[216:219], v[28:31]
	v_mfma_f32_16x16x32_bf16 v[20:23], v[166:169], v[224:227], v[20:23]
	v_mfma_f32_16x16x32_bf16 v[12:15], v[174:177], v[224:227], v[12:15]
	v_mfma_f32_16x16x32_bf16 v[48:51], v[178:181], v[196:199], v[48:51]
	v_mfma_f32_16x16x32_bf16 v[40:43], v[188:191], v[196:199], v[40:43]
	v_mfma_f32_16x16x32_bf16 v[32:35], v[178:181], v[204:207], v[32:35]
	v_mfma_f32_16x16x32_bf16 v[24:27], v[188:191], v[204:207], v[24:27]
	v_mfma_f32_16x16x32_bf16 v[16:19], v[178:181], v[212:215], v[16:19]
	v_mfma_f32_16x16x32_bf16 v[8:11], v[188:191], v[212:215], v[8:11]
	v_mfma_f32_16x16x32_bf16 v[4:7], v[178:181], v[220:223], v[4:7]
	v_mfma_f32_16x16x32_bf16 v[0:3], v[188:191], v[220:223], v[0:3]
	v_mfma_f32_16x16x32_bf16 v[48:51], v[182:185], v[200:203], v[48:51]
	v_mfma_f32_16x16x32_bf16 v[40:43], v[192:195], v[200:203], v[40:43]
	v_mfma_f32_16x16x32_bf16 v[32:35], v[182:185], v[208:211], v[32:35]
	v_mfma_f32_16x16x32_bf16 v[24:27], v[192:195], v[208:211], v[24:27]
	v_mfma_f32_16x16x32_bf16 v[16:19], v[182:185], v[216:219], v[16:19]
	v_mfma_f32_16x16x32_bf16 v[8:11], v[192:195], v[216:219], v[8:11]
	v_mfma_f32_16x16x32_bf16 v[4:7], v[182:185], v[224:227], v[4:7]
	v_mfma_f32_16x16x32_bf16 v[0:3], v[192:195], v[224:227], v[0:3]
	s_barrier
; #define PG8_STAGE(bufoff, gbase, voff) do { _Pragma("unroll") for (int _i = 0; _i < 2; ++_i) \
;         __builtin_amdgcn_global_load_lds((const unsigned*)((const char*)(gbase) + (voff)[_i]), (PG8_LAS unsigned*)(lds + (bufoff) + ldsw + _i * 8192), 16, 0, 0); } while (0)
; #define PG8_LDA(dst, b, h) do { _Pragma("unroll") for (int m = 0; m < 4; ++m) _Pragma("unroll") for (int k = 0; k < 2; ++k) dst[m][k] = *(const PG8_LAS bf16x8*)(lds + PG8_SA(b, h) + aoff + m * 2048 + k * 1024); } while (0)
; #define PG8_LDB(dst, b, h) do { _Pragma("unroll") for (int n = 0; n < 2; ++n) _Pragma("unroll") for (int k = 0; k < 2; ++k) dst[n][k] = *(const PG8_LAS bf16x8*)(lds + PG8_SB(b, h) + boff + n * 2048 + k * 1024); } while (0)
; #define PG8_MMA(ai, bj, At, Bt) do { __builtin_amdgcn_s_setprio(1); _Pragma("unroll") for (int m = 0; m < 4; ++m) _Pragma("unroll") for (int n = 0; n < 2; ++n) _Pragma("unroll") for (int k = 0; k < 2; ++k) \
;         acc[ai][bj][m][n] = __builtin_amdgcn_mfma_f32_16x16x32_bf16(Bt[n][k], At[m][k], acc[ai][bj][m][n], 0, 0, 0); __builtin_amdgcn_s_setprio(0); } while (0)
; #define PG8_WAIT_V(n) asm volatile("s_waitcnt vmcnt(" #n ")" ::: "memory")
; #define PG8_WAIT_L(n) asm volatile("s_waitcnt lgkmcnt(" #n ")" ::: "memory")
; #define PG8_BAR __builtin_amdgcn_s_barrier()
; #define PG8_SCHED __builtin_amdgcn_sched_barrier(0)
; template <class Epi, class Sched, bool ALIGN_EPI = false, bool SP2 = false>
; __device__ __forceinline__ void gemm_phase(PG8_LAS unsigned char* lds, const Gemm g, const Sched S, const Epi E, const int tid) {
;     ...
;             PG8_LDB(B0, 1, 0); PG8_LDB(B1, 1, 1); PG8_SCHED; PG8_LDA(At, 1, 0); PG8_STAGE(PG8_SA(0, 1), a2 + hstepA, voffA);
;             PG8_WAIT_V(8); PG8_WAIT_L(0); PG8_BAR; PG8_MMA(0, 0, At, B0); PG8_MMA(0, 1, At, B1); PG8_BAR; PG8_SCHED;
;             PG8_LDA(At, 1, 1); PG8_STAGE(PG8_SB(1, 0), b3, voffB); PG8_STAGE(PG8_SB(1, 1), b3 + hstepB, voffB); PG8_STAGE(PG8_SA(1, 0), a3, voffA);
;             PG8_WAIT_V(8); PG8_WAIT_L(0); PG8_BAR; PG8_MMA(1, 0, At, B0); PG8_MMA(1, 1, At, B1); PG8_BAR; PG8_SCHED;
	s_add_i32 s80, 0, 0x18000
	v_add_u32_e32 v165, s80, v145
	s_add_i32 s81, 0, 0x1c000
	ds_read_b128 v[150:153], v165
	ds_read_b128 v[166:169], v165 offset:1024
	ds_read_b128 v[170:173], v165 offset:2048
	ds_read_b128 v[174:177], v165 offset:3072
	v_add_u32_e32 v165, s81, v145
	ds_read_b128 v[178:181], v165
	ds_read_b128 v[182:185], v165 offset:1024
	ds_read_b128 v[188:191], v165 offset:2048
	ds_read_b128 v[192:195], v165 offset:3072
	s_add_u32 s54, s54, 0x40000
	s_addc_u32 s55, s55, 0
	s_mov_b32 m0, s66
	ds_read_b128 v[196:199], v149 offset:32768
	ds_read_b128 v[200:203], v149 offset:33792
	ds_read_b128 v[204:207], v149 offset:34816
	ds_read_b128 v[208:211], v149 offset:35840
	ds_read_b128 v[212:215], v149 offset:36864
	ds_read_b128 v[216:219], v149 offset:37888
	ds_read_b128 v[220:223], v149 offset:38912
	ds_read_b128 v[224:227], v149 offset:39936
	global_load_lds_dwordx4 v128, s[54:55]
	s_mov_b32 m0, s67
	s_nop 0
	global_load_lds_dwordx4 v132, s[54:55]
	s_waitcnt vmcnt(8)
	s_waitcnt lgkmcnt(0)
	s_barrier
	s_waitcnt lgkmcnt(0)
	v_mfma_f32_16x16x32_bf16 v[124:127], v[150:153], v[196:199], v[124:127]
	v_mfma_f32_16x16x32_bf16 v[120:123], v[170:173], v[196:199], v[120:123]
	v_mfma_f32_16x16x32_bf16 v[112:115], v[150:153], v[204:207], v[112:115]
	v_mfma_f32_16x16x32_bf16 v[104:107], v[170:173], v[204:207], v[104:107]
	v_mfma_f32_16x16x32_bf16 v[96:99], v[150:153], v[212:215], v[96:99]
	v_mfma_f32_16x16x32_bf16 v[88:91], v[170:173], v[212:215], v[88:91]
	v_mfma_f32_16x16x32_bf16 v[80:83], v[150:153], v[220:223], v[80:83]
	v_mfma_f32_16x16x32_bf16 v[72:75], v[170:173], v[220:223], v[72:75]
	v_mfma_f32_16x16x32_bf16 v[124:127], v[166:169], v[200:203], v[124:127]
	v_mfma_f32_16x16x32_bf16 v[120:123], v[174:177], v[200:203], v[120:123]
	v_mfma_f32_16x16x32_bf16 v[112:115], v[166:169], v[208:211], v[112:115]
	v_mfma_f32_16x16x32_bf16 v[104:107], v[174:177], v[208:211], v[104:107]
	v_mfma_f32_16x16x32_bf16 v[96:99], v[166:169], v[216:219], v[96:99]
	v_mfma_f32_16x16x32_bf16 v[88:91], v[174:177], v[216:219], v[88:91]
	v_mfma_f32_16x16x32_bf16 v[80:83], v[166:169], v[224:227], v[80:83]
	v_mfma_f32_16x16x32_bf16 v[72:75], v[174:177], v[224:227], v[72:75]
	v_mfma_f32_16x16x32_bf16 v[116:119], v[178:181], v[196:199], v[116:119]
	v_mfma_f32_16x16x32_bf16 v[108:111], v[188:191], v[196:199], v[108:111]
	v_mfma_f32_16x16x32_bf16 v[100:103], v[178:181], v[204:207], v[100:103]
	v_mfma_f32_16x16x32_bf16 v[92:95], v[188:191], v[204:207], v[92:95]
	v_mfma_f32_16x16x32_bf16 v[84:87], v[178:181], v[212:215], v[84:87]
	v_mfma_f32_16x16x32_bf16 v[76:79], v[188:191], v[212:215], v[76:79]
	v_mfma_f32_16x16x32_bf16 v[68:71], v[178:181], v[220:223], v[68:71]
	v_mfma_f32_16x16x32_bf16 v[64:67], v[188:191], v[220:223], v[64:67]
	v_mfma_f32_16x16x32_bf16 v[116:119], v[182:185], v[200:203], v[116:119]
	v_mfma_f32_16x16x32_bf16 v[108:111], v[192:195], v[200:203], v[108:111]
	v_mfma_f32_16x16x32_bf16 v[100:103], v[182:185], v[208:211], v[100:103]
	v_mfma_f32_16x16x32_bf16 v[92:95], v[192:195], v[208:211], v[92:95]
	v_mfma_f32_16x16x32_bf16 v[84:87], v[182:185], v[216:219], v[84:87]
	v_mfma_f32_16x16x32_bf16 v[76:79], v[192:195], v[216:219], v[76:79]
	v_mfma_f32_16x16x32_bf16 v[68:71], v[182:185], v[224:227], v[68:71]
	v_mfma_f32_16x16x32_bf16 v[64:67], v[192:195], v[224:227], v[64:67]
	s_barrier
	s_add_i32 s54, s80, s64
	s_mov_b32 m0, s54
	ds_read_b128 v[196:199], v149 offset:49152
	ds_read_b128 v[200:203], v149 offset:50176
	ds_read_b128 v[204:207], v149 offset:51200
	ds_read_b128 v[208:211], v149 offset:52224
	ds_read_b128 v[212:215], v149 offset:53248
	ds_read_b128 v[216:219], v149 offset:54272
	ds_read_b128 v[220:223], v149 offset:55296
	ds_read_b128 v[224:227], v149 offset:56320
	global_load_lds_dwordx4 v130, s[98:99]
	s_add_i32 m0, s54, 0x2000
	s_add_u32 s52, s52, 0x40080
	s_addc_u32 s53, s53, 0
	s_add_i32 s54, s81, s64
	global_load_lds_dwordx4 v134, s[98:99]
	s_mov_b32 m0, s54
	s_nop 0
	global_load_lds_dwordx4 v130, s[52:53]
	s_add_i32 m0, s54, 0x2000
	s_nop 0
	global_load_lds_dwordx4 v134, s[52:53]
	s_mov_b32 m0, s70
	s_nop 0
	global_load_lds_dwordx4 v128, s[100:101]
	s_mov_b32 m0, s71
	s_nop 0
	global_load_lds_dwordx4 v132, s[100:101]
	s_waitcnt vmcnt(8)
	s_waitcnt lgkmcnt(0)
	s_barrier
	s_waitcnt lgkmcnt(0)
	v_mfma_f32_16x16x32_bf16 v[60:63], v[150:153], v[196:199], v[60:63]
	v_mfma_f32_16x16x32_bf16 v[56:59], v[170:173], v[196:199], v[56:59]
	v_mfma_f32_16x16x32_bf16 v[52:55], v[150:153], v[204:207], v[52:55]
	v_mfma_f32_16x16x32_bf16 v[44:47], v[170:173], v[204:207], v[44:47]
	v_mfma_f32_16x16x32_bf16 v[36:39], v[150:153], v[212:215], v[36:39]
	v_mfma_f32_16x16x32_bf16 v[28:31], v[170:173], v[212:215], v[28:31]
	v_mfma_f32_16x16x32_bf16 v[20:23], v[150:153], v[220:223], v[20:23]
	v_mfma_f32_16x16x32_bf16 v[12:15], v[170:173], v[220:223], v[12:15]
	v_mfma_f32_16x16x32_bf16 v[60:63], v[166:169], v[200:203], v[60:63]
	v_mfma_f32_16x16x32_bf16 v[56:59], v[174:177], v[200:203], v[56:59]
	v_mfma_f32_16x16x32_bf16 v[52:55], v[166:169], v[208:211], v[52:55]
	v_mfma_f32_16x16x32_bf16 v[44:47], v[174:177], v[208:211], v[44:47]
	v_mfma_f32_16x16x32_bf16 v[36:39], v[166:169], v[216:219], v[36:39]
	v_mfma_f32_16x16x32_bf16 v[28:31], v[174:177], v[216:219], v[28:31]
	v_mfma_f32_16x16x32_bf16 v[20:23], v[166:169], v[224:227], v[20:23]
	v_mfma_f32_16x16x32_bf16 v[12:15], v[174:177], v[224:227], v[12:15]
	v_mfma_f32_16x16x32_bf16 v[48:51], v[178:181], v[196:199], v[48:51]
	v_mfma_f32_16x16x32_bf16 v[40:43], v[188:191], v[196:199], v[40:43]
	v_mfma_f32_16x16x32_bf16 v[32:35], v[178:181], v[204:207], v[32:35]
	v_mfma_f32_16x16x32_bf16 v[24:27], v[188:191], v[204:207], v[24:27]
	v_mfma_f32_16x16x32_bf16 v[16:19], v[178:181], v[212:215], v[16:19]
	v_mfma_f32_16x16x32_bf16 v[8:11], v[188:191], v[212:215], v[8:11]
	v_mfma_f32_16x16x32_bf16 v[4:7], v[178:181], v[220:223], v[4:7]
	v_mfma_f32_16x16x32_bf16 v[0:3], v[188:191], v[220:223], v[0:3]
	v_mfma_f32_16x16x32_bf16 v[48:51], v[182:185], v[200:203], v[48:51]
	v_mfma_f32_16x16x32_bf16 v[40:43], v[192:195], v[200:203], v[40:43]
	v_mfma_f32_16x16x32_bf16 v[32:35], v[182:185], v[208:211], v[32:35]
	v_mfma_f32_16x16x32_bf16 v[24:27], v[192:195], v[208:211], v[24:27]
	v_mfma_f32_16x16x32_bf16 v[16:19], v[182:185], v[216:219], v[16:19]
	v_mfma_f32_16x16x32_bf16 v[8:11], v[192:195], v[216:219], v[8:11]
	v_mfma_f32_16x16x32_bf16 v[4:7], v[182:185], v[224:227], v[4:7]
	v_mfma_f32_16x16x32_bf16 v[0:3], v[192:195], v[224:227], v[0:3]
	s_barrier
	s_add_i32 s79, s79, 2
	s_add_u32 s50, s50, 0x100
	s_addc_u32 s51, s51, 0
	s_add_u32 s77, s77, 0x100
	s_addc_u32 s78, s78, 0
	s_cmp_gt_u32 s79, 13
	s_cbranch_scc0 .LBB0_1239
	s_and_b64 vcc, exec, s[10:11]
	s_cbranch_vccz .LBB0_1242
	s_barrier

; #define PG8_STAGE(bufoff, gbase, voff) do { _Pragma("unroll") for (int _i = 0; _i < 2; ++_i) \
;         __builtin_amdgcn_global_load_lds((const unsigned*)((const char*)(gbase) + (voff)[_i]), (PG8_LAS unsigned*)(lds + (bufoff) + ldsw + _i * 8192), 16, 0, 0); } while (0)
; #define PG8_LDA(dst, b, h) do { _Pragma("unroll") for (int m = 0; m < 4; ++m) _Pragma("unroll") for (int k = 0; k < 2; ++k) dst[m][k] = *(const PG8_LAS bf16x8*)(lds + PG8_SA(b, h) + aoff + m * 2048 + k * 1024); } while (0)
; #define PG8_LDB(dst, b, h) do { _Pragma("unroll") for (int n = 0; n < 2; ++n) _Pragma("unroll") for (int k = 0; k < 2; ++k) dst[n][k] = *(const PG8_LAS bf16x8*)(lds + PG8_SB(b, h) + boff + n * 2048 + k * 1024); } while (0)
; #define PG8_MMA(ai, bj, At, Bt) do { __builtin_amdgcn_s_setprio(1); _Pragma("unroll") for (int m = 0; m < 4; ++m) _Pragma("unroll") for (int n = 0; n < 2; ++n) _Pragma("unroll") for (int k = 0; k < 2; ++k) \
;         acc[ai][bj][m][n] = __builtin_amdgcn_mfma_f32_16x16x32_bf16(Bt[n][k], At[m][k], acc[ai][bj][m][n], 0, 0, 0); __builtin_amdgcn_s_setprio(0); } while (0)
; #define PG8_WAIT_V(n) asm volatile("s_waitcnt vmcnt(" #n ")" ::: "memory")
; #define PG8_WAIT_L(n) asm volatile("s_waitcnt lgkmcnt(" #n ")" ::: "memory")
; #define PG8_BAR __builtin_amdgcn_s_barrier()
; #define PG8_SCHED __builtin_amdgcn_sched_barrier(0)
; template <class Epi, class Sched, bool ALIGN_EPI = false, bool SP2 = false>
; __device__ __forceinline__ void gemm_phase(PG8_LAS unsigned char* lds, const Gemm g, const Sched S, const Epi E, const int tid) {
;     ...
;             PG8_LDB(B0, 0, 0); PG8_LDB(B1, 0, 1); PG8_SCHED; PG8_LDA(At, 0, 0); PG8_STAGE(PG8_SA(1, 1), a1 + hstepA, voffA);
;             PG8_WAIT_V(8); PG8_WAIT_L(0); PG8_BAR; PG8_MMA(0, 0, At, B0); PG8_MMA(0, 1, At, B1); PG8_BAR; PG8_SCHED;
;             PG8_LDA(At, 0, 1); PG8_STAGE(PG8_SB(0, 0), b2, voffB); PG8_STAGE(PG8_SB(0, 1), b2 + hstepB, voffB); PG8_STAGE(PG8_SA(0, 0), a2, voffA);
;             PG8_WAIT_V(8); PG8_WAIT_L(0); PG8_BAR; PG8_MMA(1, 0, At, B0); PG8_MMA(1, 1, At, B1); PG8_BAR; PG8_SCHED;
.LBB0_1255:
	ds_read_b128 v[148:151], v145
	ds_read_b128 v[152:155], v145 offset:1024
	ds_read_b128 v[156:159], v145 offset:2048
	ds_read_b128 v[160:163], v145 offset:3072
	ds_read_b128 v[164:167], v146
	ds_read_b128 v[168:171], v146 offset:1024
	ds_read_b128 v[172:175], v146 offset:2048
	ds_read_b128 v[176:179], v146 offset:3072
	s_add_u32 s52, s50, 0xfffc0080
	s_addc_u32 s53, s51, -1
	s_cmp_eq_u32 s76, 12
	s_cselect_b32 s55, s37, s53
	s_cselect_b32 s54, s72, s52
	s_cselect_b32 s53, s35, s75
	s_cselect_b32 s52, s73, s74
	s_add_i32 m0, s49, 0xc000
	ds_read_b128 v[180:183], v147
	ds_read_b128 v[188:191], v147 offset:1024
	ds_read_b128 v[192:195], v147 offset:2048
	ds_read_b128 v[196:199], v147 offset:3072
	ds_read_b128 v[200:203], v147 offset:4096
	ds_read_b128 v[204:207], v147 offset:5120
	ds_read_b128 v[208:211], v147 offset:6144
	ds_read_b128 v[212:215], v147 offset:7168
	global_load_lds_dwordx4 v136, s[50:51]
	s_add_i32 m0, s49, 0xe000
	s_nop 0
	global_load_lds_dwordx4 v138, s[50:51]
	s_waitcnt vmcnt(8)
	s_waitcnt lgkmcnt(0)
	s_barrier
	s_waitcnt lgkmcnt(0)
	v_mfma_f32_16x16x32_bf16 v[124:127], v[148:151], v[180:183], v[124:127]
	v_mfma_f32_16x16x32_bf16 v[120:123], v[156:159], v[180:183], v[120:123]
	v_mfma_f32_16x16x32_bf16 v[112:115], v[148:151], v[192:195], v[112:115]
	v_mfma_f32_16x16x32_bf16 v[104:107], v[156:159], v[192:195], v[104:107]
	v_mfma_f32_16x16x32_bf16 v[96:99], v[148:151], v[200:203], v[96:99]
	v_mfma_f32_16x16x32_bf16 v[88:91], v[156:159], v[200:203], v[88:91]
	v_mfma_f32_16x16x32_bf16 v[80:83], v[148:151], v[208:211], v[80:83]
	v_mfma_f32_16x16x32_bf16 v[72:75], v[156:159], v[208:211], v[72:75]
	v_mfma_f32_16x16x32_bf16 v[124:127], v[152:155], v[188:191], v[124:127]
	v_mfma_f32_16x16x32_bf16 v[120:123], v[160:163], v[188:191], v[120:123]
	v_mfma_f32_16x16x32_bf16 v[112:115], v[152:155], v[196:199], v[112:115]
	v_mfma_f32_16x16x32_bf16 v[104:107], v[160:163], v[196:199], v[104:107]
	v_mfma_f32_16x16x32_bf16 v[96:99], v[152:155], v[204:207], v[96:99]
	v_mfma_f32_16x16x32_bf16 v[88:91], v[160:163], v[204:207], v[88:91]
	v_mfma_f32_16x16x32_bf16 v[80:83], v[152:155], v[212:215], v[80:83]
	v_mfma_f32_16x16x32_bf16 v[72:75], v[160:163], v[212:215], v[72:75]
	v_mfma_f32_16x16x32_bf16 v[116:119], v[164:167], v[180:183], v[116:119]
	v_mfma_f32_16x16x32_bf16 v[108:111], v[172:175], v[180:183], v[108:111]
	v_mfma_f32_16x16x32_bf16 v[100:103], v[164:167], v[192:195], v[100:103]
	v_mfma_f32_16x16x32_bf16 v[92:95], v[172:175], v[192:195], v[92:95]
	v_mfma_f32_16x16x32_bf16 v[84:87], v[164:167], v[200:203], v[84:87]
	v_mfma_f32_16x16x32_bf16 v[76:79], v[172:175], v[200:203], v[76:79]
	v_mfma_f32_16x16x32_bf16 v[68:71], v[164:167], v[208:211], v[68:71]
	v_mfma_f32_16x16x32_bf16 v[64:67], v[172:175], v[208:211], v[64:67]
	v_mfma_f32_16x16x32_bf16 v[116:119], v[168:171], v[188:191], v[116:119]
	v_mfma_f32_16x16x32_bf16 v[108:111], v[176:179], v[188:191], v[108:111]
	v_mfma_f32_16x16x32_bf16 v[100:103], v[168:171], v[196:199], v[100:103]
	v_mfma_f32_16x16x32_bf16 v[92:95], v[176:179], v[196:199], v[92:95]
	v_mfma_f32_16x16x32_bf16 v[84:87], v[168:171], v[204:207], v[84:87]
	v_mfma_f32_16x16x32_bf16 v[76:79], v[176:179], v[204:207], v[76:79]
	v_mfma_f32_16x16x32_bf16 v[68:71], v[168:171], v[212:215], v[68:71]
	v_mfma_f32_16x16x32_bf16 v[64:67], v[176:179], v[212:215], v[64:67]
	s_barrier
	s_add_u32 s98, s52, 0x80
	s_addc_u32 s99, s53, 0
	s_add_u32 s100, s54, 0x80
	s_addc_u32 s101, s55, 0
	s_add_i32 s77, s69, s61
	s_mov_b32 m0, s77
	ds_read_b128 v[180:183], v147 offset:16384
	ds_read_b128 v[188:191], v147 offset:17408
	ds_read_b128 v[192:195], v147 offset:18432
	ds_read_b128 v[196:199], v147 offset:19456
	ds_read_b128 v[200:203], v147 offset:20480
	ds_read_b128 v[204:207], v147 offset:21504
	ds_read_b128 v[208:211], v147 offset:22528
	ds_read_b128 v[212:215], v147 offset:23552
	global_load_lds_dwordx4 v130, s[52:53]
	s_add_i32 m0, s77, 0x2000
	s_add_u32 s78, s52, 0x40000
	s_addc_u32 s79, s53, 0
	s_add_i32 s77, s70, s61
	global_load_lds_dwordx4 v134, s[52:53]
	s_mov_b32 m0, s77
	s_nop 0
	global_load_lds_dwordx4 v130, s[78:79]
	s_add_i32 m0, s77, 0x2000
	s_nop 0
	global_load_lds_dwordx4 v134, s[78:79]
	s_mov_b32 m0, s49
	s_nop 0
	global_load_lds_dwordx4 v128, s[54:55]
	s_mov_b32 m0, s62
	s_nop 0
	global_load_lds_dwordx4 v132, s[54:55]
	s_waitcnt vmcnt(8)
	s_waitcnt lgkmcnt(0)
	s_barrier
	s_waitcnt lgkmcnt(0)
	v_mfma_f32_16x16x32_bf16 v[60:63], v[148:151], v[180:183], v[60:63]
	v_mfma_f32_16x16x32_bf16 v[56:59], v[156:159], v[180:183], v[56:59]
	v_mfma_f32_16x16x32_bf16 v[52:55], v[148:151], v[192:195], v[52:55]
	v_mfma_f32_16x16x32_bf16 v[44:47], v[156:159], v[192:195], v[44:47]
	v_mfma_f32_16x16x32_bf16 v[36:39], v[148:151], v[200:203], v[36:39]
	v_mfma_f32_16x16x32_bf16 v[28:31], v[156:159], v[200:203], v[28:31]
	v_mfma_f32_16x16x32_bf16 v[20:23], v[148:151], v[208:211], v[20:23]
	v_mfma_f32_16x16x32_bf16 v[12:15], v[156:159], v[208:211], v[12:15]
	v_mfma_f32_16x16x32_bf16 v[60:63], v[152:155], v[188:191], v[60:63]
	v_mfma_f32_16x16x32_bf16 v[56:59], v[160:163], v[188:191], v[56:59]
	v_mfma_f32_16x16x32_bf16 v[52:55], v[152:155], v[196:199], v[52:55]
	v_mfma_f32_16x16x32_bf16 v[44:47], v[160:163], v[196:199], v[44:47]
	v_mfma_f32_16x16x32_bf16 v[36:39], v[152:155], v[204:207], v[36:39]
	v_mfma_f32_16x16x32_bf16 v[28:31], v[160:163], v[204:207], v[28:31]
	v_mfma_f32_16x16x32_bf16 v[20:23], v[152:155], v[212:215], v[20:23]
	v_mfma_f32_16x16x32_bf16 v[12:15], v[160:163], v[212:215], v[12:15]
	v_mfma_f32_16x16x32_bf16 v[48:51], v[164:167], v[180:183], v[48:51]
	v_mfma_f32_16x16x32_bf16 v[40:43], v[172:175], v[180:183], v[40:43]
	v_mfma_f32_16x16x32_bf16 v[32:35], v[164:167], v[192:195], v[32:35]
	v_mfma_f32_16x16x32_bf16 v[24:27], v[172:175], v[192:195], v[24:27]
	v_mfma_f32_16x16x32_bf16 v[16:19], v[164:167], v[200:203], v[16:19]
	v_mfma_f32_16x16x32_bf16 v[8:11], v[172:175], v[200:203], v[8:11]
	v_mfma_f32_16x16x32_bf16 v[4:7], v[164:167], v[208:211], v[4:7]
	v_mfma_f32_16x16x32_bf16 v[0:3], v[172:175], v[208:211], v[0:3]
	v_mfma_f32_16x16x32_bf16 v[48:51], v[168:171], v[188:191], v[48:51]
	v_mfma_f32_16x16x32_bf16 v[40:43], v[176:179], v[188:191], v[40:43]
	v_mfma_f32_16x16x32_bf16 v[32:35], v[168:171], v[196:199], v[32:35]
	v_mfma_f32_16x16x32_bf16 v[24:27], v[176:179], v[196:199], v[24:27]
	v_mfma_f32_16x16x32_bf16 v[16:19], v[168:171], v[204:207], v[16:19]
	v_mfma_f32_16x16x32_bf16 v[8:11], v[176:179], v[204:207], v[8:11]
	v_mfma_f32_16x16x32_bf16 v[4:7], v[168:171], v[212:215], v[4:7]
	v_mfma_f32_16x16x32_bf16 v[0:3], v[176:179], v[212:215], v[0:3]
	s_barrier
; #define PG8_STAGE(bufoff, gbase, voff) do { _Pragma("unroll") for (int _i = 0; _i < 2; ++_i) \
;         __builtin_amdgcn_global_load_lds((const unsigned*)((const char*)(gbase) + (voff)[_i]), (PG8_LAS unsigned*)(lds + (bufoff) + ldsw + _i * 8192), 16, 0, 0); } while (0)
; #define PG8_LDA(dst, b, h) do { _Pragma("unroll") for (int m = 0; m < 4; ++m) _Pragma("unroll") for (int k = 0; k < 2; ++k) dst[m][k] = *(const PG8_LAS bf16x8*)(lds + PG8_SA(b, h) + aoff + m * 2048 + k * 1024); } while (0)
; #define PG8_LDB(dst, b, h) do { _Pragma("unroll") for (int n = 0; n < 2; ++n) _Pragma("unroll") for (int k = 0; k < 2; ++k) dst[n][k] = *(const PG8_LAS bf16x8*)(lds + PG8_SB(b, h) + boff + n * 2048 + k * 1024); } while (0)
; #define PG8_MMA(ai, bj, At, Bt) do { __builtin_amdgcn_s_setprio(1); _Pragma("unroll") for (int m = 0; m < 4; ++m) _Pragma("unroll") for (int n = 0; n < 2; ++n) _Pragma("unroll") for (int k = 0; k < 2; ++k) \
;         acc[ai][bj][m][n] = __builtin_amdgcn_mfma_f32_16x16x32_bf16(Bt[n][k], At[m][k], acc[ai][bj][m][n], 0, 0, 0); __builtin_amdgcn_s_setprio(0); } while (0)
; #define PG8_WAIT_V(n) asm volatile("s_waitcnt vmcnt(" #n ")" ::: "memory")
; #define PG8_WAIT_L(n) asm volatile("s_waitcnt lgkmcnt(" #n ")" ::: "memory")
; #define PG8_BAR __builtin_amdgcn_s_barrier()
; #define PG8_SCHED __builtin_amdgcn_sched_barrier(0)
; template <class Epi, class Sched, bool ALIGN_EPI = false, bool SP2 = false>
; __device__ __forceinline__ void gemm_phase(PG8_LAS unsigned char* lds, const Gemm g, const Sched S, const Epi E, const int tid) {
;     ...
;             PG8_LDB(B0, 1, 0); PG8_LDB(B1, 1, 1); PG8_SCHED; PG8_LDA(At, 1, 0); PG8_STAGE(PG8_SA(0, 1), a2 + hstepA, voffA);
;             PG8_WAIT_V(8); PG8_WAIT_L(0); PG8_BAR; PG8_MMA(0, 0, At, B0); PG8_MMA(0, 1, At, B1); PG8_BAR; PG8_SCHED;
;             PG8_LDA(At, 1, 1); PG8_STAGE(PG8_SB(1, 0), b3, voffB); PG8_STAGE(PG8_SB(1, 1), b3 + hstepB, voffB); PG8_STAGE(PG8_SA(1, 0), a3, voffA);
;             PG8_WAIT_V(8); PG8_WAIT_L(0); PG8_BAR; PG8_MMA(1, 0, At, B0); PG8_MMA(1, 1, At, B1); PG8_BAR; PG8_SCHED;
	s_add_i32 s77, 0, 0x18000
	s_add_i32 s78, 0, 0x1c000
	v_add_u32_e32 v160, s77, v143
	v_add_u32_e32 v176, s78, v143
	ds_read_b128 v[148:151], v160
	ds_read_b128 v[152:155], v160 offset:1024
	ds_read_b128 v[156:159], v160 offset:2048
	ds_read_b128 v[160:163], v160 offset:3072
	ds_read_b128 v[164:167], v176
	ds_read_b128 v[168:171], v176 offset:1024
	ds_read_b128 v[172:175], v176 offset:2048
	ds_read_b128 v[176:179], v176 offset:3072
	s_add_u32 s54, s54, 0x40000
	s_addc_u32 s55, s55, 0
	s_mov_b32 m0, s63
	ds_read_b128 v[180:183], v147 offset:32768
	ds_read_b128 v[188:191], v147 offset:33792
	ds_read_b128 v[192:195], v147 offset:34816
	ds_read_b128 v[196:199], v147 offset:35840
	ds_read_b128 v[200:203], v147 offset:36864
	ds_read_b128 v[204:207], v147 offset:37888
	ds_read_b128 v[208:211], v147 offset:38912
	ds_read_b128 v[212:215], v147 offset:39936
	global_load_lds_dwordx4 v128, s[54:55]
	s_mov_b32 m0, s64
	s_nop 0
	global_load_lds_dwordx4 v132, s[54:55]
	s_waitcnt vmcnt(8)
	s_waitcnt lgkmcnt(0)
	s_barrier
	s_waitcnt lgkmcnt(0)
	v_mfma_f32_16x16x32_bf16 v[124:127], v[148:151], v[180:183], v[124:127]
	v_mfma_f32_16x16x32_bf16 v[120:123], v[156:159], v[180:183], v[120:123]
	v_mfma_f32_16x16x32_bf16 v[112:115], v[148:151], v[192:195], v[112:115]
	v_mfma_f32_16x16x32_bf16 v[104:107], v[156:159], v[192:195], v[104:107]
	v_mfma_f32_16x16x32_bf16 v[96:99], v[148:151], v[200:203], v[96:99]
	v_mfma_f32_16x16x32_bf16 v[88:91], v[156:159], v[200:203], v[88:91]
	v_mfma_f32_16x16x32_bf16 v[80:83], v[148:151], v[208:211], v[80:83]
	v_mfma_f32_16x16x32_bf16 v[72:75], v[156:159], v[208:211], v[72:75]
	v_mfma_f32_16x16x32_bf16 v[124:127], v[152:155], v[188:191], v[124:127]
	v_mfma_f32_16x16x32_bf16 v[120:123], v[160:163], v[188:191], v[120:123]
	v_mfma_f32_16x16x32_bf16 v[112:115], v[152:155], v[196:199], v[112:115]
	v_mfma_f32_16x16x32_bf16 v[104:107], v[160:163], v[196:199], v[104:107]
	v_mfma_f32_16x16x32_bf16 v[96:99], v[152:155], v[204:207], v[96:99]
	v_mfma_f32_16x16x32_bf16 v[88:91], v[160:163], v[204:207], v[88:91]
	v_mfma_f32_16x16x32_bf16 v[80:83], v[152:155], v[212:215], v[80:83]
	v_mfma_f32_16x16x32_bf16 v[72:75], v[160:163], v[212:215], v[72:75]
	v_mfma_f32_16x16x32_bf16 v[116:119], v[164:167], v[180:183], v[116:119]
	v_mfma_f32_16x16x32_bf16 v[108:111], v[172:175], v[180:183], v[108:111]
	v_mfma_f32_16x16x32_bf16 v[100:103], v[164:167], v[192:195], v[100:103]
	v_mfma_f32_16x16x32_bf16 v[92:95], v[172:175], v[192:195], v[92:95]
	v_mfma_f32_16x16x32_bf16 v[84:87], v[164:167], v[200:203], v[84:87]
	v_mfma_f32_16x16x32_bf16 v[76:79], v[172:175], v[200:203], v[76:79]
	v_mfma_f32_16x16x32_bf16 v[68:71], v[164:167], v[208:211], v[68:71]
	v_mfma_f32_16x16x32_bf16 v[64:67], v[172:175], v[208:211], v[64:67]
	v_mfma_f32_16x16x32_bf16 v[116:119], v[168:171], v[188:191], v[116:119]
	v_mfma_f32_16x16x32_bf16 v[108:111], v[176:179], v[188:191], v[108:111]
	v_mfma_f32_16x16x32_bf16 v[100:103], v[168:171], v[196:199], v[100:103]
	v_mfma_f32_16x16x32_bf16 v[92:95], v[176:179], v[196:199], v[92:95]
	v_mfma_f32_16x16x32_bf16 v[84:87], v[168:171], v[204:207], v[84:87]
	v_mfma_f32_16x16x32_bf16 v[76:79], v[176:179], v[204:207], v[76:79]
	v_mfma_f32_16x16x32_bf16 v[68:71], v[168:171], v[212:215], v[68:71]
	v_mfma_f32_16x16x32_bf16 v[64:67], v[176:179], v[212:215], v[64:67]
	s_barrier
	s_add_i32 s54, s77, s61
	s_mov_b32 m0, s54
	ds_read_b128 v[180:183], v147 offset:49152
	ds_read_b128 v[188:191], v147 offset:50176
	ds_read_b128 v[192:195], v147 offset:51200
	ds_read_b128 v[196:199], v147 offset:52224
	ds_read_b128 v[200:203], v147 offset:53248
	ds_read_b128 v[204:207], v147 offset:54272
	ds_read_b128 v[208:211], v147 offset:55296
	ds_read_b128 v[212:215], v147 offset:56320
	global_load_lds_dwordx4 v130, s[98:99]
	s_add_i32 m0, s54, 0x2000
	s_add_u32 s52, s52, 0x40080
	s_addc_u32 s53, s53, 0
	s_add_i32 s54, s78, s61
	global_load_lds_dwordx4 v134, s[98:99]
	s_mov_b32 m0, s54
	s_nop 0
	global_load_lds_dwordx4 v130, s[52:53]
	s_add_i32 m0, s54, 0x2000
	s_nop 0
	global_load_lds_dwordx4 v134, s[52:53]
	s_mov_b32 m0, s66
	s_nop 0
	global_load_lds_dwordx4 v128, s[100:101]
	s_mov_b32 m0, s67
	s_nop 0
	global_load_lds_dwordx4 v132, s[100:101]
	s_waitcnt vmcnt(8)
	s_waitcnt lgkmcnt(0)
	s_barrier
	s_waitcnt lgkmcnt(0)
	v_mfma_f32_16x16x32_bf16 v[60:63], v[148:151], v[180:183], v[60:63]
	v_mfma_f32_16x16x32_bf16 v[56:59], v[156:159], v[180:183], v[56:59]
	v_mfma_f32_16x16x32_bf16 v[52:55], v[148:151], v[192:195], v[52:55]
	v_mfma_f32_16x16x32_bf16 v[44:47], v[156:159], v[192:195], v[44:47]
	v_mfma_f32_16x16x32_bf16 v[36:39], v[148:151], v[200:203], v[36:39]
	v_mfma_f32_16x16x32_bf16 v[28:31], v[156:159], v[200:203], v[28:31]
	v_mfma_f32_16x16x32_bf16 v[20:23], v[148:151], v[208:211], v[20:23]
	v_mfma_f32_16x16x32_bf16 v[12:15], v[156:159], v[208:211], v[12:15]
	v_mfma_f32_16x16x32_bf16 v[60:63], v[152:155], v[188:191], v[60:63]
	v_mfma_f32_16x16x32_bf16 v[56:59], v[160:163], v[188:191], v[56:59]
	v_mfma_f32_16x16x32_bf16 v[52:55], v[152:155], v[196:199], v[52:55]
	v_mfma_f32_16x16x32_bf16 v[44:47], v[160:163], v[196:199], v[44:47]
	v_mfma_f32_16x16x32_bf16 v[36:39], v[152:155], v[204:207], v[36:39]
	v_mfma_f32_16x16x32_bf16 v[28:31], v[160:163], v[204:207], v[28:31]
	v_mfma_f32_16x16x32_bf16 v[20:23], v[152:155], v[212:215], v[20:23]
	v_mfma_f32_16x16x32_bf16 v[12:15], v[160:163], v[212:215], v[12:15]
	v_mfma_f32_16x16x32_bf16 v[48:51], v[164:167], v[180:183], v[48:51]
	v_mfma_f32_16x16x32_bf16 v[40:43], v[172:175], v[180:183], v[40:43]
	v_mfma_f32_16x16x32_bf16 v[32:35], v[164:167], v[192:195], v[32:35]
	v_mfma_f32_16x16x32_bf16 v[24:27], v[172:175], v[192:195], v[24:27]
	v_mfma_f32_16x16x32_bf16 v[16:19], v[164:167], v[200:203], v[16:19]
	v_mfma_f32_16x16x32_bf16 v[8:11], v[172:175], v[200:203], v[8:11]
	v_mfma_f32_16x16x32_bf16 v[4:7], v[164:167], v[208:211], v[4:7]
	v_mfma_f32_16x16x32_bf16 v[0:3], v[172:175], v[208:211], v[0:3]
	v_mfma_f32_16x16x32_bf16 v[48:51], v[168:171], v[188:191], v[48:51]
	v_mfma_f32_16x16x32_bf16 v[40:43], v[176:179], v[188:191], v[40:43]
	v_mfma_f32_16x16x32_bf16 v[32:35], v[168:171], v[196:199], v[32:35]
	v_mfma_f32_16x16x32_bf16 v[24:27], v[176:179], v[196:199], v[24:27]
	v_mfma_f32_16x16x32_bf16 v[16:19], v[168:171], v[204:207], v[16:19]
	v_mfma_f32_16x16x32_bf16 v[8:11], v[176:179], v[204:207], v[8:11]
	v_mfma_f32_16x16x32_bf16 v[4:7], v[168:171], v[212:215], v[4:7]
	v_mfma_f32_16x16x32_bf16 v[0:3], v[176:179], v[212:215], v[0:3]
	s_barrier
	s_add_i32 s76, s76, 2
	s_add_u32 s50, s50, 0x100
	s_addc_u32 s51, s51, 0
	s_add_u32 s74, s74, 0x100
	s_addc_u32 s75, s75, 0
	s_cmp_gt_u32 s76, 13
	s_cbranch_scc0 .LBB0_1255
	s_and_b64 vcc, exec, s[8:9]
	s_cbranch_vccz .LBB0_1258
	s_barrier
